# duplicate s_waitcnt lgkmcnt(0) after s_setprio 1 removed in all GEMM K-loops (the asm one right before already drained)
# speedup vs baseline: 1.0122x; 1.0003x over previous
; #define PG8_STAGE(bufoff, gbase, voff) do { _Pragma("unroll") for (int _i = 0; _i < 2; ++_i) \
;         __builtin_amdgcn_global_load_lds((const unsigned*)((const char*)(gbase) + (voff)[_i]), (LAS unsigned*)(lds + (bufoff) + ldsw + _i * 8192), 16, 0, 0); } while (0)
; #define PG8_LDA(dst, b, h) do { _Pragma("unroll") for (int m = 0; m < 4; ++m) _Pragma("unroll") for (int k = 0; k < 2; ++k) dst[m][k] = *(const LAS bf16x8*)(lds + PG8_SA(b, h) + aoff + m * 2048 + k * 1024); } while (0)
; #define PG8_LDB(dst, b, h) do { _Pragma("unroll") for (int n = 0; n < 2; ++n) _Pragma("unroll") for (int k = 0; k < 2; ++k) dst[n][k] = *(const LAS bf16x8*)(lds + PG8_SB(b, h) + boff + n * 2048 + k * 1024); } while (0)
; #define PG8_MMA(ai, bj, At, Bt) do { __builtin_amdgcn_s_setprio(1); _Pragma("unroll") for (int m = 0; m < 4; ++m) _Pragma("unroll") for (int n = 0; n < 2; ++n) _Pragma("unroll") for (int k = 0; k < 2; ++k) \
;         acc[ai][bj][m][n] = __builtin_amdgcn_mfma_f32_16x16x32_bf16(Bt[n][k], At[m][k], acc[ai][bj][m][n], 0, 0, 0); __builtin_amdgcn_s_setprio(0); } while (0)
; #define PG8_WAIT_V(n) asm volatile("s_waitcnt vmcnt(" #n ")" ::: "memory")
; #define PG8_WAIT_L(n) asm volatile("s_waitcnt lgkmcnt(" #n ")" ::: "memory")
; #define PG8_BAR __builtin_amdgcn_s_barrier()
; #define PG8_SCHED __builtin_amdgcn_sched_barrier(0)
; template <class Epi, class Sched>
; __device__ __forceinline__ void gemm_phase(LAS unsigned char* lds, const int K, const Sched& S, const Epi& E) {
;     ...
;             PG8_LDB(B0, 0, 0); PG8_SCHED; PG8_LDA(At, 0, 0); PG8_STAGE(PG8_SA(1, 1), a1 + hstepA, voffA);
;             PG8_WAIT_L(8); PG8_BAR; PG8_WAIT_L(0); PG8_MMA(0, 0, At, B0); PG8_BAR; PG8_SCHED;
;             PG8_LDB(B1, 0, 1); PG8_STAGE(PG8_SB(0, 0), b2, voffB);
;             PG8_BAR; PG8_WAIT_L(0); PG8_MMA(0, 1, At, B1); PG8_BAR;
;             PG8_LDA(At, 0, 1); PG8_STAGE(PG8_SA(0, 0), a2, voffA);
;             PG8_BAR; PG8_WAIT_L(0); PG8_MMA(1, 0, At, B0); PG8_BAR; PG8_SCHED;
;             PG8_STAGE(PG8_SB(0, 1), b2 + hstep, voffB);
;             PG8_WAIT_V(6); PG8_BAR; PG8_MMA(1, 1, At, B1); PG8_BAR;
.Lpeel_p2:
	ds_read_b128 v[164:167], v160
	ds_read_b128 v[174:177], v160 offset:1024
	ds_read_b128 v[178:181], v160 offset:2048
	ds_read_b128 v[182:185], v160 offset:3072
	s_add_u32 s72, s70, 0xfffc0080
	s_addc_u32 s73, s71, -1
	s_cmp_eq_u32 s67, 12
	s_cselect_b32 s75, s45, s73
	s_cselect_b32 s74, s44, s72
	s_cselect_b32 s73, s47, s65
	s_cselect_b32 s72, s46, s43
	v_lshl_add_u64 v[168:169], s[70:71], 0, v[156:157]
	s_add_i32 m0, s55, 0xc000
	ds_read_b128 v[186:189], v161
	ds_read_b128 v[190:193], v161 offset:1024
	ds_read_b128 v[194:197], v161 offset:2048
	ds_read_b128 v[198:201], v161 offset:3072
	ds_read_b128 v[202:205], v161 offset:4096
	ds_read_b128 v[206:209], v161 offset:5120
	ds_read_b128 v[210:213], v161 offset:6144
	ds_read_b128 v[214:217], v161 offset:7168
	global_load_lds_dwordx4 v[168:169], off
	v_lshl_add_u64 v[168:169], s[70:71], 0, v[158:159]
	s_add_i32 m0, s55, 0xe000
	s_nop 0
	global_load_lds_dwordx4 v[168:169], off
	s_waitcnt lgkmcnt(8)
	s_barrier
	s_waitcnt lgkmcnt(0)
	s_setprio 1
	v_mfma_f32_16x16x32_bf16 v[124:127], v[164:167], v[186:189], 0
	v_mfma_f32_16x16x32_bf16 v[120:123], v[178:181], v[186:189], 0
	v_mfma_f32_16x16x32_bf16 v[112:115], v[164:167], v[194:197], 0
	v_mfma_f32_16x16x32_bf16 v[104:107], v[178:181], v[194:197], 0
	v_mfma_f32_16x16x32_bf16 v[100:103], v[164:167], v[202:205], 0
	v_mfma_f32_16x16x32_bf16 v[92:95], v[178:181], v[202:205], 0
	v_mfma_f32_16x16x32_bf16 v[84:87], v[164:167], v[210:213], 0
	v_mfma_f32_16x16x32_bf16 v[76:79], v[178:181], v[210:213], 0
	v_mfma_f32_16x16x32_bf16 v[124:127], v[174:177], v[190:193], v[124:127]
	v_mfma_f32_16x16x32_bf16 v[120:123], v[182:185], v[190:193], v[120:123]
	v_mfma_f32_16x16x32_bf16 v[112:115], v[174:177], v[198:201], v[112:115]
	v_mfma_f32_16x16x32_bf16 v[104:107], v[182:185], v[198:201], v[104:107]
	v_mfma_f32_16x16x32_bf16 v[100:103], v[174:177], v[206:209], v[100:103]
	v_mfma_f32_16x16x32_bf16 v[92:95], v[182:185], v[206:209], v[92:95]
	v_mfma_f32_16x16x32_bf16 v[84:87], v[174:177], v[214:217], v[84:87]
	v_mfma_f32_16x16x32_bf16 v[76:79], v[182:185], v[214:217], v[76:79]
	s_setprio 0
	s_barrier
	s_add_i32 vcc_lo, s33, s54
	v_lshl_add_u64 v[168:169], s[72:73], 0, v[130:131]
	s_mov_b32 m0, vcc_lo
	ds_read_b128 v[218:221], v162
	ds_read_b128 v[222:225], v162 offset:1024
	ds_read_b128 v[226:229], v162 offset:2048
	ds_read_b128 v[230:233], v162 offset:3072
	global_load_lds_dwordx4 v[168:169], off
	v_lshl_add_u64 v[234:235], s[72:73], 0, v[134:135]
	s_add_i32 m0, vcc_lo, 0x2000
	s_nop 0
	global_load_lds_dwordx4 v[234:235], off
	s_barrier
	s_waitcnt lgkmcnt(0)
	s_setprio 1
	v_mfma_f32_16x16x32_bf16 v[116:119], v[218:221], v[186:189], 0
	v_mfma_f32_16x16x32_bf16 v[108:111], v[226:229], v[186:189], 0
	v_mfma_f32_16x16x32_bf16 v[96:99], v[218:221], v[194:197], 0
	v_mfma_f32_16x16x32_bf16 v[88:91], v[226:229], v[194:197], 0
	v_mfma_f32_16x16x32_bf16 v[80:83], v[218:221], v[202:205], 0
	v_mfma_f32_16x16x32_bf16 v[72:75], v[226:229], v[202:205], 0
	v_mfma_f32_16x16x32_bf16 v[68:71], v[218:221], v[210:213], 0
	v_mfma_f32_16x16x32_bf16 v[64:67], v[226:229], v[210:213], 0
	v_mfma_f32_16x16x32_bf16 v[116:119], v[222:225], v[190:193], v[116:119]
	v_mfma_f32_16x16x32_bf16 v[108:111], v[230:233], v[190:193], v[108:111]
	v_mfma_f32_16x16x32_bf16 v[96:99], v[222:225], v[198:201], v[96:99]
	v_mfma_f32_16x16x32_bf16 v[88:91], v[230:233], v[198:201], v[88:91]
	v_mfma_f32_16x16x32_bf16 v[80:83], v[222:225], v[206:209], v[80:83]
	v_mfma_f32_16x16x32_bf16 v[72:75], v[230:233], v[206:209], v[72:75]
	v_mfma_f32_16x16x32_bf16 v[68:71], v[222:225], v[214:217], v[68:71]
	v_mfma_f32_16x16x32_bf16 v[64:67], v[230:233], v[214:217], v[64:67]
	s_setprio 0
	s_mov_b32 m0, s55
	v_lshl_add_u64 v[236:237], s[74:75], 0, v[128:129]
	s_barrier
	ds_read_b128 v[186:189], v161 offset:16384
	ds_read_b128 v[190:193], v161 offset:17408
	ds_read_b128 v[194:197], v161 offset:18432
	ds_read_b128 v[198:201], v161 offset:19456
	ds_read_b128 v[202:205], v161 offset:20480
	ds_read_b128 v[206:209], v161 offset:21504
	ds_read_b128 v[210:213], v161 offset:22528
	ds_read_b128 v[214:217], v161 offset:23552
	global_load_lds_dwordx4 v[236:237], off
	v_lshl_add_u64 v[238:239], s[74:75], 0, v[132:133]
	s_mov_b32 m0, s86
	s_nop 0
	global_load_lds_dwordx4 v[238:239], off
	s_barrier
	s_waitcnt lgkmcnt(0)
	s_setprio 1
	v_mfma_f32_16x16x32_bf16 v[60:63], v[164:167], v[186:189], 0
	v_mfma_f32_16x16x32_bf16 v[56:59], v[178:181], v[186:189], 0
	v_mfma_f32_16x16x32_bf16 v[52:55], v[164:167], v[194:197], 0
	v_mfma_f32_16x16x32_bf16 v[44:47], v[178:181], v[194:197], 0
	v_mfma_f32_16x16x32_bf16 v[36:39], v[164:167], v[202:205], 0
	v_mfma_f32_16x16x32_bf16 v[28:31], v[178:181], v[202:205], 0
	v_mfma_f32_16x16x32_bf16 v[20:23], v[164:167], v[210:213], 0
	v_mfma_f32_16x16x32_bf16 v[12:15], v[178:181], v[210:213], 0
	v_mfma_f32_16x16x32_bf16 v[60:63], v[174:177], v[190:193], v[60:63]
	v_mfma_f32_16x16x32_bf16 v[56:59], v[182:185], v[190:193], v[56:59]
	v_mfma_f32_16x16x32_bf16 v[52:55], v[174:177], v[198:201], v[52:55]
	v_mfma_f32_16x16x32_bf16 v[44:47], v[182:185], v[198:201], v[44:47]
	v_mfma_f32_16x16x32_bf16 v[36:39], v[174:177], v[206:209], v[36:39]
	v_mfma_f32_16x16x32_bf16 v[28:31], v[182:185], v[206:209], v[28:31]
	v_mfma_f32_16x16x32_bf16 v[20:23], v[174:177], v[214:217], v[20:23]
	v_mfma_f32_16x16x32_bf16 v[12:15], v[182:185], v[214:217], v[12:15]
	s_setprio 0
	s_barrier
	s_add_u32 vcc_lo, s72, 0x40000
	s_addc_u32 vcc_hi, s73, 0
	s_add_i32 s79, s52, s54
	v_lshl_add_u64 v[164:165], vcc, 0, v[130:131]
	s_mov_b32 m0, s79
	s_nop 0
	global_load_lds_dwordx4 v[164:165], off
	v_lshl_add_u64 v[164:165], vcc, 0, v[134:135]
	s_add_i32 m0, s79, 0x2000
	s_nop 0
	global_load_lds_dwordx4 v[164:165], off
	s_waitcnt vmcnt(6)
	s_barrier
; #define PG8_STAGE(bufoff, gbase, voff) do { _Pragma("unroll") for (int _i = 0; _i < 2; ++_i) \
;         __builtin_amdgcn_global_load_lds((const unsigned*)((const char*)(gbase) + (voff)[_i]), (LAS unsigned*)(lds + (bufoff) + ldsw + _i * 8192), 16, 0, 0); } while (0)
; #define PG8_LDA(dst, b, h) do { _Pragma("unroll") for (int m = 0; m < 4; ++m) _Pragma("unroll") for (int k = 0; k < 2; ++k) dst[m][k] = *(const LAS bf16x8*)(lds + PG8_SA(b, h) + aoff + m * 2048 + k * 1024); } while (0)
; #define PG8_LDB(dst, b, h) do { _Pragma("unroll") for (int n = 0; n < 2; ++n) _Pragma("unroll") for (int k = 0; k < 2; ++k) dst[n][k] = *(const LAS bf16x8*)(lds + PG8_SB(b, h) + boff + n * 2048 + k * 1024); } while (0)
; #define PG8_MMA(ai, bj, At, Bt) do { __builtin_amdgcn_s_setprio(1); _Pragma("unroll") for (int m = 0; m < 4; ++m) _Pragma("unroll") for (int n = 0; n < 2; ++n) _Pragma("unroll") for (int k = 0; k < 2; ++k) \
;         acc[ai][bj][m][n] = __builtin_amdgcn_mfma_f32_16x16x32_bf16(Bt[n][k], At[m][k], acc[ai][bj][m][n], 0, 0, 0); __builtin_amdgcn_s_setprio(0); } while (0)
; #define PG8_WAIT_V(n) asm volatile("s_waitcnt vmcnt(" #n ")" ::: "memory")
; #define PG8_WAIT_L(n) asm volatile("s_waitcnt lgkmcnt(" #n ")" ::: "memory")
; #define PG8_BAR __builtin_amdgcn_s_barrier()
; #define PG8_SCHED __builtin_amdgcn_sched_barrier(0)
; template <class Epi, class Sched>
; __device__ __forceinline__ void gemm_phase(LAS unsigned char* lds, const int K, const Sched& S, const Epi& E) {
;     ...
;             PG8_WAIT_V(6); PG8_BAR; PG8_MMA(1, 1, At, B1); PG8_BAR;
;             PG8_LDB(B0, 1, 0); PG8_SCHED; PG8_LDA(At, 1, 0); PG8_STAGE(PG8_SA(0, 1), a2 + hstepA, voffA);
;             PG8_WAIT_L(8); PG8_BAR; PG8_WAIT_L(0); PG8_MMA(0, 0, At, B0); PG8_BAR; PG8_SCHED;
;             PG8_LDB(B1, 1, 1); PG8_STAGE(PG8_SB(1, 0), b3, voffB);
;             PG8_BAR; PG8_WAIT_L(0); PG8_MMA(0, 1, At, B1); PG8_BAR;
;             PG8_LDA(At, 1, 1); PG8_STAGE(PG8_SA(1, 0), a3, voffA);
;             PG8_BAR; PG8_WAIT_L(0); PG8_MMA(1, 0, At, B0); PG8_BAR; PG8_SCHED;
	s_setprio 1
	v_mfma_f32_16x16x32_bf16 v[48:51], v[218:221], v[186:189], 0
	v_mfma_f32_16x16x32_bf16 v[40:43], v[226:229], v[186:189], 0
	v_mfma_f32_16x16x32_bf16 v[32:35], v[218:221], v[194:197], 0
	v_mfma_f32_16x16x32_bf16 v[24:27], v[226:229], v[194:197], 0
	v_mfma_f32_16x16x32_bf16 v[16:19], v[218:221], v[202:205], 0
	v_mfma_f32_16x16x32_bf16 v[8:11], v[226:229], v[202:205], 0
	v_mfma_f32_16x16x32_bf16 v[4:7], v[218:221], v[210:213], 0
	v_mfma_f32_16x16x32_bf16 v[0:3], v[226:229], v[210:213], 0
	v_mfma_f32_16x16x32_bf16 v[48:51], v[222:225], v[190:193], v[48:51]
	v_mfma_f32_16x16x32_bf16 v[40:43], v[230:233], v[190:193], v[40:43]
	v_mfma_f32_16x16x32_bf16 v[32:35], v[222:225], v[198:201], v[32:35]
	v_mfma_f32_16x16x32_bf16 v[24:27], v[230:233], v[198:201], v[24:27]
	v_mfma_f32_16x16x32_bf16 v[16:19], v[222:225], v[206:209], v[16:19]
	v_mfma_f32_16x16x32_bf16 v[8:11], v[230:233], v[206:209], v[8:11]
	v_mfma_f32_16x16x32_bf16 v[4:7], v[222:225], v[214:217], v[4:7]
	v_mfma_f32_16x16x32_bf16 v[0:3], v[230:233], v[214:217], v[0:3]
	s_setprio 0
	s_add_i32 s79, 0, 0x18000
	v_add_u32_e32 v173, s79, v139
	s_barrier
	ds_read_b128 v[164:167], v173
	ds_read_b128 v[174:177], v173 offset:1024
	ds_read_b128 v[178:181], v173 offset:2048
	ds_read_b128 v[182:185], v173 offset:3072
	s_add_u32 s74, s74, 0x40000
	s_addc_u32 s75, s75, 0
	s_mov_b32 m0, s56
	v_lshl_add_u64 v[218:219], s[74:75], 0, v[128:129]
	ds_read_b128 v[186:189], v161 offset:32768
	ds_read_b128 v[190:193], v161 offset:33792
	ds_read_b128 v[194:197], v161 offset:34816
	ds_read_b128 v[198:201], v161 offset:35840
	ds_read_b128 v[202:205], v161 offset:36864
	ds_read_b128 v[206:209], v161 offset:37888
	ds_read_b128 v[210:213], v161 offset:38912
	ds_read_b128 v[214:217], v161 offset:39936
	global_load_lds_dwordx4 v[218:219], off
	v_lshl_add_u64 v[218:219], s[74:75], 0, v[132:133]
	s_mov_b32 m0, s57
	s_nop 0
	global_load_lds_dwordx4 v[218:219], off
	s_waitcnt lgkmcnt(8)
	s_barrier
	s_waitcnt lgkmcnt(0)
	s_setprio 1
	v_mfma_f32_16x16x32_bf16 v[124:127], v[164:167], v[186:189], v[124:127]
	v_mfma_f32_16x16x32_bf16 v[120:123], v[178:181], v[186:189], v[120:123]
	v_mfma_f32_16x16x32_bf16 v[112:115], v[164:167], v[194:197], v[112:115]
	v_mfma_f32_16x16x32_bf16 v[104:107], v[178:181], v[194:197], v[104:107]
	v_mfma_f32_16x16x32_bf16 v[100:103], v[164:167], v[202:205], v[100:103]
	v_mfma_f32_16x16x32_bf16 v[92:95], v[178:181], v[202:205], v[92:95]
	v_mfma_f32_16x16x32_bf16 v[84:87], v[164:167], v[210:213], v[84:87]
	v_mfma_f32_16x16x32_bf16 v[76:79], v[178:181], v[210:213], v[76:79]
	v_mfma_f32_16x16x32_bf16 v[124:127], v[174:177], v[190:193], v[124:127]
	v_mfma_f32_16x16x32_bf16 v[120:123], v[182:185], v[190:193], v[120:123]
	v_mfma_f32_16x16x32_bf16 v[112:115], v[174:177], v[198:201], v[112:115]
	v_mfma_f32_16x16x32_bf16 v[104:107], v[182:185], v[198:201], v[104:107]
	v_mfma_f32_16x16x32_bf16 v[100:103], v[174:177], v[206:209], v[100:103]
	v_mfma_f32_16x16x32_bf16 v[92:95], v[182:185], v[206:209], v[92:95]
	v_mfma_f32_16x16x32_bf16 v[84:87], v[174:177], v[214:217], v[84:87]
	v_mfma_f32_16x16x32_bf16 v[76:79], v[182:185], v[214:217], v[76:79]
	s_setprio 0
	s_barrier
	s_add_i32 s74, 0, 0x1c000
	s_add_i32 s75, s79, s54
	v_add_u32_e32 v173, s74, v139
	v_lshl_add_u64 v[168:169], v[168:169], 0, s[38:39]
	s_mov_b32 m0, s75
	ds_read_b128 v[218:221], v173
	ds_read_b128 v[222:225], v173 offset:1024
	ds_read_b128 v[226:229], v173 offset:2048
	ds_read_b128 v[230:233], v173 offset:3072
	global_load_lds_dwordx4 v[168:169], off
	v_lshl_add_u64 v[168:169], v[234:235], 0, s[38:39]
	s_add_i32 m0, s75, 0x2000
	s_nop 0
	global_load_lds_dwordx4 v[168:169], off
	s_barrier
	s_waitcnt lgkmcnt(0)
	s_setprio 1
	v_mfma_f32_16x16x32_bf16 v[116:119], v[218:221], v[186:189], v[116:119]
	v_mfma_f32_16x16x32_bf16 v[108:111], v[226:229], v[186:189], v[108:111]
	v_mfma_f32_16x16x32_bf16 v[96:99], v[218:221], v[194:197], v[96:99]
	v_mfma_f32_16x16x32_bf16 v[88:91], v[226:229], v[194:197], v[88:91]
	v_mfma_f32_16x16x32_bf16 v[80:83], v[218:221], v[202:205], v[80:83]
	v_mfma_f32_16x16x32_bf16 v[72:75], v[226:229], v[202:205], v[72:75]
	v_mfma_f32_16x16x32_bf16 v[68:71], v[218:221], v[210:213], v[68:71]
	v_mfma_f32_16x16x32_bf16 v[64:67], v[226:229], v[210:213], v[64:67]
	v_mfma_f32_16x16x32_bf16 v[116:119], v[222:225], v[190:193], v[116:119]
	v_mfma_f32_16x16x32_bf16 v[108:111], v[230:233], v[190:193], v[108:111]
	v_mfma_f32_16x16x32_bf16 v[96:99], v[222:225], v[198:201], v[96:99]
	v_mfma_f32_16x16x32_bf16 v[88:91], v[230:233], v[198:201], v[88:91]
	v_mfma_f32_16x16x32_bf16 v[80:83], v[222:225], v[206:209], v[80:83]
	v_mfma_f32_16x16x32_bf16 v[72:75], v[230:233], v[206:209], v[72:75]
	v_mfma_f32_16x16x32_bf16 v[68:71], v[222:225], v[214:217], v[68:71]
	v_mfma_f32_16x16x32_bf16 v[64:67], v[230:233], v[214:217], v[64:67]
	s_setprio 0
	s_mov_b32 m0, s58
	v_lshl_add_u64 v[168:169], v[236:237], 0, s[38:39]
	s_barrier
	ds_read_b128 v[186:189], v161 offset:49152
	ds_read_b128 v[190:193], v161 offset:50176
	ds_read_b128 v[194:197], v161 offset:51200
	ds_read_b128 v[198:201], v161 offset:52224
	ds_read_b128 v[202:205], v161 offset:53248
	ds_read_b128 v[206:209], v161 offset:54272
	ds_read_b128 v[210:213], v161 offset:55296
	ds_read_b128 v[214:217], v161 offset:56320
	global_load_lds_dwordx4 v[168:169], off
	v_lshl_add_u64 v[168:169], v[238:239], 0, s[38:39]
	s_mov_b32 m0, s59
	s_nop 0
	global_load_lds_dwordx4 v[168:169], off
	s_barrier
; #define PG8_STAGE(bufoff, gbase, voff) do { _Pragma("unroll") for (int _i = 0; _i < 2; ++_i) \
;         __builtin_amdgcn_global_load_lds((const unsigned*)((const char*)(gbase) + (voff)[_i]), (LAS unsigned*)(lds + (bufoff) + ldsw + _i * 8192), 16, 0, 0); } while (0)
; #define PG8_LDA(dst, b, h) do { _Pragma("unroll") for (int m = 0; m < 4; ++m) _Pragma("unroll") for (int k = 0; k < 2; ++k) dst[m][k] = *(const LAS bf16x8*)(lds + PG8_SA(b, h) + aoff + m * 2048 + k * 1024); } while (0)
; #define PG8_LDB(dst, b, h) do { _Pragma("unroll") for (int n = 0; n < 2; ++n) _Pragma("unroll") for (int k = 0; k < 2; ++k) dst[n][k] = *(const LAS bf16x8*)(lds + PG8_SB(b, h) + boff + n * 2048 + k * 1024); } while (0)
; #define PG8_WAIT_V(n) asm volatile("s_waitcnt vmcnt(" #n ")" ::: "memory")
; #define PG8_WAIT_L(n) asm volatile("s_waitcnt lgkmcnt(" #n ")" ::: "memory")
; #define PG8_BAR __builtin_amdgcn_s_barrier()
; #define PG8_SCHED __builtin_amdgcn_sched_barrier(0)
; template <class Epi, class Sched>
; __device__ __forceinline__ void gemm_phase(LAS unsigned char* lds, const int K, const Sched& S, const Epi& E) {
;     ...
;             PG8_LDB(B0, 0, 0); PG8_SCHED; PG8_LDA(At, 0, 0); PG8_STAGE(PG8_SA(1, 1), a1 + hstepA, voffA);
;             PG8_WAIT_L(8); PG8_BAR; PG8_WAIT_L(0); PG8_MMA(0, 0, At, B0); PG8_BAR; PG8_SCHED;
;             PG8_LDB(B1, 0, 1); PG8_STAGE(PG8_SB(0, 0), b2, voffB);
;             PG8_BAR; PG8_WAIT_L(0); PG8_MMA(0, 1, At, B1); PG8_BAR;
;             PG8_LDA(At, 0, 1); PG8_STAGE(PG8_SA(0, 0), a2, voffA);
;             PG8_BAR; PG8_WAIT_L(0); PG8_MMA(1, 0, At, B0); PG8_BAR; PG8_SCHED;
;             PG8_STAGE(PG8_SB(0, 1), b2 + hstep, voffB);
;             PG8_WAIT_V(6); PG8_BAR; PG8_MMA(1, 1, At, B1); PG8_BAR;
;             PG8_LDB(B0, 1, 0); PG8_SCHED; PG8_LDA(At, 1, 0); PG8_STAGE(PG8_SA(0, 1), a2 + hstepA, voffA);
;             PG8_WAIT_L(8); PG8_BAR; PG8_WAIT_L(0); PG8_MMA(0, 0, At, B0); PG8_BAR; PG8_SCHED;
;             PG8_LDB(B1, 1, 1); PG8_STAGE(PG8_SB(1, 0), b3, voffB);
;             PG8_BAR; PG8_WAIT_L(0); PG8_MMA(0, 1, At, B1); PG8_BAR;
;             PG8_LDA(At, 1, 1); PG8_STAGE(PG8_SA(1, 0), a3, voffA);
;             PG8_BAR; PG8_WAIT_L(0); PG8_MMA(1, 0, At, B0); PG8_BAR; PG8_SCHED;
;             PG8_STAGE(PG8_SB(1, 1), b3 + hstep, voffB);
;             PG8_WAIT_V(6); PG8_BAR; PG8_MMA(1, 1, At, B1); PG8_BAR;
	s_waitcnt lgkmcnt(0)
	s_setprio 1
	v_mfma_f32_16x16x32_bf16 v[60:63], v[164:167], v[186:189], v[60:63]
	v_mfma_f32_16x16x32_bf16 v[56:59], v[178:181], v[186:189], v[56:59]
	v_mfma_f32_16x16x32_bf16 v[52:55], v[164:167], v[194:197], v[52:55]
	v_mfma_f32_16x16x32_bf16 v[44:47], v[178:181], v[194:197], v[44:47]
	v_mfma_f32_16x16x32_bf16 v[36:39], v[164:167], v[202:205], v[36:39]
	v_mfma_f32_16x16x32_bf16 v[28:31], v[178:181], v[202:205], v[28:31]
	v_mfma_f32_16x16x32_bf16 v[20:23], v[164:167], v[210:213], v[20:23]
	v_mfma_f32_16x16x32_bf16 v[12:15], v[178:181], v[210:213], v[12:15]
	v_mfma_f32_16x16x32_bf16 v[60:63], v[174:177], v[190:193], v[60:63]
	v_mfma_f32_16x16x32_bf16 v[56:59], v[182:185], v[190:193], v[56:59]
	v_mfma_f32_16x16x32_bf16 v[52:55], v[174:177], v[198:201], v[52:55]
	v_mfma_f32_16x16x32_bf16 v[44:47], v[182:185], v[198:201], v[44:47]
	v_mfma_f32_16x16x32_bf16 v[36:39], v[174:177], v[206:209], v[36:39]
	v_mfma_f32_16x16x32_bf16 v[28:31], v[182:185], v[206:209], v[28:31]
	v_mfma_f32_16x16x32_bf16 v[20:23], v[174:177], v[214:217], v[20:23]
	v_mfma_f32_16x16x32_bf16 v[12:15], v[182:185], v[214:217], v[12:15]
	s_setprio 0
	s_barrier
	s_add_u32 s72, s72, 0x40080
	s_addc_u32 s73, s73, 0
	s_add_i32 s74, s74, s54
	v_lshl_add_u64 v[164:165], s[72:73], 0, v[130:131]
	s_mov_b32 m0, s74
	s_nop 0
	global_load_lds_dwordx4 v[164:165], off
	v_lshl_add_u64 v[164:165], s[72:73], 0, v[134:135]
	s_add_i32 m0, s74, 0x2000
	s_nop 0
	global_load_lds_dwordx4 v[164:165], off
	s_waitcnt vmcnt(6)
	s_barrier
	s_setprio 1
	v_mfma_f32_16x16x32_bf16 v[48:51], v[218:221], v[186:189], v[48:51]
	v_mfma_f32_16x16x32_bf16 v[40:43], v[226:229], v[186:189], v[40:43]
	v_mfma_f32_16x16x32_bf16 v[32:35], v[218:221], v[194:197], v[32:35]
	v_mfma_f32_16x16x32_bf16 v[24:27], v[226:229], v[194:197], v[24:27]
	v_mfma_f32_16x16x32_bf16 v[16:19], v[218:221], v[202:205], v[16:19]
	v_mfma_f32_16x16x32_bf16 v[8:11], v[226:229], v[202:205], v[8:11]
	v_mfma_f32_16x16x32_bf16 v[4:7], v[218:221], v[210:213], v[4:7]
	v_mfma_f32_16x16x32_bf16 v[0:3], v[226:229], v[210:213], v[0:3]
	v_mfma_f32_16x16x32_bf16 v[48:51], v[222:225], v[190:193], v[48:51]
	v_mfma_f32_16x16x32_bf16 v[40:43], v[230:233], v[190:193], v[40:43]
	v_mfma_f32_16x16x32_bf16 v[32:35], v[222:225], v[198:201], v[32:35]
	v_mfma_f32_16x16x32_bf16 v[24:27], v[230:233], v[198:201], v[24:27]
	v_mfma_f32_16x16x32_bf16 v[16:19], v[222:225], v[206:209], v[16:19]
	v_mfma_f32_16x16x32_bf16 v[8:11], v[230:233], v[206:209], v[8:11]
	v_mfma_f32_16x16x32_bf16 v[4:7], v[222:225], v[214:217], v[4:7]
	v_mfma_f32_16x16x32_bf16 v[0:3], v[230:233], v[214:217], v[0:3]
	s_setprio 0
	s_add_i32 s67, s67, 2
	s_add_u32 s70, s70, 0x100
	s_addc_u32 s71, s71, 0
	s_add_u32 s43, s43, 0x100
	s_addc_u32 s65, s65, 0
	s_cmp_gt_u32 s67, 13
	s_barrier
.LBB0_189:
	ds_read_b128 v[164:167], v160
	ds_read_b128 v[174:177], v160 offset:1024
	ds_read_b128 v[178:181], v160 offset:2048
	ds_read_b128 v[182:185], v160 offset:3072
	s_add_u32 s72, s70, 0xfffc0080
	s_addc_u32 s73, s71, -1
	s_cmp_eq_u32 s67, 12
	s_cselect_b32 s75, s45, s73
	s_cselect_b32 s74, s44, s72
	s_cselect_b32 s73, s47, s65
	s_cselect_b32 s72, s46, s43
	v_lshl_add_u64 v[168:169], s[70:71], 0, v[156:157]
	s_add_i32 m0, s55, 0xc000
	ds_read_b128 v[186:189], v161
	ds_read_b128 v[190:193], v161 offset:1024
	ds_read_b128 v[194:197], v161 offset:2048
	ds_read_b128 v[198:201], v161 offset:3072
	ds_read_b128 v[202:205], v161 offset:4096
	ds_read_b128 v[206:209], v161 offset:5120
	ds_read_b128 v[210:213], v161 offset:6144
	ds_read_b128 v[214:217], v161 offset:7168
	global_load_lds_dwordx4 v[168:169], off
	v_lshl_add_u64 v[168:169], s[70:71], 0, v[158:159]
	s_add_i32 m0, s55, 0xe000
	s_nop 0
	global_load_lds_dwordx4 v[168:169], off
	s_waitcnt lgkmcnt(8)
	s_barrier
	s_waitcnt lgkmcnt(0)
	s_setprio 1
	v_mfma_f32_16x16x32_bf16 v[124:127], v[164:167], v[186:189], v[124:127]
	v_mfma_f32_16x16x32_bf16 v[120:123], v[178:181], v[186:189], v[120:123]
	v_mfma_f32_16x16x32_bf16 v[112:115], v[164:167], v[194:197], v[112:115]
	v_mfma_f32_16x16x32_bf16 v[104:107], v[178:181], v[194:197], v[104:107]
	v_mfma_f32_16x16x32_bf16 v[100:103], v[164:167], v[202:205], v[100:103]
	v_mfma_f32_16x16x32_bf16 v[92:95], v[178:181], v[202:205], v[92:95]
	v_mfma_f32_16x16x32_bf16 v[84:87], v[164:167], v[210:213], v[84:87]
	v_mfma_f32_16x16x32_bf16 v[76:79], v[178:181], v[210:213], v[76:79]
	v_mfma_f32_16x16x32_bf16 v[124:127], v[174:177], v[190:193], v[124:127]
	v_mfma_f32_16x16x32_bf16 v[120:123], v[182:185], v[190:193], v[120:123]
	v_mfma_f32_16x16x32_bf16 v[112:115], v[174:177], v[198:201], v[112:115]
	v_mfma_f32_16x16x32_bf16 v[104:107], v[182:185], v[198:201], v[104:107]
	v_mfma_f32_16x16x32_bf16 v[100:103], v[174:177], v[206:209], v[100:103]
	v_mfma_f32_16x16x32_bf16 v[92:95], v[182:185], v[206:209], v[92:95]
	v_mfma_f32_16x16x32_bf16 v[84:87], v[174:177], v[214:217], v[84:87]
	v_mfma_f32_16x16x32_bf16 v[76:79], v[182:185], v[214:217], v[76:79]
	s_setprio 0
	s_barrier
	s_add_i32 vcc_lo, s33, s54
	v_lshl_add_u64 v[168:169], s[72:73], 0, v[130:131]
	s_mov_b32 m0, vcc_lo
	ds_read_b128 v[218:221], v162
	ds_read_b128 v[222:225], v162 offset:1024
	ds_read_b128 v[226:229], v162 offset:2048
	ds_read_b128 v[230:233], v162 offset:3072
	global_load_lds_dwordx4 v[168:169], off
	v_lshl_add_u64 v[234:235], s[72:73], 0, v[134:135]
	s_add_i32 m0, vcc_lo, 0x2000
	s_nop 0
	global_load_lds_dwordx4 v[234:235], off
	s_barrier
; #define PG8_STAGE(bufoff, gbase, voff) do { _Pragma("unroll") for (int _i = 0; _i < 2; ++_i) \
;         __builtin_amdgcn_global_load_lds((const unsigned*)((const char*)(gbase) + (voff)[_i]), (LAS unsigned*)(lds + (bufoff) + ldsw + _i * 8192), 16, 0, 0); } while (0)
; #define PG8_LDA(dst, b, h) do { _Pragma("unroll") for (int m = 0; m < 4; ++m) _Pragma("unroll") for (int k = 0; k < 2; ++k) dst[m][k] = *(const LAS bf16x8*)(lds + PG8_SA(b, h) + aoff + m * 2048 + k * 1024); } while (0)
; #define PG8_LDB(dst, b, h) do { _Pragma("unroll") for (int n = 0; n < 2; ++n) _Pragma("unroll") for (int k = 0; k < 2; ++k) dst[n][k] = *(const LAS bf16x8*)(lds + PG8_SB(b, h) + boff + n * 2048 + k * 1024); } while (0)
; #define PG8_MMA(ai, bj, At, Bt) do { __builtin_amdgcn_s_setprio(1); _Pragma("unroll") for (int m = 0; m < 4; ++m) _Pragma("unroll") for (int n = 0; n < 2; ++n) _Pragma("unroll") for (int k = 0; k < 2; ++k) \
;         acc[ai][bj][m][n] = __builtin_amdgcn_mfma_f32_16x16x32_bf16(Bt[n][k], At[m][k], acc[ai][bj][m][n], 0, 0, 0); __builtin_amdgcn_s_setprio(0); } while (0)
; #define PG8_WAIT_V(n) asm volatile("s_waitcnt vmcnt(" #n ")" ::: "memory")
; #define PG8_WAIT_L(n) asm volatile("s_waitcnt lgkmcnt(" #n ")" ::: "memory")
; #define PG8_BAR __builtin_amdgcn_s_barrier()
; #define PG8_SCHED __builtin_amdgcn_sched_barrier(0)
; template <class Epi, class Sched>
; __device__ __forceinline__ void gemm_phase(LAS unsigned char* lds, const int K, const Sched& S, const Epi& E) {
;     ...
;             PG8_BAR; PG8_WAIT_L(0); PG8_MMA(0, 1, At, B1); PG8_BAR;
;             PG8_LDA(At, 0, 1); PG8_STAGE(PG8_SA(0, 0), a2, voffA);
;             PG8_BAR; PG8_WAIT_L(0); PG8_MMA(1, 0, At, B0); PG8_BAR; PG8_SCHED;
;             PG8_STAGE(PG8_SB(0, 1), b2 + hstep, voffB);
;             PG8_WAIT_V(6); PG8_BAR; PG8_MMA(1, 1, At, B1); PG8_BAR;
;             PG8_LDB(B0, 1, 0); PG8_SCHED; PG8_LDA(At, 1, 0); PG8_STAGE(PG8_SA(0, 1), a2 + hstepA, voffA);
;             PG8_WAIT_L(8); PG8_BAR; PG8_WAIT_L(0); PG8_MMA(0, 0, At, B0); PG8_BAR; PG8_SCHED;
	s_waitcnt lgkmcnt(0)
	s_setprio 1
	v_mfma_f32_16x16x32_bf16 v[116:119], v[218:221], v[186:189], v[116:119]
	v_mfma_f32_16x16x32_bf16 v[108:111], v[226:229], v[186:189], v[108:111]
	v_mfma_f32_16x16x32_bf16 v[96:99], v[218:221], v[194:197], v[96:99]
	v_mfma_f32_16x16x32_bf16 v[88:91], v[226:229], v[194:197], v[88:91]
	v_mfma_f32_16x16x32_bf16 v[80:83], v[218:221], v[202:205], v[80:83]
	v_mfma_f32_16x16x32_bf16 v[72:75], v[226:229], v[202:205], v[72:75]
	v_mfma_f32_16x16x32_bf16 v[68:71], v[218:221], v[210:213], v[68:71]
	v_mfma_f32_16x16x32_bf16 v[64:67], v[226:229], v[210:213], v[64:67]
	v_mfma_f32_16x16x32_bf16 v[116:119], v[222:225], v[190:193], v[116:119]
	v_mfma_f32_16x16x32_bf16 v[108:111], v[230:233], v[190:193], v[108:111]
	v_mfma_f32_16x16x32_bf16 v[96:99], v[222:225], v[198:201], v[96:99]
	v_mfma_f32_16x16x32_bf16 v[88:91], v[230:233], v[198:201], v[88:91]
	v_mfma_f32_16x16x32_bf16 v[80:83], v[222:225], v[206:209], v[80:83]
	v_mfma_f32_16x16x32_bf16 v[72:75], v[230:233], v[206:209], v[72:75]
	v_mfma_f32_16x16x32_bf16 v[68:71], v[222:225], v[214:217], v[68:71]
	v_mfma_f32_16x16x32_bf16 v[64:67], v[230:233], v[214:217], v[64:67]
	s_setprio 0
	s_mov_b32 m0, s55
	v_lshl_add_u64 v[236:237], s[74:75], 0, v[128:129]
	s_barrier
	ds_read_b128 v[186:189], v161 offset:16384
	ds_read_b128 v[190:193], v161 offset:17408
	ds_read_b128 v[194:197], v161 offset:18432
	ds_read_b128 v[198:201], v161 offset:19456
	ds_read_b128 v[202:205], v161 offset:20480
	ds_read_b128 v[206:209], v161 offset:21504
	ds_read_b128 v[210:213], v161 offset:22528
	ds_read_b128 v[214:217], v161 offset:23552
	global_load_lds_dwordx4 v[236:237], off
	v_lshl_add_u64 v[238:239], s[74:75], 0, v[132:133]
	s_mov_b32 m0, s86
	s_nop 0
	global_load_lds_dwordx4 v[238:239], off
	s_barrier
	s_waitcnt lgkmcnt(0)
	s_setprio 1
	v_mfma_f32_16x16x32_bf16 v[60:63], v[164:167], v[186:189], v[60:63]
	v_mfma_f32_16x16x32_bf16 v[56:59], v[178:181], v[186:189], v[56:59]
	v_mfma_f32_16x16x32_bf16 v[52:55], v[164:167], v[194:197], v[52:55]
	v_mfma_f32_16x16x32_bf16 v[44:47], v[178:181], v[194:197], v[44:47]
	v_mfma_f32_16x16x32_bf16 v[36:39], v[164:167], v[202:205], v[36:39]
	v_mfma_f32_16x16x32_bf16 v[28:31], v[178:181], v[202:205], v[28:31]
	v_mfma_f32_16x16x32_bf16 v[20:23], v[164:167], v[210:213], v[20:23]
	v_mfma_f32_16x16x32_bf16 v[12:15], v[178:181], v[210:213], v[12:15]
	v_mfma_f32_16x16x32_bf16 v[60:63], v[174:177], v[190:193], v[60:63]
	v_mfma_f32_16x16x32_bf16 v[56:59], v[182:185], v[190:193], v[56:59]
	v_mfma_f32_16x16x32_bf16 v[52:55], v[174:177], v[198:201], v[52:55]
	v_mfma_f32_16x16x32_bf16 v[44:47], v[182:185], v[198:201], v[44:47]
	v_mfma_f32_16x16x32_bf16 v[36:39], v[174:177], v[206:209], v[36:39]
	v_mfma_f32_16x16x32_bf16 v[28:31], v[182:185], v[206:209], v[28:31]
	v_mfma_f32_16x16x32_bf16 v[20:23], v[174:177], v[214:217], v[20:23]
	v_mfma_f32_16x16x32_bf16 v[12:15], v[182:185], v[214:217], v[12:15]
	s_setprio 0
	s_barrier
	s_add_u32 vcc_lo, s72, 0x40000
	s_addc_u32 vcc_hi, s73, 0
	s_add_i32 s79, s52, s54
	v_lshl_add_u64 v[164:165], vcc, 0, v[130:131]
	s_mov_b32 m0, s79
	s_nop 0
	global_load_lds_dwordx4 v[164:165], off
	v_lshl_add_u64 v[164:165], vcc, 0, v[134:135]
	s_add_i32 m0, s79, 0x2000
	s_nop 0
	global_load_lds_dwordx4 v[164:165], off
	s_waitcnt vmcnt(6)
	s_barrier
	s_setprio 1
	v_mfma_f32_16x16x32_bf16 v[48:51], v[218:221], v[186:189], v[48:51]
	v_mfma_f32_16x16x32_bf16 v[40:43], v[226:229], v[186:189], v[40:43]
	v_mfma_f32_16x16x32_bf16 v[32:35], v[218:221], v[194:197], v[32:35]
	v_mfma_f32_16x16x32_bf16 v[24:27], v[226:229], v[194:197], v[24:27]
	v_mfma_f32_16x16x32_bf16 v[16:19], v[218:221], v[202:205], v[16:19]
	v_mfma_f32_16x16x32_bf16 v[8:11], v[226:229], v[202:205], v[8:11]
	v_mfma_f32_16x16x32_bf16 v[4:7], v[218:221], v[210:213], v[4:7]
	v_mfma_f32_16x16x32_bf16 v[0:3], v[226:229], v[210:213], v[0:3]
	v_mfma_f32_16x16x32_bf16 v[48:51], v[222:225], v[190:193], v[48:51]
	v_mfma_f32_16x16x32_bf16 v[40:43], v[230:233], v[190:193], v[40:43]
	v_mfma_f32_16x16x32_bf16 v[32:35], v[222:225], v[198:201], v[32:35]
	v_mfma_f32_16x16x32_bf16 v[24:27], v[230:233], v[198:201], v[24:27]
	v_mfma_f32_16x16x32_bf16 v[16:19], v[222:225], v[206:209], v[16:19]
	v_mfma_f32_16x16x32_bf16 v[8:11], v[230:233], v[206:209], v[8:11]
	v_mfma_f32_16x16x32_bf16 v[4:7], v[222:225], v[214:217], v[4:7]
	v_mfma_f32_16x16x32_bf16 v[0:3], v[230:233], v[214:217], v[0:3]
	s_setprio 0
	s_add_i32 s79, 0, 0x18000
	v_add_u32_e32 v173, s79, v139
	s_barrier
	ds_read_b128 v[164:167], v173
	ds_read_b128 v[174:177], v173 offset:1024
	ds_read_b128 v[178:181], v173 offset:2048
	ds_read_b128 v[182:185], v173 offset:3072
	s_add_u32 s74, s74, 0x40000
	s_addc_u32 s75, s75, 0
	s_mov_b32 m0, s56
	v_lshl_add_u64 v[218:219], s[74:75], 0, v[128:129]
	ds_read_b128 v[186:189], v161 offset:32768
	ds_read_b128 v[190:193], v161 offset:33792
	ds_read_b128 v[194:197], v161 offset:34816
	ds_read_b128 v[198:201], v161 offset:35840
	ds_read_b128 v[202:205], v161 offset:36864
	ds_read_b128 v[206:209], v161 offset:37888
	ds_read_b128 v[210:213], v161 offset:38912
	ds_read_b128 v[214:217], v161 offset:39936
	global_load_lds_dwordx4 v[218:219], off
	v_lshl_add_u64 v[218:219], s[74:75], 0, v[132:133]
	s_mov_b32 m0, s57
	s_nop 0
	global_load_lds_dwordx4 v[218:219], off
	s_waitcnt lgkmcnt(8)
	s_barrier
; #define PG8_STAGE(bufoff, gbase, voff) do { _Pragma("unroll") for (int _i = 0; _i < 2; ++_i) \
;         __builtin_amdgcn_global_load_lds((const unsigned*)((const char*)(gbase) + (voff)[_i]), (LAS unsigned*)(lds + (bufoff) + ldsw + _i * 8192), 16, 0, 0); } while (0)
; #define PG8_LDA(dst, b, h) do { _Pragma("unroll") for (int m = 0; m < 4; ++m) _Pragma("unroll") for (int k = 0; k < 2; ++k) dst[m][k] = *(const LAS bf16x8*)(lds + PG8_SA(b, h) + aoff + m * 2048 + k * 1024); } while (0)
; #define PG8_LDB(dst, b, h) do { _Pragma("unroll") for (int n = 0; n < 2; ++n) _Pragma("unroll") for (int k = 0; k < 2; ++k) dst[n][k] = *(const LAS bf16x8*)(lds + PG8_SB(b, h) + boff + n * 2048 + k * 1024); } while (0)
; #define PG8_MMA(ai, bj, At, Bt) do { __builtin_amdgcn_s_setprio(1); _Pragma("unroll") for (int m = 0; m < 4; ++m) _Pragma("unroll") for (int n = 0; n < 2; ++n) _Pragma("unroll") for (int k = 0; k < 2; ++k) \
;         acc[ai][bj][m][n] = __builtin_amdgcn_mfma_f32_16x16x32_bf16(Bt[n][k], At[m][k], acc[ai][bj][m][n], 0, 0, 0); __builtin_amdgcn_s_setprio(0); } while (0)
; #define PG8_WAIT_V(n) asm volatile("s_waitcnt vmcnt(" #n ")" ::: "memory")
; #define PG8_WAIT_L(n) asm volatile("s_waitcnt lgkmcnt(" #n ")" ::: "memory")
; #define PG8_BAR __builtin_amdgcn_s_barrier()
; #define PG8_SCHED __builtin_amdgcn_sched_barrier(0)
; template <class Epi, class Sched>
; __device__ __forceinline__ void gemm_phase(LAS unsigned char* lds, const int K, const Sched& S, const Epi& E) {
;     ...
;             PG8_WAIT_L(8); PG8_BAR; PG8_WAIT_L(0); PG8_MMA(0, 0, At, B0); PG8_BAR; PG8_SCHED;
;             PG8_LDB(B1, 1, 1); PG8_STAGE(PG8_SB(1, 0), b3, voffB);
;             PG8_BAR; PG8_WAIT_L(0); PG8_MMA(0, 1, At, B1); PG8_BAR;
;             PG8_LDA(At, 1, 1); PG8_STAGE(PG8_SA(1, 0), a3, voffA);
;             PG8_BAR; PG8_WAIT_L(0); PG8_MMA(1, 0, At, B0); PG8_BAR; PG8_SCHED;
;             PG8_STAGE(PG8_SB(1, 1), b3 + hstep, voffB);
;             PG8_WAIT_V(6); PG8_BAR; PG8_MMA(1, 1, At, B1); PG8_BAR;
	s_waitcnt lgkmcnt(0)
	s_setprio 1
	v_mfma_f32_16x16x32_bf16 v[124:127], v[164:167], v[186:189], v[124:127]
	v_mfma_f32_16x16x32_bf16 v[120:123], v[178:181], v[186:189], v[120:123]
	v_mfma_f32_16x16x32_bf16 v[112:115], v[164:167], v[194:197], v[112:115]
	v_mfma_f32_16x16x32_bf16 v[104:107], v[178:181], v[194:197], v[104:107]
	v_mfma_f32_16x16x32_bf16 v[100:103], v[164:167], v[202:205], v[100:103]
	v_mfma_f32_16x16x32_bf16 v[92:95], v[178:181], v[202:205], v[92:95]
	v_mfma_f32_16x16x32_bf16 v[84:87], v[164:167], v[210:213], v[84:87]
	v_mfma_f32_16x16x32_bf16 v[76:79], v[178:181], v[210:213], v[76:79]
	v_mfma_f32_16x16x32_bf16 v[124:127], v[174:177], v[190:193], v[124:127]
	v_mfma_f32_16x16x32_bf16 v[120:123], v[182:185], v[190:193], v[120:123]
	v_mfma_f32_16x16x32_bf16 v[112:115], v[174:177], v[198:201], v[112:115]
	v_mfma_f32_16x16x32_bf16 v[104:107], v[182:185], v[198:201], v[104:107]
	v_mfma_f32_16x16x32_bf16 v[100:103], v[174:177], v[206:209], v[100:103]
	v_mfma_f32_16x16x32_bf16 v[92:95], v[182:185], v[206:209], v[92:95]
	v_mfma_f32_16x16x32_bf16 v[84:87], v[174:177], v[214:217], v[84:87]
	v_mfma_f32_16x16x32_bf16 v[76:79], v[182:185], v[214:217], v[76:79]
	s_setprio 0
	s_barrier
	s_add_i32 s74, 0, 0x1c000
	s_add_i32 s75, s79, s54
	v_add_u32_e32 v173, s74, v139
	v_lshl_add_u64 v[168:169], v[168:169], 0, s[38:39]
	s_mov_b32 m0, s75
	ds_read_b128 v[218:221], v173
	ds_read_b128 v[222:225], v173 offset:1024
	ds_read_b128 v[226:229], v173 offset:2048
	ds_read_b128 v[230:233], v173 offset:3072
	global_load_lds_dwordx4 v[168:169], off
	v_lshl_add_u64 v[168:169], v[234:235], 0, s[38:39]
	s_add_i32 m0, s75, 0x2000
	s_nop 0
	global_load_lds_dwordx4 v[168:169], off
	s_barrier
	s_waitcnt lgkmcnt(0)
	s_setprio 1
	v_mfma_f32_16x16x32_bf16 v[116:119], v[218:221], v[186:189], v[116:119]
	v_mfma_f32_16x16x32_bf16 v[108:111], v[226:229], v[186:189], v[108:111]
	v_mfma_f32_16x16x32_bf16 v[96:99], v[218:221], v[194:197], v[96:99]
	v_mfma_f32_16x16x32_bf16 v[88:91], v[226:229], v[194:197], v[88:91]
	v_mfma_f32_16x16x32_bf16 v[80:83], v[218:221], v[202:205], v[80:83]
	v_mfma_f32_16x16x32_bf16 v[72:75], v[226:229], v[202:205], v[72:75]
	v_mfma_f32_16x16x32_bf16 v[68:71], v[218:221], v[210:213], v[68:71]
	v_mfma_f32_16x16x32_bf16 v[64:67], v[226:229], v[210:213], v[64:67]
	v_mfma_f32_16x16x32_bf16 v[116:119], v[222:225], v[190:193], v[116:119]
	v_mfma_f32_16x16x32_bf16 v[108:111], v[230:233], v[190:193], v[108:111]
	v_mfma_f32_16x16x32_bf16 v[96:99], v[222:225], v[198:201], v[96:99]
	v_mfma_f32_16x16x32_bf16 v[88:91], v[230:233], v[198:201], v[88:91]
	v_mfma_f32_16x16x32_bf16 v[80:83], v[222:225], v[206:209], v[80:83]
	v_mfma_f32_16x16x32_bf16 v[72:75], v[230:233], v[206:209], v[72:75]
	v_mfma_f32_16x16x32_bf16 v[68:71], v[222:225], v[214:217], v[68:71]
	v_mfma_f32_16x16x32_bf16 v[64:67], v[230:233], v[214:217], v[64:67]
	s_setprio 0
	s_mov_b32 m0, s58
	v_lshl_add_u64 v[168:169], v[236:237], 0, s[38:39]
	s_barrier
	ds_read_b128 v[186:189], v161 offset:49152
	ds_read_b128 v[190:193], v161 offset:50176
	ds_read_b128 v[194:197], v161 offset:51200
	ds_read_b128 v[198:201], v161 offset:52224
	ds_read_b128 v[202:205], v161 offset:53248
	ds_read_b128 v[206:209], v161 offset:54272
	ds_read_b128 v[210:213], v161 offset:55296
	ds_read_b128 v[214:217], v161 offset:56320
	global_load_lds_dwordx4 v[168:169], off
	v_lshl_add_u64 v[168:169], v[238:239], 0, s[38:39]
	s_mov_b32 m0, s59
	s_nop 0
	global_load_lds_dwordx4 v[168:169], off
	s_barrier
	s_waitcnt lgkmcnt(0)
	s_setprio 1
	v_mfma_f32_16x16x32_bf16 v[60:63], v[164:167], v[186:189], v[60:63]
	v_mfma_f32_16x16x32_bf16 v[56:59], v[178:181], v[186:189], v[56:59]
	v_mfma_f32_16x16x32_bf16 v[52:55], v[164:167], v[194:197], v[52:55]
	v_mfma_f32_16x16x32_bf16 v[44:47], v[178:181], v[194:197], v[44:47]
	v_mfma_f32_16x16x32_bf16 v[36:39], v[164:167], v[202:205], v[36:39]
	v_mfma_f32_16x16x32_bf16 v[28:31], v[178:181], v[202:205], v[28:31]
	v_mfma_f32_16x16x32_bf16 v[20:23], v[164:167], v[210:213], v[20:23]
	v_mfma_f32_16x16x32_bf16 v[12:15], v[178:181], v[210:213], v[12:15]
	v_mfma_f32_16x16x32_bf16 v[60:63], v[174:177], v[190:193], v[60:63]
	v_mfma_f32_16x16x32_bf16 v[56:59], v[182:185], v[190:193], v[56:59]
	v_mfma_f32_16x16x32_bf16 v[52:55], v[174:177], v[198:201], v[52:55]
	v_mfma_f32_16x16x32_bf16 v[44:47], v[182:185], v[198:201], v[44:47]
	v_mfma_f32_16x16x32_bf16 v[36:39], v[174:177], v[206:209], v[36:39]
	v_mfma_f32_16x16x32_bf16 v[28:31], v[182:185], v[206:209], v[28:31]
	v_mfma_f32_16x16x32_bf16 v[20:23], v[174:177], v[214:217], v[20:23]
	v_mfma_f32_16x16x32_bf16 v[12:15], v[182:185], v[214:217], v[12:15]
	s_setprio 0
	s_barrier
	s_add_u32 s72, s72, 0x40080
	s_addc_u32 s73, s73, 0
	s_add_i32 s74, s74, s54
	v_lshl_add_u64 v[164:165], s[72:73], 0, v[130:131]
	s_mov_b32 m0, s74
	s_nop 0
	global_load_lds_dwordx4 v[164:165], off
	v_lshl_add_u64 v[164:165], s[72:73], 0, v[134:135]
	s_add_i32 m0, s74, 0x2000
	s_nop 0
	global_load_lds_dwordx4 v[164:165], off
	s_waitcnt vmcnt(6)
	s_barrier
	s_setprio 1
	v_mfma_f32_16x16x32_bf16 v[48:51], v[218:221], v[186:189], v[48:51]
	v_mfma_f32_16x16x32_bf16 v[40:43], v[226:229], v[186:189], v[40:43]
	v_mfma_f32_16x16x32_bf16 v[32:35], v[218:221], v[194:197], v[32:35]
	v_mfma_f32_16x16x32_bf16 v[24:27], v[226:229], v[194:197], v[24:27]
	v_mfma_f32_16x16x32_bf16 v[16:19], v[218:221], v[202:205], v[16:19]
	v_mfma_f32_16x16x32_bf16 v[8:11], v[226:229], v[202:205], v[8:11]
	v_mfma_f32_16x16x32_bf16 v[4:7], v[218:221], v[210:213], v[4:7]
	v_mfma_f32_16x16x32_bf16 v[0:3], v[226:229], v[210:213], v[0:3]
	v_mfma_f32_16x16x32_bf16 v[48:51], v[222:225], v[190:193], v[48:51]
	v_mfma_f32_16x16x32_bf16 v[40:43], v[230:233], v[190:193], v[40:43]
	v_mfma_f32_16x16x32_bf16 v[32:35], v[222:225], v[198:201], v[32:35]
	v_mfma_f32_16x16x32_bf16 v[24:27], v[230:233], v[198:201], v[24:27]
	v_mfma_f32_16x16x32_bf16 v[16:19], v[222:225], v[206:209], v[16:19]
	v_mfma_f32_16x16x32_bf16 v[8:11], v[230:233], v[206:209], v[8:11]
	v_mfma_f32_16x16x32_bf16 v[4:7], v[222:225], v[214:217], v[4:7]
	v_mfma_f32_16x16x32_bf16 v[0:3], v[230:233], v[214:217], v[0:3]
	s_setprio 0
	s_add_i32 s67, s67, 2
	s_add_u32 s70, s70, 0x100
	s_addc_u32 s71, s71, 0
	s_add_u32 s43, s43, 0x100
	s_addc_u32 s65, s65, 0
	s_cmp_gt_u32 s67, 13
	s_barrier
; __device__ __forceinline__ unsigned cvt_pk_bf16(float lo, float hi) { unsigned r; asm volatile("v_cvt_pk_bf16_f32 %0, %1, %2" : "=v"(r) : "v"(lo), "v"(hi)); return r; }
;     __device__ __forceinline__ void operator()(const f32x4 (&acc)[2][2][4][2], const Unit& u, int wr, int wc, int fr, int fq) const {
;         bf16_t* base = (bf16_t*)u.po + (size_t)wr * u.RS + (size_t)fr * u.rp + (size_t)(wc >> 1) * u.CS + (wc & 1) * 32 + 8 * fq;
; #pragma unroll
;         for (int ai = 0; ai < 2; ++ai)
; #pragma unroll
;             for (int m = 0; m < 4; ++m) { bf16_t* rowp = base + (size_t)(2 * ai) * u.RS + (size_t)(m * 16) * u.rp;
; #pragma unroll
;                 for (int bj = 0; bj < 2; ++bj) { const f32x4 v0 = acc[ai][bj][m][0], v1 = acc[ai][bj][m][1];
;                     u32x4 w; w.x = cvt_pk_bf16(v0[0], v0[1]); w.y = cvt_pk_bf16(v0[2], v0[3]); w.z = cvt_pk_bf16(v1[0], v1[1]); w.w = cvt_pk_bf16(v1[2], v1[3]);
;                     *(u32x4*)(rowp + (size_t)(2 * bj) * u.CS) = w; } }
;         if (u.sp) {
; #pragma unroll
;             for (int ai = 0; ai < 2; ++ai)
; #pragma unroll
;                 for (int m = 0; m < 4; ++m) { float s = 0.f;
; #pragma unroll
;                     for (int bj = 0; bj < 2; ++bj)
; #pragma unroll
;                         for (int n = 0; n < 2; ++n) { const f32x4 v = acc[ai][bj][m][n]; s += (v[0] - v[1]) + (v[2] - v[3]); }
;                     s += __shfl_xor(s, 16); s += __shfl_xor(s, 32);
;                     if (fq == 0) u.sp[(size_t)(ai * HALF + wr * 64 + m * 16 + fr) * 32 + wc] = s; }
	s_cbranch_scc0 .LBB0_189
	s_mul_hi_i32 s71, s42, s97
	s_mul_i32 s70, s42, s97
	s_ashr_i32 s43, s42, 31
	s_lshl_b64 s[70:71], s[70:71], 1
	s_add_u32 s68, s68, s70
	s_addc_u32 s69, s69, s71
	v_mad_i64_i32 v[164:165], s[70:71], s66, v138, 0
	v_lshl_add_u64 v[164:165], v[164:165], 1, s[68:69]
	s_mul_hi_i32 s69, s64, s87
	s_mul_i32 s68, s64, s87
	v_lshl_add_u64 v[164:165], s[68:69], 1, v[164:165]
	s_ashr_i32 s65, s64, 31
	v_lshl_add_u64 v[164:165], v[164:165], 0, s[6:7]
	s_ashr_i32 s67, s66, 31
	v_lshl_add_u64 v[168:169], v[164:165], 0, v[136:137]
	v_cvt_pk_bf16_f32 v164, v124, v125
	v_cvt_pk_bf16_f32 v165, v126, v127
	v_cvt_pk_bf16_f32 v166, v120, v121
	v_cvt_pk_bf16_f32 v167, v122, v123
	s_lshl_b64 s[64:65], s[64:65], 2
	global_store_dwordx4 v[168:169], v[164:167], off sc1
	v_lshl_add_u64 v[174:175], v[168:169], 0, s[64:65]
	s_lshl_b64 s[66:67], s[66:67], 5
	v_cvt_pk_bf16_f32 v164, v116, v117
	v_cvt_pk_bf16_f32 v165, v118, v119
	v_cvt_pk_bf16_f32 v166, v108, v109
	v_cvt_pk_bf16_f32 v167, v110, v111
	global_store_dwordx4 v[174:175], v[164:167], off sc1
	v_lshl_add_u64 v[174:175], v[168:169], 0, s[66:67]
	v_lshl_add_u64 v[176:177], v[174:175], 0, s[64:65]
	v_cvt_pk_bf16_f32 v164, v112, v113
	v_cvt_pk_bf16_f32 v165, v114, v115
	v_cvt_pk_bf16_f32 v166, v104, v105
	v_cvt_pk_bf16_f32 v167, v106, v107
	global_store_dwordx4 v[174:175], v[164:167], off sc1
	v_lshl_add_u64 v[174:175], v[174:175], 0, s[66:67]
	v_lshl_add_u64 v[168:169], s[42:43], 2, v[168:169]
	v_cvt_pk_bf16_f32 v164, v96, v97
	v_cvt_pk_bf16_f32 v165, v98, v99
	v_cvt_pk_bf16_f32 v166, v88, v89
	v_cvt_pk_bf16_f32 v167, v90, v91
	global_store_dwordx4 v[176:177], v[164:167], off sc1
	v_lshl_add_u64 v[176:177], v[174:175], 0, s[64:65]
	s_cmp_eq_u64 s[8:9], 0
	v_cvt_pk_bf16_f32 v164, v100, v101
	v_cvt_pk_bf16_f32 v165, v102, v103
	v_cvt_pk_bf16_f32 v166, v92, v93
	v_cvt_pk_bf16_f32 v167, v94, v95
	global_store_dwordx4 v[174:175], v[164:167], off sc1
	v_lshl_add_u64 v[174:175], v[174:175], 0, s[66:67]
	s_nop 0
	v_cvt_pk_bf16_f32 v164, v80, v81
	v_cvt_pk_bf16_f32 v165, v82, v83
	v_cvt_pk_bf16_f32 v166, v72, v73
	v_cvt_pk_bf16_f32 v167, v74, v75
	global_store_dwordx4 v[176:177], v[164:167], off sc1
	s_nop 1
	v_cvt_pk_bf16_f32 v164, v84, v85
	v_cvt_pk_bf16_f32 v165, v86, v87
	v_cvt_pk_bf16_f32 v166, v76, v77
	v_cvt_pk_bf16_f32 v167, v78, v79
	global_store_dwordx4 v[174:175], v[164:167], off sc1
	v_lshl_add_u64 v[174:175], v[174:175], 0, s[64:65]
	s_nop 0
	v_cvt_pk_bf16_f32 v164, v68, v69
	v_cvt_pk_bf16_f32 v165, v70, v71
	v_cvt_pk_bf16_f32 v166, v64, v65
	v_cvt_pk_bf16_f32 v167, v66, v67
	global_store_dwordx4 v[174:175], v[164:167], off sc1
	v_lshl_add_u64 v[174:175], v[168:169], 0, s[64:65]
	s_nop 0
	v_cvt_pk_bf16_f32 v164, v60, v61
	v_cvt_pk_bf16_f32 v165, v62, v63
	v_cvt_pk_bf16_f32 v166, v56, v57
	v_cvt_pk_bf16_f32 v167, v58, v59
	global_store_dwordx4 v[168:169], v[164:167], off sc1
	v_lshl_add_u64 v[168:169], v[168:169], 0, s[66:67]
	s_nop 0
	v_cvt_pk_bf16_f32 v164, v48, v49
	v_cvt_pk_bf16_f32 v165, v50, v51
	v_cvt_pk_bf16_f32 v166, v40, v41
	v_cvt_pk_bf16_f32 v167, v42, v43
	global_store_dwordx4 v[174:175], v[164:167], off sc1
	v_lshl_add_u64 v[174:175], v[168:169], 0, s[64:65]
	s_nop 0
	v_cvt_pk_bf16_f32 v164, v52, v53
	v_cvt_pk_bf16_f32 v165, v54, v55
	v_cvt_pk_bf16_f32 v166, v44, v45
	v_cvt_pk_bf16_f32 v167, v46, v47
	global_store_dwordx4 v[168:169], v[164:167], off sc1
	v_lshl_add_u64 v[168:169], v[168:169], 0, s[66:67]
	s_nop 0
	v_cvt_pk_bf16_f32 v164, v32, v33
	v_cvt_pk_bf16_f32 v165, v34, v35
	v_cvt_pk_bf16_f32 v166, v24, v25
	v_cvt_pk_bf16_f32 v167, v26, v27
	global_store_dwordx4 v[174:175], v[164:167], off sc1
	v_lshl_add_u64 v[174:175], v[168:169], 0, s[64:65]
	s_nop 0
	v_cvt_pk_bf16_f32 v164, v36, v37
	v_cvt_pk_bf16_f32 v165, v38, v39
	v_cvt_pk_bf16_f32 v166, v28, v29
	v_cvt_pk_bf16_f32 v167, v30, v31
	global_store_dwordx4 v[168:169], v[164:167], off sc1
	v_lshl_add_u64 v[168:169], v[168:169], 0, s[66:67]
	s_nop 0
	v_cvt_pk_bf16_f32 v164, v16, v17
	v_cvt_pk_bf16_f32 v165, v18, v19
	v_cvt_pk_bf16_f32 v166, v8, v9
	v_cvt_pk_bf16_f32 v167, v10, v11
	global_store_dwordx4 v[174:175], v[164:167], off sc1
	s_nop 1
	v_cvt_pk_bf16_f32 v164, v20, v21
	v_cvt_pk_bf16_f32 v165, v22, v23
	v_cvt_pk_bf16_f32 v166, v12, v13
	v_cvt_pk_bf16_f32 v167, v14, v15
	global_store_dwordx4 v[168:169], v[164:167], off sc1
	v_lshl_add_u64 v[168:169], v[168:169], 0, s[64:65]
	s_nop 0
	v_cvt_pk_bf16_f32 v164, v4, v5
	v_cvt_pk_bf16_f32 v165, v6, v7
	v_cvt_pk_bf16_f32 v166, v0, v1
	v_cvt_pk_bf16_f32 v167, v2, v3
	global_store_dwordx4 v[168:169], v[164:167], off sc1
	s_cbranch_scc1 .LBB0_175
	v_sub_f32_e32 v124, v124, v125
	v_sub_f32_e32 v125, v126, v127
	v_and_b32_e32 v165, 64, v163
	v_add_f32_e32 v124, v124, v125
	v_sub_f32_e32 v120, v120, v121
	v_sub_f32_e32 v121, v122, v123
	v_xor_b32_e32 v164, 16, v163
	v_add_u32_e32 v165, 64, v165
	v_add_f32_e32 v124, 0, v124
	v_add_f32_e32 v120, v120, v121
	v_sub_f32_e32 v116, v116, v117
	v_sub_f32_e32 v117, v118, v119
	v_cmp_lt_i32_e32 vcc, v164, v165
	v_add_f32_e32 v120, v124, v120
	v_add_f32_e32 v116, v116, v117
	v_sub_f32_e32 v108, v108, v109
	v_sub_f32_e32 v109, v110, v111
	v_cndmask_b32_e32 v164, v163, v164, vcc
	v_add_f32_e32 v116, v120, v116
	v_add_f32_e32 v108, v108, v109
	v_lshlrev_b32_e32 v164, 2, v164
	v_add_f32_e32 v109, v116, v108
	ds_bpermute_b32 v110, v164, v109
	v_xor_b32_e32 v108, 32, v163
	v_cmp_lt_i32_e32 vcc, v108, v165
	s_add_u32 s8, s8, s53
	s_addc_u32 s9, s9, 0
	v_cndmask_b32_e32 v108, v163, v108, vcc
	v_lshlrev_b32_e32 v108, 2, v108
	s_waitcnt lgkmcnt(0)
	v_add_f32_e32 v109, v109, v110
	ds_bpermute_b32 v110, v108, v109
	s_and_saveexec_b64 s[42:43], s[0:1]
	s_cbranch_execz .LBB0_193
	s_waitcnt lgkmcnt(0)
	v_add_f32_e32 v109, v109, v110
	v_lshl_add_u64 v[110:111], s[8:9], 0, v[140:141]
	global_store_dword v[110:111], v109, off

; #define PG8_STAGE(bufoff, gbase, voff) do { _Pragma("unroll") for (int _i = 0; _i < 2; ++_i) \
;         __builtin_amdgcn_global_load_lds((const unsigned*)((const char*)(gbase) + (voff)[_i]), (LAS unsigned*)(lds + (bufoff) + ldsw + _i * 8192), 16, 0, 0); } while (0)
; #define PG8_LDA(dst, b, h) do { _Pragma("unroll") for (int m = 0; m < 4; ++m) _Pragma("unroll") for (int k = 0; k < 2; ++k) dst[m][k] = *(const LAS bf16x8*)(lds + PG8_SA(b, h) + aoff + m * 2048 + k * 1024); } while (0)
; #define PG8_LDB(dst, b, h) do { _Pragma("unroll") for (int n = 0; n < 2; ++n) _Pragma("unroll") for (int k = 0; k < 2; ++k) dst[n][k] = *(const LAS bf16x8*)(lds + PG8_SB(b, h) + boff + n * 2048 + k * 1024); } while (0)
; #define PG8_MMA(ai, bj, At, Bt) do { __builtin_amdgcn_s_setprio(1); _Pragma("unroll") for (int m = 0; m < 4; ++m) _Pragma("unroll") for (int n = 0; n < 2; ++n) _Pragma("unroll") for (int k = 0; k < 2; ++k) \
;         acc[ai][bj][m][n] = __builtin_amdgcn_mfma_f32_16x16x32_bf16(Bt[n][k], At[m][k], acc[ai][bj][m][n], 0, 0, 0); __builtin_amdgcn_s_setprio(0); } while (0)
; #define PG8_WAIT_V(n) asm volatile("s_waitcnt vmcnt(" #n ")" ::: "memory")
; #define PG8_WAIT_L(n) asm volatile("s_waitcnt lgkmcnt(" #n ")" ::: "memory")
; #define PG8_BAR __builtin_amdgcn_s_barrier()
; #define PG8_SCHED __builtin_amdgcn_sched_barrier(0)
; template <class Epi, class Sched>
; __device__ __forceinline__ void gemm_phase(LAS unsigned char* lds, const int K, const Sched& S, const Epi& E) {
;     ...
;             PG8_LDB(B0, 0, 0); PG8_SCHED; PG8_LDA(At, 0, 0); PG8_STAGE(PG8_SA(1, 1), a1 + hstepA, voffA);
;             PG8_WAIT_L(8); PG8_BAR; PG8_WAIT_L(0); PG8_MMA(0, 0, At, B0); PG8_BAR; PG8_SCHED;
;             PG8_LDB(B1, 0, 1); PG8_STAGE(PG8_SB(0, 0), b2, voffB);
;             PG8_BAR; PG8_WAIT_L(0); PG8_MMA(0, 1, At, B1); PG8_BAR;
;             PG8_LDA(At, 0, 1); PG8_STAGE(PG8_SA(0, 0), a2, voffA);
;             PG8_BAR; PG8_WAIT_L(0); PG8_MMA(1, 0, At, B0); PG8_BAR; PG8_SCHED;
;             PG8_STAGE(PG8_SB(0, 1), b2 + hstep, voffB);
;             PG8_WAIT_V(6); PG8_BAR; PG8_MMA(1, 1, At, B1); PG8_BAR;
.Lpeel_p3:
	ds_read_b128 v[156:159], v153
	ds_read_b128 v[160:163], v153 offset:1024
	ds_read_b128 v[164:167], v153 offset:2048
	ds_read_b128 v[174:177], v153 offset:3072
	s_add_u32 s66, s64, 0xfffc0080
	s_addc_u32 s67, s65, -1
	s_cmp_eq_u32 s83, 12
	s_cselect_b32 s69, s45, s67
	s_cselect_b32 s68, s44, s66
	s_cselect_b32 s67, s47, s82
	s_cselect_b32 s66, s46, s41
	v_lshl_add_u64 v[150:151], s[64:65], 0, v[144:145]
	s_add_i32 m0, s54, 0xc000
	ds_read_b128 v[178:181], v154
	ds_read_b128 v[182:185], v154 offset:1024
	ds_read_b128 v[186:189], v154 offset:2048
	ds_read_b128 v[190:193], v154 offset:3072
	ds_read_b128 v[194:197], v154 offset:4096
	ds_read_b128 v[198:201], v154 offset:5120
	ds_read_b128 v[202:205], v154 offset:6144
	ds_read_b128 v[206:209], v154 offset:7168
	global_load_lds_dwordx4 v[150:151], off
	v_lshl_add_u64 v[150:151], s[64:65], 0, v[146:147]
	s_add_i32 m0, s54, 0xe000
	s_nop 0
	global_load_lds_dwordx4 v[150:151], off
	s_waitcnt lgkmcnt(8)
	s_barrier
	s_waitcnt lgkmcnt(0)
	s_setprio 1
	v_mfma_f32_16x16x32_bf16 v[124:127], v[156:159], v[178:181], 0
	v_mfma_f32_16x16x32_bf16 v[120:123], v[164:167], v[178:181], 0
	v_mfma_f32_16x16x32_bf16 v[116:119], v[156:159], v[186:189], 0
	v_mfma_f32_16x16x32_bf16 v[108:111], v[164:167], v[186:189], 0
	v_mfma_f32_16x16x32_bf16 v[100:103], v[156:159], v[194:197], 0
	v_mfma_f32_16x16x32_bf16 v[92:95], v[164:167], v[194:197], 0
	v_mfma_f32_16x16x32_bf16 v[84:87], v[156:159], v[202:205], 0
	v_mfma_f32_16x16x32_bf16 v[76:79], v[164:167], v[202:205], 0
	v_mfma_f32_16x16x32_bf16 v[124:127], v[160:163], v[182:185], v[124:127]
	v_mfma_f32_16x16x32_bf16 v[120:123], v[174:177], v[182:185], v[120:123]
	v_mfma_f32_16x16x32_bf16 v[116:119], v[160:163], v[190:193], v[116:119]
	v_mfma_f32_16x16x32_bf16 v[108:111], v[174:177], v[190:193], v[108:111]
	v_mfma_f32_16x16x32_bf16 v[100:103], v[160:163], v[198:201], v[100:103]
	v_mfma_f32_16x16x32_bf16 v[92:95], v[174:177], v[198:201], v[92:95]
	v_mfma_f32_16x16x32_bf16 v[84:87], v[160:163], v[206:209], v[84:87]
	v_mfma_f32_16x16x32_bf16 v[76:79], v[174:177], v[206:209], v[76:79]
	s_setprio 0
	s_barrier
	s_add_i32 s84, s72, s53
	v_lshl_add_u64 v[150:151], s[66:67], 0, v[136:137]
	s_mov_b32 m0, s84
	ds_read_b128 v[210:213], v155
	ds_read_b128 v[214:217], v155 offset:1024
	ds_read_b128 v[218:221], v155 offset:2048
	ds_read_b128 v[222:225], v155 offset:3072
	global_load_lds_dwordx4 v[150:151], off
	v_lshl_add_u64 v[168:169], s[66:67], 0, v[140:141]
	s_add_i32 m0, s84, 0x2000
	s_nop 0
	global_load_lds_dwordx4 v[168:169], off
	s_barrier
	s_waitcnt lgkmcnt(0)
	s_setprio 1
	v_mfma_f32_16x16x32_bf16 v[112:115], v[210:213], v[178:181], 0
	v_mfma_f32_16x16x32_bf16 v[104:107], v[218:221], v[178:181], 0
	v_mfma_f32_16x16x32_bf16 v[96:99], v[210:213], v[186:189], 0
	v_mfma_f32_16x16x32_bf16 v[88:91], v[218:221], v[186:189], 0
	v_mfma_f32_16x16x32_bf16 v[80:83], v[210:213], v[194:197], 0
	v_mfma_f32_16x16x32_bf16 v[72:75], v[218:221], v[194:197], 0
	v_mfma_f32_16x16x32_bf16 v[68:71], v[210:213], v[202:205], 0
	v_mfma_f32_16x16x32_bf16 v[64:67], v[218:221], v[202:205], 0
	v_mfma_f32_16x16x32_bf16 v[112:115], v[214:217], v[182:185], v[112:115]
	v_mfma_f32_16x16x32_bf16 v[104:107], v[222:225], v[182:185], v[104:107]
	v_mfma_f32_16x16x32_bf16 v[96:99], v[214:217], v[190:193], v[96:99]
	v_mfma_f32_16x16x32_bf16 v[88:91], v[222:225], v[190:193], v[88:91]
	v_mfma_f32_16x16x32_bf16 v[80:83], v[214:217], v[198:201], v[80:83]
	v_mfma_f32_16x16x32_bf16 v[72:75], v[222:225], v[198:201], v[72:75]
	v_mfma_f32_16x16x32_bf16 v[68:71], v[214:217], v[206:209], v[68:71]
	v_mfma_f32_16x16x32_bf16 v[64:67], v[222:225], v[206:209], v[64:67]
	s_setprio 0
	s_mov_b32 m0, s54
	v_lshl_add_u64 v[226:227], s[68:69], 0, v[134:135]
	s_barrier
	ds_read_b128 v[178:181], v154 offset:16384
	ds_read_b128 v[182:185], v154 offset:17408
	ds_read_b128 v[186:189], v154 offset:18432
	ds_read_b128 v[190:193], v154 offset:19456
	ds_read_b128 v[194:197], v154 offset:20480
	ds_read_b128 v[198:201], v154 offset:21504
	ds_read_b128 v[202:205], v154 offset:22528
	ds_read_b128 v[206:209], v154 offset:23552
	global_load_lds_dwordx4 v[226:227], off
	v_lshl_add_u64 v[228:229], s[68:69], 0, v[138:139]
	s_mov_b32 m0, s55
	s_nop 0
	global_load_lds_dwordx4 v[228:229], off
	s_barrier
	s_waitcnt lgkmcnt(0)
	s_setprio 1
	v_mfma_f32_16x16x32_bf16 v[60:63], v[156:159], v[178:181], 0
	v_mfma_f32_16x16x32_bf16 v[56:59], v[164:167], v[178:181], 0
	v_mfma_f32_16x16x32_bf16 v[52:55], v[156:159], v[186:189], 0
	v_mfma_f32_16x16x32_bf16 v[44:47], v[164:167], v[186:189], 0
	v_mfma_f32_16x16x32_bf16 v[36:39], v[156:159], v[194:197], 0
	v_mfma_f32_16x16x32_bf16 v[28:31], v[164:167], v[194:197], 0
	v_mfma_f32_16x16x32_bf16 v[20:23], v[156:159], v[202:205], 0
	v_mfma_f32_16x16x32_bf16 v[12:15], v[164:167], v[202:205], 0
	v_mfma_f32_16x16x32_bf16 v[60:63], v[160:163], v[182:185], v[60:63]
	v_mfma_f32_16x16x32_bf16 v[56:59], v[174:177], v[182:185], v[56:59]
	v_mfma_f32_16x16x32_bf16 v[52:55], v[160:163], v[190:193], v[52:55]
	v_mfma_f32_16x16x32_bf16 v[44:47], v[174:177], v[190:193], v[44:47]
	v_mfma_f32_16x16x32_bf16 v[36:39], v[160:163], v[198:201], v[36:39]
	v_mfma_f32_16x16x32_bf16 v[28:31], v[174:177], v[198:201], v[28:31]
	v_mfma_f32_16x16x32_bf16 v[20:23], v[160:163], v[206:209], v[20:23]
	v_mfma_f32_16x16x32_bf16 v[12:15], v[174:177], v[206:209], v[12:15]
	s_setprio 0
	s_barrier
	s_add_u32 s84, s66, 0x40000
	s_addc_u32 s85, s67, 0
	s_add_i32 s86, s73, s53
	v_lshl_add_u64 v[156:157], s[84:85], 0, v[136:137]
	s_mov_b32 m0, s86
	s_nop 0
	global_load_lds_dwordx4 v[156:157], off
	v_lshl_add_u64 v[156:157], s[84:85], 0, v[140:141]
	s_add_i32 m0, s86, 0x2000
	s_nop 0
	global_load_lds_dwordx4 v[156:157], off
	s_waitcnt vmcnt(6)
	s_barrier
; #define PG8_STAGE(bufoff, gbase, voff) do { _Pragma("unroll") for (int _i = 0; _i < 2; ++_i) \
;         __builtin_amdgcn_global_load_lds((const unsigned*)((const char*)(gbase) + (voff)[_i]), (LAS unsigned*)(lds + (bufoff) + ldsw + _i * 8192), 16, 0, 0); } while (0)
; #define PG8_LDA(dst, b, h) do { _Pragma("unroll") for (int m = 0; m < 4; ++m) _Pragma("unroll") for (int k = 0; k < 2; ++k) dst[m][k] = *(const LAS bf16x8*)(lds + PG8_SA(b, h) + aoff + m * 2048 + k * 1024); } while (0)
; #define PG8_LDB(dst, b, h) do { _Pragma("unroll") for (int n = 0; n < 2; ++n) _Pragma("unroll") for (int k = 0; k < 2; ++k) dst[n][k] = *(const LAS bf16x8*)(lds + PG8_SB(b, h) + boff + n * 2048 + k * 1024); } while (0)
; #define PG8_MMA(ai, bj, At, Bt) do { __builtin_amdgcn_s_setprio(1); _Pragma("unroll") for (int m = 0; m < 4; ++m) _Pragma("unroll") for (int n = 0; n < 2; ++n) _Pragma("unroll") for (int k = 0; k < 2; ++k) \
;         acc[ai][bj][m][n] = __builtin_amdgcn_mfma_f32_16x16x32_bf16(Bt[n][k], At[m][k], acc[ai][bj][m][n], 0, 0, 0); __builtin_amdgcn_s_setprio(0); } while (0)
; #define PG8_WAIT_V(n) asm volatile("s_waitcnt vmcnt(" #n ")" ::: "memory")
; #define PG8_WAIT_L(n) asm volatile("s_waitcnt lgkmcnt(" #n ")" ::: "memory")
; #define PG8_BAR __builtin_amdgcn_s_barrier()
; #define PG8_SCHED __builtin_amdgcn_sched_barrier(0)
; template <class Epi, class Sched>
; __device__ __forceinline__ void gemm_phase(LAS unsigned char* lds, const int K, const Sched& S, const Epi& E) {
;     ...
;             PG8_WAIT_V(6); PG8_BAR; PG8_MMA(1, 1, At, B1); PG8_BAR;
;             PG8_LDB(B0, 1, 0); PG8_SCHED; PG8_LDA(At, 1, 0); PG8_STAGE(PG8_SA(0, 1), a2 + hstepA, voffA);
;             PG8_WAIT_L(8); PG8_BAR; PG8_WAIT_L(0); PG8_MMA(0, 0, At, B0); PG8_BAR; PG8_SCHED;
;             PG8_LDB(B1, 1, 1); PG8_STAGE(PG8_SB(1, 0), b3, voffB);
;             PG8_BAR; PG8_WAIT_L(0); PG8_MMA(0, 1, At, B1); PG8_BAR;
;             PG8_LDA(At, 1, 1); PG8_STAGE(PG8_SA(1, 0), a3, voffA);
;             PG8_BAR; PG8_WAIT_L(0); PG8_MMA(1, 0, At, B0); PG8_BAR; PG8_SCHED;
	s_setprio 1
	v_mfma_f32_16x16x32_bf16 v[48:51], v[210:213], v[178:181], 0
	v_mfma_f32_16x16x32_bf16 v[40:43], v[218:221], v[178:181], 0
	v_mfma_f32_16x16x32_bf16 v[32:35], v[210:213], v[186:189], 0
	v_mfma_f32_16x16x32_bf16 v[24:27], v[218:221], v[186:189], 0
	v_mfma_f32_16x16x32_bf16 v[16:19], v[210:213], v[194:197], 0
	v_mfma_f32_16x16x32_bf16 v[8:11], v[218:221], v[194:197], 0
	v_mfma_f32_16x16x32_bf16 v[4:7], v[210:213], v[202:205], 0
	v_mfma_f32_16x16x32_bf16 v[0:3], v[218:221], v[202:205], 0
	v_mfma_f32_16x16x32_bf16 v[48:51], v[214:217], v[182:185], v[48:51]
	v_mfma_f32_16x16x32_bf16 v[40:43], v[222:225], v[182:185], v[40:43]
	v_mfma_f32_16x16x32_bf16 v[32:35], v[214:217], v[190:193], v[32:35]
	v_mfma_f32_16x16x32_bf16 v[24:27], v[222:225], v[190:193], v[24:27]
	v_mfma_f32_16x16x32_bf16 v[16:19], v[214:217], v[198:201], v[16:19]
	v_mfma_f32_16x16x32_bf16 v[8:11], v[222:225], v[198:201], v[8:11]
	v_mfma_f32_16x16x32_bf16 v[4:7], v[214:217], v[206:209], v[4:7]
	v_mfma_f32_16x16x32_bf16 v[0:3], v[222:225], v[206:209], v[0:3]
	s_setprio 0
	s_add_i32 s84, 0, 0x18000
	v_add_u32_e32 v149, s84, v152
	s_barrier
	ds_read_b128 v[156:159], v149
	ds_read_b128 v[160:163], v149 offset:1024
	ds_read_b128 v[164:167], v149 offset:2048
	ds_read_b128 v[174:177], v149 offset:3072
	s_add_u32 s68, s68, 0x40000
	s_addc_u32 s69, s69, 0
	s_mov_b32 m0, s56
	v_lshl_add_u64 v[210:211], s[68:69], 0, v[134:135]
	ds_read_b128 v[178:181], v154 offset:32768
	ds_read_b128 v[182:185], v154 offset:33792
	ds_read_b128 v[186:189], v154 offset:34816
	ds_read_b128 v[190:193], v154 offset:35840
	ds_read_b128 v[194:197], v154 offset:36864
	ds_read_b128 v[198:201], v154 offset:37888
	ds_read_b128 v[202:205], v154 offset:38912
	ds_read_b128 v[206:209], v154 offset:39936
	global_load_lds_dwordx4 v[210:211], off
	v_lshl_add_u64 v[210:211], s[68:69], 0, v[138:139]
	s_mov_b32 m0, s57
	s_nop 0
	global_load_lds_dwordx4 v[210:211], off
	s_waitcnt lgkmcnt(8)
	s_barrier
	s_waitcnt lgkmcnt(0)
	s_setprio 1
	v_mfma_f32_16x16x32_bf16 v[124:127], v[156:159], v[178:181], v[124:127]
	v_mfma_f32_16x16x32_bf16 v[120:123], v[164:167], v[178:181], v[120:123]
	v_mfma_f32_16x16x32_bf16 v[116:119], v[156:159], v[186:189], v[116:119]
	v_mfma_f32_16x16x32_bf16 v[108:111], v[164:167], v[186:189], v[108:111]
	v_mfma_f32_16x16x32_bf16 v[100:103], v[156:159], v[194:197], v[100:103]
	v_mfma_f32_16x16x32_bf16 v[92:95], v[164:167], v[194:197], v[92:95]
	v_mfma_f32_16x16x32_bf16 v[84:87], v[156:159], v[202:205], v[84:87]
	v_mfma_f32_16x16x32_bf16 v[76:79], v[164:167], v[202:205], v[76:79]
	v_mfma_f32_16x16x32_bf16 v[124:127], v[160:163], v[182:185], v[124:127]
	v_mfma_f32_16x16x32_bf16 v[120:123], v[174:177], v[182:185], v[120:123]
	v_mfma_f32_16x16x32_bf16 v[116:119], v[160:163], v[190:193], v[116:119]
	v_mfma_f32_16x16x32_bf16 v[108:111], v[174:177], v[190:193], v[108:111]
	v_mfma_f32_16x16x32_bf16 v[100:103], v[160:163], v[198:201], v[100:103]
	v_mfma_f32_16x16x32_bf16 v[92:95], v[174:177], v[198:201], v[92:95]
	v_mfma_f32_16x16x32_bf16 v[84:87], v[160:163], v[206:209], v[84:87]
	v_mfma_f32_16x16x32_bf16 v[76:79], v[174:177], v[206:209], v[76:79]
	s_setprio 0
	s_barrier
	s_add_i32 s68, 0, 0x1c000
	s_add_i32 s69, s84, s53
	v_add_u32_e32 v149, s68, v152
	v_lshl_add_u64 v[150:151], v[150:151], 0, s[6:7]
	s_mov_b32 m0, s69
	ds_read_b128 v[210:213], v149
	ds_read_b128 v[214:217], v149 offset:1024
	ds_read_b128 v[218:221], v149 offset:2048
	ds_read_b128 v[222:225], v149 offset:3072
	global_load_lds_dwordx4 v[150:151], off
	v_lshl_add_u64 v[150:151], v[168:169], 0, s[6:7]
	s_add_i32 m0, s69, 0x2000
	s_nop 0
	global_load_lds_dwordx4 v[150:151], off
	s_barrier
	s_waitcnt lgkmcnt(0)
	s_setprio 1
	v_mfma_f32_16x16x32_bf16 v[112:115], v[210:213], v[178:181], v[112:115]
	v_mfma_f32_16x16x32_bf16 v[104:107], v[218:221], v[178:181], v[104:107]
	v_mfma_f32_16x16x32_bf16 v[96:99], v[210:213], v[186:189], v[96:99]
	v_mfma_f32_16x16x32_bf16 v[88:91], v[218:221], v[186:189], v[88:91]
	v_mfma_f32_16x16x32_bf16 v[80:83], v[210:213], v[194:197], v[80:83]
	v_mfma_f32_16x16x32_bf16 v[72:75], v[218:221], v[194:197], v[72:75]
	v_mfma_f32_16x16x32_bf16 v[68:71], v[210:213], v[202:205], v[68:71]
	v_mfma_f32_16x16x32_bf16 v[64:67], v[218:221], v[202:205], v[64:67]
	v_mfma_f32_16x16x32_bf16 v[112:115], v[214:217], v[182:185], v[112:115]
	v_mfma_f32_16x16x32_bf16 v[104:107], v[222:225], v[182:185], v[104:107]
	v_mfma_f32_16x16x32_bf16 v[96:99], v[214:217], v[190:193], v[96:99]
	v_mfma_f32_16x16x32_bf16 v[88:91], v[222:225], v[190:193], v[88:91]
	v_mfma_f32_16x16x32_bf16 v[80:83], v[214:217], v[198:201], v[80:83]
	v_mfma_f32_16x16x32_bf16 v[72:75], v[222:225], v[198:201], v[72:75]
	v_mfma_f32_16x16x32_bf16 v[68:71], v[214:217], v[206:209], v[68:71]
	v_mfma_f32_16x16x32_bf16 v[64:67], v[222:225], v[206:209], v[64:67]
	s_setprio 0
	s_mov_b32 m0, s70
	v_lshl_add_u64 v[150:151], v[226:227], 0, s[6:7]
	s_barrier
	ds_read_b128 v[178:181], v154 offset:49152
	ds_read_b128 v[182:185], v154 offset:50176
	ds_read_b128 v[186:189], v154 offset:51200
	ds_read_b128 v[190:193], v154 offset:52224
	ds_read_b128 v[194:197], v154 offset:53248
	ds_read_b128 v[198:201], v154 offset:54272
	ds_read_b128 v[202:205], v154 offset:55296
	ds_read_b128 v[206:209], v154 offset:56320
	global_load_lds_dwordx4 v[150:151], off
	v_lshl_add_u64 v[150:151], v[228:229], 0, s[6:7]
	s_mov_b32 m0, s71
	s_nop 0
	global_load_lds_dwordx4 v[150:151], off
	s_barrier
; #define PG8_STAGE(bufoff, gbase, voff) do { _Pragma("unroll") for (int _i = 0; _i < 2; ++_i) \
;         __builtin_amdgcn_global_load_lds((const unsigned*)((const char*)(gbase) + (voff)[_i]), (LAS unsigned*)(lds + (bufoff) + ldsw + _i * 8192), 16, 0, 0); } while (0)
; #define PG8_LDA(dst, b, h) do { _Pragma("unroll") for (int m = 0; m < 4; ++m) _Pragma("unroll") for (int k = 0; k < 2; ++k) dst[m][k] = *(const LAS bf16x8*)(lds + PG8_SA(b, h) + aoff + m * 2048 + k * 1024); } while (0)
; #define PG8_LDB(dst, b, h) do { _Pragma("unroll") for (int n = 0; n < 2; ++n) _Pragma("unroll") for (int k = 0; k < 2; ++k) dst[n][k] = *(const LAS bf16x8*)(lds + PG8_SB(b, h) + boff + n * 2048 + k * 1024); } while (0)
; #define PG8_MMA(ai, bj, At, Bt) do { __builtin_amdgcn_s_setprio(1); _Pragma("unroll") for (int m = 0; m < 4; ++m) _Pragma("unroll") for (int n = 0; n < 2; ++n) _Pragma("unroll") for (int k = 0; k < 2; ++k) \
;         acc[ai][bj][m][n] = __builtin_amdgcn_mfma_f32_16x16x32_bf16(Bt[n][k], At[m][k], acc[ai][bj][m][n], 0, 0, 0); __builtin_amdgcn_s_setprio(0); } while (0)
; #define PG8_WAIT_V(n) asm volatile("s_waitcnt vmcnt(" #n ")" ::: "memory")
; #define PG8_WAIT_L(n) asm volatile("s_waitcnt lgkmcnt(" #n ")" ::: "memory")
; #define PG8_BAR __builtin_amdgcn_s_barrier()
; #define PG8_SCHED __builtin_amdgcn_sched_barrier(0)
; template <class Epi, class Sched>
; __device__ __forceinline__ void gemm_phase(LAS unsigned char* lds, const int K, const Sched& S, const Epi& E) {
;     ...
;             PG8_LDB(B0, 0, 0); PG8_SCHED; PG8_LDA(At, 0, 0); PG8_STAGE(PG8_SA(1, 1), a1 + hstepA, voffA);
;             PG8_WAIT_L(8); PG8_BAR; PG8_WAIT_L(0); PG8_MMA(0, 0, At, B0); PG8_BAR; PG8_SCHED;
;             PG8_LDB(B1, 0, 1); PG8_STAGE(PG8_SB(0, 0), b2, voffB);
;     ...
;             PG8_BAR; PG8_WAIT_L(0); PG8_MMA(0, 1, At, B1); PG8_BAR;
;             PG8_LDA(At, 1, 1); PG8_STAGE(PG8_SA(1, 0), a3, voffA);
;             PG8_BAR; PG8_WAIT_L(0); PG8_MMA(1, 0, At, B0); PG8_BAR; PG8_SCHED;
;             PG8_STAGE(PG8_SB(1, 1), b3 + hstep, voffB);
;             PG8_WAIT_V(6); PG8_BAR; PG8_MMA(1, 1, At, B1); PG8_BAR;
	s_waitcnt lgkmcnt(0)
	s_setprio 1
	v_mfma_f32_16x16x32_bf16 v[60:63], v[156:159], v[178:181], v[60:63]
	v_mfma_f32_16x16x32_bf16 v[56:59], v[164:167], v[178:181], v[56:59]
	v_mfma_f32_16x16x32_bf16 v[52:55], v[156:159], v[186:189], v[52:55]
	v_mfma_f32_16x16x32_bf16 v[44:47], v[164:167], v[186:189], v[44:47]
	v_mfma_f32_16x16x32_bf16 v[36:39], v[156:159], v[194:197], v[36:39]
	v_mfma_f32_16x16x32_bf16 v[28:31], v[164:167], v[194:197], v[28:31]
	v_mfma_f32_16x16x32_bf16 v[20:23], v[156:159], v[202:205], v[20:23]
	v_mfma_f32_16x16x32_bf16 v[12:15], v[164:167], v[202:205], v[12:15]
	v_mfma_f32_16x16x32_bf16 v[60:63], v[160:163], v[182:185], v[60:63]
	v_mfma_f32_16x16x32_bf16 v[56:59], v[174:177], v[182:185], v[56:59]
	v_mfma_f32_16x16x32_bf16 v[52:55], v[160:163], v[190:193], v[52:55]
	v_mfma_f32_16x16x32_bf16 v[44:47], v[174:177], v[190:193], v[44:47]
	v_mfma_f32_16x16x32_bf16 v[36:39], v[160:163], v[198:201], v[36:39]
	v_mfma_f32_16x16x32_bf16 v[28:31], v[174:177], v[198:201], v[28:31]
	v_mfma_f32_16x16x32_bf16 v[20:23], v[160:163], v[206:209], v[20:23]
	v_mfma_f32_16x16x32_bf16 v[12:15], v[174:177], v[206:209], v[12:15]
	s_setprio 0
	s_barrier
	s_add_u32 s66, s66, 0x40080
	s_addc_u32 s67, s67, 0
	s_add_i32 s68, s68, s53
	v_lshl_add_u64 v[150:151], s[66:67], 0, v[136:137]
	s_mov_b32 m0, s68
	s_nop 0
	global_load_lds_dwordx4 v[150:151], off
	v_lshl_add_u64 v[150:151], s[66:67], 0, v[140:141]
	s_add_i32 m0, s68, 0x2000
	s_nop 0
	global_load_lds_dwordx4 v[150:151], off
	s_waitcnt vmcnt(6)
	s_barrier
	s_setprio 1
	v_mfma_f32_16x16x32_bf16 v[48:51], v[210:213], v[178:181], v[48:51]
	v_mfma_f32_16x16x32_bf16 v[40:43], v[218:221], v[178:181], v[40:43]
	v_mfma_f32_16x16x32_bf16 v[32:35], v[210:213], v[186:189], v[32:35]
	v_mfma_f32_16x16x32_bf16 v[24:27], v[218:221], v[186:189], v[24:27]
	v_mfma_f32_16x16x32_bf16 v[16:19], v[210:213], v[194:197], v[16:19]
	v_mfma_f32_16x16x32_bf16 v[8:11], v[218:221], v[194:197], v[8:11]
	v_mfma_f32_16x16x32_bf16 v[4:7], v[210:213], v[202:205], v[4:7]
	v_mfma_f32_16x16x32_bf16 v[0:3], v[218:221], v[202:205], v[0:3]
	v_mfma_f32_16x16x32_bf16 v[48:51], v[214:217], v[182:185], v[48:51]
	v_mfma_f32_16x16x32_bf16 v[40:43], v[222:225], v[182:185], v[40:43]
	v_mfma_f32_16x16x32_bf16 v[32:35], v[214:217], v[190:193], v[32:35]
	v_mfma_f32_16x16x32_bf16 v[24:27], v[222:225], v[190:193], v[24:27]
	v_mfma_f32_16x16x32_bf16 v[16:19], v[214:217], v[198:201], v[16:19]
	v_mfma_f32_16x16x32_bf16 v[8:11], v[222:225], v[198:201], v[8:11]
	v_mfma_f32_16x16x32_bf16 v[4:7], v[214:217], v[206:209], v[4:7]
	v_mfma_f32_16x16x32_bf16 v[0:3], v[222:225], v[206:209], v[0:3]
	s_setprio 0
	s_add_i32 s83, s83, 2
	s_add_u32 s64, s64, 0x100
	s_addc_u32 s65, s65, 0
	s_add_u32 s41, s41, 0x100
	s_addc_u32 s82, s82, 0
	s_cmp_gt_u32 s83, 13
	s_barrier
.LBB0_299:
	ds_read_b128 v[156:159], v153
	ds_read_b128 v[160:163], v153 offset:1024
	ds_read_b128 v[164:167], v153 offset:2048
	ds_read_b128 v[174:177], v153 offset:3072
	s_add_u32 s66, s64, 0xfffc0080
	s_addc_u32 s67, s65, -1
	s_cmp_eq_u32 s83, 12
	s_cselect_b32 s69, s45, s67
	s_cselect_b32 s68, s44, s66
	s_cselect_b32 s67, s47, s82
	s_cselect_b32 s66, s46, s41
	v_lshl_add_u64 v[150:151], s[64:65], 0, v[144:145]
	s_add_i32 m0, s54, 0xc000
	ds_read_b128 v[178:181], v154
	ds_read_b128 v[182:185], v154 offset:1024
	ds_read_b128 v[186:189], v154 offset:2048
	ds_read_b128 v[190:193], v154 offset:3072
	ds_read_b128 v[194:197], v154 offset:4096
	ds_read_b128 v[198:201], v154 offset:5120
	ds_read_b128 v[202:205], v154 offset:6144
	ds_read_b128 v[206:209], v154 offset:7168
	global_load_lds_dwordx4 v[150:151], off
	v_lshl_add_u64 v[150:151], s[64:65], 0, v[146:147]
	s_add_i32 m0, s54, 0xe000
	s_nop 0
	global_load_lds_dwordx4 v[150:151], off
	s_waitcnt lgkmcnt(8)
	s_barrier
	s_waitcnt lgkmcnt(0)
	s_setprio 1
	v_mfma_f32_16x16x32_bf16 v[124:127], v[156:159], v[178:181], v[124:127]
	v_mfma_f32_16x16x32_bf16 v[120:123], v[164:167], v[178:181], v[120:123]
	v_mfma_f32_16x16x32_bf16 v[116:119], v[156:159], v[186:189], v[116:119]
	v_mfma_f32_16x16x32_bf16 v[108:111], v[164:167], v[186:189], v[108:111]
	v_mfma_f32_16x16x32_bf16 v[100:103], v[156:159], v[194:197], v[100:103]
	v_mfma_f32_16x16x32_bf16 v[92:95], v[164:167], v[194:197], v[92:95]
	v_mfma_f32_16x16x32_bf16 v[84:87], v[156:159], v[202:205], v[84:87]
	v_mfma_f32_16x16x32_bf16 v[76:79], v[164:167], v[202:205], v[76:79]
	v_mfma_f32_16x16x32_bf16 v[124:127], v[160:163], v[182:185], v[124:127]
	v_mfma_f32_16x16x32_bf16 v[120:123], v[174:177], v[182:185], v[120:123]
	v_mfma_f32_16x16x32_bf16 v[116:119], v[160:163], v[190:193], v[116:119]
	v_mfma_f32_16x16x32_bf16 v[108:111], v[174:177], v[190:193], v[108:111]
	v_mfma_f32_16x16x32_bf16 v[100:103], v[160:163], v[198:201], v[100:103]
	v_mfma_f32_16x16x32_bf16 v[92:95], v[174:177], v[198:201], v[92:95]
	v_mfma_f32_16x16x32_bf16 v[84:87], v[160:163], v[206:209], v[84:87]
	v_mfma_f32_16x16x32_bf16 v[76:79], v[174:177], v[206:209], v[76:79]
	s_setprio 0
	s_barrier
	s_add_i32 s84, s72, s53
	v_lshl_add_u64 v[150:151], s[66:67], 0, v[136:137]
	s_mov_b32 m0, s84
	ds_read_b128 v[210:213], v155
	ds_read_b128 v[214:217], v155 offset:1024
	ds_read_b128 v[218:221], v155 offset:2048
	ds_read_b128 v[222:225], v155 offset:3072
	global_load_lds_dwordx4 v[150:151], off
	v_lshl_add_u64 v[168:169], s[66:67], 0, v[140:141]
	s_add_i32 m0, s84, 0x2000
	s_nop 0
	global_load_lds_dwordx4 v[168:169], off
	s_barrier
; #define PG8_STAGE(bufoff, gbase, voff) do { _Pragma("unroll") for (int _i = 0; _i < 2; ++_i) \
;         __builtin_amdgcn_global_load_lds((const unsigned*)((const char*)(gbase) + (voff)[_i]), (LAS unsigned*)(lds + (bufoff) + ldsw + _i * 8192), 16, 0, 0); } while (0)
; #define PG8_LDA(dst, b, h) do { _Pragma("unroll") for (int m = 0; m < 4; ++m) _Pragma("unroll") for (int k = 0; k < 2; ++k) dst[m][k] = *(const LAS bf16x8*)(lds + PG8_SA(b, h) + aoff + m * 2048 + k * 1024); } while (0)
; #define PG8_LDB(dst, b, h) do { _Pragma("unroll") for (int n = 0; n < 2; ++n) _Pragma("unroll") for (int k = 0; k < 2; ++k) dst[n][k] = *(const LAS bf16x8*)(lds + PG8_SB(b, h) + boff + n * 2048 + k * 1024); } while (0)
; #define PG8_MMA(ai, bj, At, Bt) do { __builtin_amdgcn_s_setprio(1); _Pragma("unroll") for (int m = 0; m < 4; ++m) _Pragma("unroll") for (int n = 0; n < 2; ++n) _Pragma("unroll") for (int k = 0; k < 2; ++k) \
;         acc[ai][bj][m][n] = __builtin_amdgcn_mfma_f32_16x16x32_bf16(Bt[n][k], At[m][k], acc[ai][bj][m][n], 0, 0, 0); __builtin_amdgcn_s_setprio(0); } while (0)
; #define PG8_WAIT_V(n) asm volatile("s_waitcnt vmcnt(" #n ")" ::: "memory")
; #define PG8_WAIT_L(n) asm volatile("s_waitcnt lgkmcnt(" #n ")" ::: "memory")
; #define PG8_BAR __builtin_amdgcn_s_barrier()
; #define PG8_SCHED __builtin_amdgcn_sched_barrier(0)
; template <class Epi, class Sched>
; __device__ __forceinline__ void gemm_phase(LAS unsigned char* lds, const int K, const Sched& S, const Epi& E) {
;     ...
;             PG8_BAR; PG8_WAIT_L(0); PG8_MMA(0, 1, At, B1); PG8_BAR;
;             PG8_LDA(At, 0, 1); PG8_STAGE(PG8_SA(0, 0), a2, voffA);
;             PG8_BAR; PG8_WAIT_L(0); PG8_MMA(1, 0, At, B0); PG8_BAR; PG8_SCHED;
;             PG8_STAGE(PG8_SB(0, 1), b2 + hstep, voffB);
;             PG8_WAIT_V(6); PG8_BAR; PG8_MMA(1, 1, At, B1); PG8_BAR;
;             PG8_LDB(B0, 1, 0); PG8_SCHED; PG8_LDA(At, 1, 0); PG8_STAGE(PG8_SA(0, 1), a2 + hstepA, voffA);
;             PG8_WAIT_L(8); PG8_BAR; PG8_WAIT_L(0); PG8_MMA(0, 0, At, B0); PG8_BAR; PG8_SCHED;
	s_waitcnt lgkmcnt(0)
	s_setprio 1
	v_mfma_f32_16x16x32_bf16 v[112:115], v[210:213], v[178:181], v[112:115]
	v_mfma_f32_16x16x32_bf16 v[104:107], v[218:221], v[178:181], v[104:107]
	v_mfma_f32_16x16x32_bf16 v[96:99], v[210:213], v[186:189], v[96:99]
	v_mfma_f32_16x16x32_bf16 v[88:91], v[218:221], v[186:189], v[88:91]
	v_mfma_f32_16x16x32_bf16 v[80:83], v[210:213], v[194:197], v[80:83]
	v_mfma_f32_16x16x32_bf16 v[72:75], v[218:221], v[194:197], v[72:75]
	v_mfma_f32_16x16x32_bf16 v[68:71], v[210:213], v[202:205], v[68:71]
	v_mfma_f32_16x16x32_bf16 v[64:67], v[218:221], v[202:205], v[64:67]
	v_mfma_f32_16x16x32_bf16 v[112:115], v[214:217], v[182:185], v[112:115]
	v_mfma_f32_16x16x32_bf16 v[104:107], v[222:225], v[182:185], v[104:107]
	v_mfma_f32_16x16x32_bf16 v[96:99], v[214:217], v[190:193], v[96:99]
	v_mfma_f32_16x16x32_bf16 v[88:91], v[222:225], v[190:193], v[88:91]
	v_mfma_f32_16x16x32_bf16 v[80:83], v[214:217], v[198:201], v[80:83]
	v_mfma_f32_16x16x32_bf16 v[72:75], v[222:225], v[198:201], v[72:75]
	v_mfma_f32_16x16x32_bf16 v[68:71], v[214:217], v[206:209], v[68:71]
	v_mfma_f32_16x16x32_bf16 v[64:67], v[222:225], v[206:209], v[64:67]
	s_setprio 0
	s_mov_b32 m0, s54
	v_lshl_add_u64 v[226:227], s[68:69], 0, v[134:135]
	s_barrier
	ds_read_b128 v[178:181], v154 offset:16384
	ds_read_b128 v[182:185], v154 offset:17408
	ds_read_b128 v[186:189], v154 offset:18432
	ds_read_b128 v[190:193], v154 offset:19456
	ds_read_b128 v[194:197], v154 offset:20480
	ds_read_b128 v[198:201], v154 offset:21504
	ds_read_b128 v[202:205], v154 offset:22528
	ds_read_b128 v[206:209], v154 offset:23552
	global_load_lds_dwordx4 v[226:227], off
	v_lshl_add_u64 v[228:229], s[68:69], 0, v[138:139]
	s_mov_b32 m0, s55
	s_nop 0
	global_load_lds_dwordx4 v[228:229], off
	s_barrier
	s_waitcnt lgkmcnt(0)
	s_setprio 1
	v_mfma_f32_16x16x32_bf16 v[60:63], v[156:159], v[178:181], v[60:63]
	v_mfma_f32_16x16x32_bf16 v[56:59], v[164:167], v[178:181], v[56:59]
	v_mfma_f32_16x16x32_bf16 v[52:55], v[156:159], v[186:189], v[52:55]
	v_mfma_f32_16x16x32_bf16 v[44:47], v[164:167], v[186:189], v[44:47]
	v_mfma_f32_16x16x32_bf16 v[36:39], v[156:159], v[194:197], v[36:39]
	v_mfma_f32_16x16x32_bf16 v[28:31], v[164:167], v[194:197], v[28:31]
	v_mfma_f32_16x16x32_bf16 v[20:23], v[156:159], v[202:205], v[20:23]
	v_mfma_f32_16x16x32_bf16 v[12:15], v[164:167], v[202:205], v[12:15]
	v_mfma_f32_16x16x32_bf16 v[60:63], v[160:163], v[182:185], v[60:63]
	v_mfma_f32_16x16x32_bf16 v[56:59], v[174:177], v[182:185], v[56:59]
	v_mfma_f32_16x16x32_bf16 v[52:55], v[160:163], v[190:193], v[52:55]
	v_mfma_f32_16x16x32_bf16 v[44:47], v[174:177], v[190:193], v[44:47]
	v_mfma_f32_16x16x32_bf16 v[36:39], v[160:163], v[198:201], v[36:39]
	v_mfma_f32_16x16x32_bf16 v[28:31], v[174:177], v[198:201], v[28:31]
	v_mfma_f32_16x16x32_bf16 v[20:23], v[160:163], v[206:209], v[20:23]
	v_mfma_f32_16x16x32_bf16 v[12:15], v[174:177], v[206:209], v[12:15]
	s_setprio 0
	s_barrier
	s_add_u32 s84, s66, 0x40000
	s_addc_u32 s85, s67, 0
	s_add_i32 s86, s73, s53
	v_lshl_add_u64 v[156:157], s[84:85], 0, v[136:137]
	s_mov_b32 m0, s86
	s_nop 0
	global_load_lds_dwordx4 v[156:157], off
	v_lshl_add_u64 v[156:157], s[84:85], 0, v[140:141]
	s_add_i32 m0, s86, 0x2000
	s_nop 0
	global_load_lds_dwordx4 v[156:157], off
	s_waitcnt vmcnt(6)
	s_barrier
	s_setprio 1
	v_mfma_f32_16x16x32_bf16 v[48:51], v[210:213], v[178:181], v[48:51]
	v_mfma_f32_16x16x32_bf16 v[40:43], v[218:221], v[178:181], v[40:43]
	v_mfma_f32_16x16x32_bf16 v[32:35], v[210:213], v[186:189], v[32:35]
	v_mfma_f32_16x16x32_bf16 v[24:27], v[218:221], v[186:189], v[24:27]
	v_mfma_f32_16x16x32_bf16 v[16:19], v[210:213], v[194:197], v[16:19]
	v_mfma_f32_16x16x32_bf16 v[8:11], v[218:221], v[194:197], v[8:11]
	v_mfma_f32_16x16x32_bf16 v[4:7], v[210:213], v[202:205], v[4:7]
	v_mfma_f32_16x16x32_bf16 v[0:3], v[218:221], v[202:205], v[0:3]
	v_mfma_f32_16x16x32_bf16 v[48:51], v[214:217], v[182:185], v[48:51]
	v_mfma_f32_16x16x32_bf16 v[40:43], v[222:225], v[182:185], v[40:43]
	v_mfma_f32_16x16x32_bf16 v[32:35], v[214:217], v[190:193], v[32:35]
	v_mfma_f32_16x16x32_bf16 v[24:27], v[222:225], v[190:193], v[24:27]
	v_mfma_f32_16x16x32_bf16 v[16:19], v[214:217], v[198:201], v[16:19]
	v_mfma_f32_16x16x32_bf16 v[8:11], v[222:225], v[198:201], v[8:11]
	v_mfma_f32_16x16x32_bf16 v[4:7], v[214:217], v[206:209], v[4:7]
	v_mfma_f32_16x16x32_bf16 v[0:3], v[222:225], v[206:209], v[0:3]
	s_setprio 0
	s_add_i32 s84, 0, 0x18000
	v_add_u32_e32 v149, s84, v152
	s_barrier
	ds_read_b128 v[156:159], v149
	ds_read_b128 v[160:163], v149 offset:1024
	ds_read_b128 v[164:167], v149 offset:2048
	ds_read_b128 v[174:177], v149 offset:3072
	s_add_u32 s68, s68, 0x40000
	s_addc_u32 s69, s69, 0
	s_mov_b32 m0, s56
	v_lshl_add_u64 v[210:211], s[68:69], 0, v[134:135]
	ds_read_b128 v[178:181], v154 offset:32768
	ds_read_b128 v[182:185], v154 offset:33792
	ds_read_b128 v[186:189], v154 offset:34816
	ds_read_b128 v[190:193], v154 offset:35840
	ds_read_b128 v[194:197], v154 offset:36864
	ds_read_b128 v[198:201], v154 offset:37888
	ds_read_b128 v[202:205], v154 offset:38912
	ds_read_b128 v[206:209], v154 offset:39936
	global_load_lds_dwordx4 v[210:211], off
	v_lshl_add_u64 v[210:211], s[68:69], 0, v[138:139]
	s_mov_b32 m0, s57
	s_nop 0
	global_load_lds_dwordx4 v[210:211], off
	s_waitcnt lgkmcnt(8)
	s_barrier
; #define PG8_STAGE(bufoff, gbase, voff) do { _Pragma("unroll") for (int _i = 0; _i < 2; ++_i) \
;         __builtin_amdgcn_global_load_lds((const unsigned*)((const char*)(gbase) + (voff)[_i]), (LAS unsigned*)(lds + (bufoff) + ldsw + _i * 8192), 16, 0, 0); } while (0)
; #define PG8_LDA(dst, b, h) do { _Pragma("unroll") for (int m = 0; m < 4; ++m) _Pragma("unroll") for (int k = 0; k < 2; ++k) dst[m][k] = *(const LAS bf16x8*)(lds + PG8_SA(b, h) + aoff + m * 2048 + k * 1024); } while (0)
; #define PG8_LDB(dst, b, h) do { _Pragma("unroll") for (int n = 0; n < 2; ++n) _Pragma("unroll") for (int k = 0; k < 2; ++k) dst[n][k] = *(const LAS bf16x8*)(lds + PG8_SB(b, h) + boff + n * 2048 + k * 1024); } while (0)
; #define PG8_MMA(ai, bj, At, Bt) do { __builtin_amdgcn_s_setprio(1); _Pragma("unroll") for (int m = 0; m < 4; ++m) _Pragma("unroll") for (int n = 0; n < 2; ++n) _Pragma("unroll") for (int k = 0; k < 2; ++k) \
;         acc[ai][bj][m][n] = __builtin_amdgcn_mfma_f32_16x16x32_bf16(Bt[n][k], At[m][k], acc[ai][bj][m][n], 0, 0, 0); __builtin_amdgcn_s_setprio(0); } while (0)
; #define PG8_WAIT_V(n) asm volatile("s_waitcnt vmcnt(" #n ")" ::: "memory")
; #define PG8_WAIT_L(n) asm volatile("s_waitcnt lgkmcnt(" #n ")" ::: "memory")
; #define PG8_BAR __builtin_amdgcn_s_barrier()
; #define PG8_SCHED __builtin_amdgcn_sched_barrier(0)
; template <class Epi, class Sched>
; __device__ __forceinline__ void gemm_phase(LAS unsigned char* lds, const int K, const Sched& S, const Epi& E) {
;     ...
;             PG8_WAIT_L(8); PG8_BAR; PG8_WAIT_L(0); PG8_MMA(0, 0, At, B0); PG8_BAR; PG8_SCHED;
;             PG8_LDB(B1, 1, 1); PG8_STAGE(PG8_SB(1, 0), b3, voffB);
;             PG8_BAR; PG8_WAIT_L(0); PG8_MMA(0, 1, At, B1); PG8_BAR;
;             PG8_LDA(At, 1, 1); PG8_STAGE(PG8_SA(1, 0), a3, voffA);
;             PG8_BAR; PG8_WAIT_L(0); PG8_MMA(1, 0, At, B0); PG8_BAR; PG8_SCHED;
;             PG8_STAGE(PG8_SB(1, 1), b3 + hstep, voffB);
;             PG8_WAIT_V(6); PG8_BAR; PG8_MMA(1, 1, At, B1); PG8_BAR;
	s_waitcnt lgkmcnt(0)
	s_setprio 1
	v_mfma_f32_16x16x32_bf16 v[124:127], v[156:159], v[178:181], v[124:127]
	v_mfma_f32_16x16x32_bf16 v[120:123], v[164:167], v[178:181], v[120:123]
	v_mfma_f32_16x16x32_bf16 v[116:119], v[156:159], v[186:189], v[116:119]
	v_mfma_f32_16x16x32_bf16 v[108:111], v[164:167], v[186:189], v[108:111]
	v_mfma_f32_16x16x32_bf16 v[100:103], v[156:159], v[194:197], v[100:103]
	v_mfma_f32_16x16x32_bf16 v[92:95], v[164:167], v[194:197], v[92:95]
	v_mfma_f32_16x16x32_bf16 v[84:87], v[156:159], v[202:205], v[84:87]
	v_mfma_f32_16x16x32_bf16 v[76:79], v[164:167], v[202:205], v[76:79]
	v_mfma_f32_16x16x32_bf16 v[124:127], v[160:163], v[182:185], v[124:127]
	v_mfma_f32_16x16x32_bf16 v[120:123], v[174:177], v[182:185], v[120:123]
	v_mfma_f32_16x16x32_bf16 v[116:119], v[160:163], v[190:193], v[116:119]
	v_mfma_f32_16x16x32_bf16 v[108:111], v[174:177], v[190:193], v[108:111]
	v_mfma_f32_16x16x32_bf16 v[100:103], v[160:163], v[198:201], v[100:103]
	v_mfma_f32_16x16x32_bf16 v[92:95], v[174:177], v[198:201], v[92:95]
	v_mfma_f32_16x16x32_bf16 v[84:87], v[160:163], v[206:209], v[84:87]
	v_mfma_f32_16x16x32_bf16 v[76:79], v[174:177], v[206:209], v[76:79]
	s_setprio 0
	s_barrier
	s_add_i32 s68, 0, 0x1c000
	s_add_i32 s69, s84, s53
	v_add_u32_e32 v149, s68, v152
	v_lshl_add_u64 v[150:151], v[150:151], 0, s[6:7]
	s_mov_b32 m0, s69
	ds_read_b128 v[210:213], v149
	ds_read_b128 v[214:217], v149 offset:1024
	ds_read_b128 v[218:221], v149 offset:2048
	ds_read_b128 v[222:225], v149 offset:3072
	global_load_lds_dwordx4 v[150:151], off
	v_lshl_add_u64 v[150:151], v[168:169], 0, s[6:7]
	s_add_i32 m0, s69, 0x2000
	s_nop 0
	global_load_lds_dwordx4 v[150:151], off
	s_barrier
	s_waitcnt lgkmcnt(0)
	s_setprio 1
	v_mfma_f32_16x16x32_bf16 v[112:115], v[210:213], v[178:181], v[112:115]
	v_mfma_f32_16x16x32_bf16 v[104:107], v[218:221], v[178:181], v[104:107]
	v_mfma_f32_16x16x32_bf16 v[96:99], v[210:213], v[186:189], v[96:99]
	v_mfma_f32_16x16x32_bf16 v[88:91], v[218:221], v[186:189], v[88:91]
	v_mfma_f32_16x16x32_bf16 v[80:83], v[210:213], v[194:197], v[80:83]
	v_mfma_f32_16x16x32_bf16 v[72:75], v[218:221], v[194:197], v[72:75]
	v_mfma_f32_16x16x32_bf16 v[68:71], v[210:213], v[202:205], v[68:71]
	v_mfma_f32_16x16x32_bf16 v[64:67], v[218:221], v[202:205], v[64:67]
	v_mfma_f32_16x16x32_bf16 v[112:115], v[214:217], v[182:185], v[112:115]
	v_mfma_f32_16x16x32_bf16 v[104:107], v[222:225], v[182:185], v[104:107]
	v_mfma_f32_16x16x32_bf16 v[96:99], v[214:217], v[190:193], v[96:99]
	v_mfma_f32_16x16x32_bf16 v[88:91], v[222:225], v[190:193], v[88:91]
	v_mfma_f32_16x16x32_bf16 v[80:83], v[214:217], v[198:201], v[80:83]
	v_mfma_f32_16x16x32_bf16 v[72:75], v[222:225], v[198:201], v[72:75]
	v_mfma_f32_16x16x32_bf16 v[68:71], v[214:217], v[206:209], v[68:71]
	v_mfma_f32_16x16x32_bf16 v[64:67], v[222:225], v[206:209], v[64:67]
	s_setprio 0
	s_mov_b32 m0, s70
	v_lshl_add_u64 v[150:151], v[226:227], 0, s[6:7]
	s_barrier
	ds_read_b128 v[178:181], v154 offset:49152
	ds_read_b128 v[182:185], v154 offset:50176
	ds_read_b128 v[186:189], v154 offset:51200
	ds_read_b128 v[190:193], v154 offset:52224
	ds_read_b128 v[194:197], v154 offset:53248
	ds_read_b128 v[198:201], v154 offset:54272
	ds_read_b128 v[202:205], v154 offset:55296
	ds_read_b128 v[206:209], v154 offset:56320
	global_load_lds_dwordx4 v[150:151], off
	v_lshl_add_u64 v[150:151], v[228:229], 0, s[6:7]
	s_mov_b32 m0, s71
	s_nop 0
	global_load_lds_dwordx4 v[150:151], off
	s_barrier
	s_waitcnt lgkmcnt(0)
	s_setprio 1
	v_mfma_f32_16x16x32_bf16 v[60:63], v[156:159], v[178:181], v[60:63]
	v_mfma_f32_16x16x32_bf16 v[56:59], v[164:167], v[178:181], v[56:59]
	v_mfma_f32_16x16x32_bf16 v[52:55], v[156:159], v[186:189], v[52:55]
	v_mfma_f32_16x16x32_bf16 v[44:47], v[164:167], v[186:189], v[44:47]
	v_mfma_f32_16x16x32_bf16 v[36:39], v[156:159], v[194:197], v[36:39]
	v_mfma_f32_16x16x32_bf16 v[28:31], v[164:167], v[194:197], v[28:31]
	v_mfma_f32_16x16x32_bf16 v[20:23], v[156:159], v[202:205], v[20:23]
	v_mfma_f32_16x16x32_bf16 v[12:15], v[164:167], v[202:205], v[12:15]
	v_mfma_f32_16x16x32_bf16 v[60:63], v[160:163], v[182:185], v[60:63]
	v_mfma_f32_16x16x32_bf16 v[56:59], v[174:177], v[182:185], v[56:59]
	v_mfma_f32_16x16x32_bf16 v[52:55], v[160:163], v[190:193], v[52:55]
	v_mfma_f32_16x16x32_bf16 v[44:47], v[174:177], v[190:193], v[44:47]
	v_mfma_f32_16x16x32_bf16 v[36:39], v[160:163], v[198:201], v[36:39]
	v_mfma_f32_16x16x32_bf16 v[28:31], v[174:177], v[198:201], v[28:31]
	v_mfma_f32_16x16x32_bf16 v[20:23], v[160:163], v[206:209], v[20:23]
	v_mfma_f32_16x16x32_bf16 v[12:15], v[174:177], v[206:209], v[12:15]
	s_setprio 0
	s_barrier
	s_add_u32 s66, s66, 0x40080
	s_addc_u32 s67, s67, 0
	s_add_i32 s68, s68, s53
	v_lshl_add_u64 v[150:151], s[66:67], 0, v[136:137]
	s_mov_b32 m0, s68
	s_nop 0
	global_load_lds_dwordx4 v[150:151], off
	v_lshl_add_u64 v[150:151], s[66:67], 0, v[140:141]
	s_add_i32 m0, s68, 0x2000
	s_nop 0
	global_load_lds_dwordx4 v[150:151], off
	s_waitcnt vmcnt(6)
	s_barrier
; __device__ __forceinline__ unsigned cvt_pk_bf16(float lo, float hi) { unsigned r; asm volatile("v_cvt_pk_bf16_f32 %0, %1, %2" : "=v"(r) : "v"(lo), "v"(hi)); return r; }
; #define PG8_MMA(ai, bj, At, Bt) do { __builtin_amdgcn_s_setprio(1); _Pragma("unroll") for (int m = 0; m < 4; ++m) _Pragma("unroll") for (int n = 0; n < 2; ++n) _Pragma("unroll") for (int k = 0; k < 2; ++k) \
;         acc[ai][bj][m][n] = __builtin_amdgcn_mfma_f32_16x16x32_bf16(Bt[n][k], At[m][k], acc[ai][bj][m][n], 0, 0, 0); __builtin_amdgcn_s_setprio(0); } while (0)
; #define PG8_WAIT_V(n) asm volatile("s_waitcnt vmcnt(" #n ")" ::: "memory")
; #define PG8_BAR __builtin_amdgcn_s_barrier()
; template <class Epi, class Sched>
; __device__ __forceinline__ void gemm_phase(LAS unsigned char* lds, const int K, const Sched& S, const Epi& E) {
;     ...
;             PG8_WAIT_V(6); PG8_BAR; PG8_MMA(1, 1, At, B1); PG8_BAR;
;         }
;         if constexpr (!Epi::AFTER_DRAIN) E(acc, cur, wr, wc, fr, fq);
;         if (!has_next) break;
; #pragma unroll
;         for (int a = 0; a < 2; ++a)
; #pragma unroll
;             for (int b = 0; b < 2; ++b)
; #pragma unroll
;                 for (int m = 0; m < 4; ++m)
; #pragma unroll
;                     for (int n = 0; n < 2; ++n) acc[a][b][m][n] = (f32x4){0.f, 0.f, 0.f, 0.f};
;         cur = nxt; cA = nA; cB = nB; ++ui;
;     }
;     PG8_WAIT_V(0);
;     if (wr == 0) PG8_BAR;
;     __device__ __forceinline__ void operator()(const f32x4 (&acc)[2][2][4][2], const Unit& u, int wr, int wc, int fr, int fq) const {
;         bf16_t* base = (bf16_t*)u.po + (size_t)wr * u.RS + (size_t)fr * u.rp + (size_t)(wc >> 1) * u.CS + (wc & 1) * 32 + 8 * fq;
; #pragma unroll
;         for (int ai = 0; ai < 2; ++ai)
; #pragma unroll
;             for (int m = 0; m < 4; ++m) { bf16_t* rowp = base + (size_t)(2 * ai) * u.RS + (size_t)(m * 16) * u.rp;
; #pragma unroll
;                 for (int bj = 0; bj < 2; ++bj) { const f32x4 v0 = acc[ai][bj][m][0], v1 = acc[ai][bj][m][1];
;                     u32x4 w; w.x = cvt_pk_bf16(v0[0], v0[1]); w.y = cvt_pk_bf16(v0[2], v0[3]); w.z = cvt_pk_bf16(v1[0], v1[1]); w.w = cvt_pk_bf16(v1[2], v1[3]);
;                     *(u32x4*)(rowp + (size_t)(2 * bj) * u.CS) = w; } }
	s_setprio 1
	v_mfma_f32_16x16x32_bf16 v[48:51], v[210:213], v[178:181], v[48:51]
	v_mfma_f32_16x16x32_bf16 v[40:43], v[218:221], v[178:181], v[40:43]
	v_mfma_f32_16x16x32_bf16 v[32:35], v[210:213], v[186:189], v[32:35]
	v_mfma_f32_16x16x32_bf16 v[24:27], v[218:221], v[186:189], v[24:27]
	v_mfma_f32_16x16x32_bf16 v[16:19], v[210:213], v[194:197], v[16:19]
	v_mfma_f32_16x16x32_bf16 v[8:11], v[218:221], v[194:197], v[8:11]
	v_mfma_f32_16x16x32_bf16 v[4:7], v[210:213], v[202:205], v[4:7]
	v_mfma_f32_16x16x32_bf16 v[0:3], v[218:221], v[202:205], v[0:3]
	v_mfma_f32_16x16x32_bf16 v[48:51], v[214:217], v[182:185], v[48:51]
	v_mfma_f32_16x16x32_bf16 v[40:43], v[222:225], v[182:185], v[40:43]
	v_mfma_f32_16x16x32_bf16 v[32:35], v[214:217], v[190:193], v[32:35]
	v_mfma_f32_16x16x32_bf16 v[24:27], v[222:225], v[190:193], v[24:27]
	v_mfma_f32_16x16x32_bf16 v[16:19], v[214:217], v[198:201], v[16:19]
	v_mfma_f32_16x16x32_bf16 v[8:11], v[222:225], v[198:201], v[8:11]
	v_mfma_f32_16x16x32_bf16 v[4:7], v[214:217], v[206:209], v[4:7]
	v_mfma_f32_16x16x32_bf16 v[0:3], v[222:225], v[206:209], v[0:3]
	s_setprio 0
	s_add_i32 s83, s83, 2
	s_add_u32 s64, s64, 0x100
	s_addc_u32 s65, s65, 0
	s_add_u32 s41, s41, 0x100
	s_addc_u32 s82, s82, 0
	s_cmp_gt_u32 s83, 13
	s_barrier
	s_cbranch_scc0 .LBB0_299
	s_add_u32 s62, s62, s38
	s_addc_u32 s63, s63, s39
	v_lshl_add_u64 v[150:151], s[62:63], 0, v[142:143]
	v_lshl_add_u64 v[150:151], v[150:151], 0, s[0:1]
	s_mov_b32 s41, s1
	v_lshl_add_u64 v[150:151], v[150:151], 0, s[40:41]
	v_mov_b32_e32 v149, v143
	v_lshl_add_u64 v[150:151], v[150:151], 0, v[148:149]
	v_cvt_pk_bf16_f32 v124, v124, v125
	v_cvt_pk_bf16_f32 v125, v126, v127
	v_cvt_pk_bf16_f32 v126, v120, v121
	v_cvt_pk_bf16_f32 v127, v122, v123
	global_store_dwordx4 v[150:151], v[124:127], off sc1
	v_cvt_pk_bf16_f32 v112, v112, v113
	v_cvt_pk_bf16_f32 v113, v114, v115
	v_cvt_pk_bf16_f32 v114, v104, v105
	v_cvt_pk_bf16_f32 v115, v106, v107
	global_store_dwordx4 v[150:151], v[112:115], off offset:256 sc1
	v_cvt_pk_bf16_f32 v104, v116, v117
	v_cvt_pk_bf16_f32 v105, v118, v119
	v_cvt_pk_bf16_f32 v106, v108, v109
	v_add_co_u32_e32 v108, vcc, s74, v150
	v_cvt_pk_bf16_f32 v107, v110, v111
	s_mov_b64 s[62:63], s[48:49]
	s_nop 0
	v_addc_co_u32_e32 v109, vcc, 0, v151, vcc
	global_store_dwordx4 v[108:109], v[104:107], off sc1
	v_cvt_pk_bf16_f32 v96, v96, v97
	v_cvt_pk_bf16_f32 v97, v98, v99
	v_cvt_pk_bf16_f32 v98, v88, v89
	v_cvt_pk_bf16_f32 v99, v90, v91
	global_store_dwordx4 v[108:109], v[96:99], off offset:256 sc1
	v_cvt_pk_bf16_f32 v88, v100, v101
	v_cvt_pk_bf16_f32 v89, v102, v103
	v_cvt_pk_bf16_f32 v90, v92, v93
	v_add_co_u32_e32 v92, vcc, s75, v150
	v_cvt_pk_bf16_f32 v91, v94, v95
	s_mov_b64 s[66:67], s[46:47]
	s_nop 0
	v_addc_co_u32_e32 v93, vcc, 0, v151, vcc
	global_store_dwordx4 v[92:93], v[88:91], off sc1
	v_cvt_pk_bf16_f32 v80, v80, v81
	v_cvt_pk_bf16_f32 v81, v82, v83
	v_cvt_pk_bf16_f32 v82, v72, v73
	v_cvt_pk_bf16_f32 v83, v74, v75
	global_store_dwordx4 v[92:93], v[80:83], off offset:256 sc1
	v_cvt_pk_bf16_f32 v72, v84, v85
	v_cvt_pk_bf16_f32 v73, v86, v87
	v_cvt_pk_bf16_f32 v74, v76, v77
	v_add_co_u32_e32 v76, vcc, s76, v150
	v_cvt_pk_bf16_f32 v75, v78, v79
	s_mov_b64 s[64:65], s[44:45]
	s_nop 0
	v_addc_co_u32_e32 v77, vcc, 0, v151, vcc
	global_store_dwordx4 v[76:77], v[72:75], off sc1
	v_cvt_pk_bf16_f32 v68, v68, v69
	v_cvt_pk_bf16_f32 v69, v70, v71
	v_cvt_pk_bf16_f32 v70, v64, v65
	v_cvt_pk_bf16_f32 v71, v66, v67
	global_store_dwordx4 v[76:77], v[68:71], off offset:256 sc1
	v_cvt_pk_bf16_f32 v60, v60, v61
	v_cvt_pk_bf16_f32 v61, v62, v63
	v_cvt_pk_bf16_f32 v62, v56, v57
	v_add_co_u32_e32 v56, vcc, s77, v150
	v_cvt_pk_bf16_f32 v63, v58, v59
	s_nop 1
	v_addc_co_u32_e32 v57, vcc, 0, v151, vcc
	global_store_dwordx4 v[56:57], v[60:63], off sc1
	v_cvt_pk_bf16_f32 v48, v48, v49
	v_cvt_pk_bf16_f32 v49, v50, v51
	v_cvt_pk_bf16_f32 v50, v40, v41
	v_cvt_pk_bf16_f32 v51, v42, v43
	global_store_dwordx4 v[56:57], v[48:51], off offset:256 sc1
	v_cvt_pk_bf16_f32 v40, v52, v53
	v_cvt_pk_bf16_f32 v41, v54, v55
	v_cvt_pk_bf16_f32 v42, v44, v45
	v_add_co_u32_e32 v44, vcc, s78, v150
	v_cvt_pk_bf16_f32 v43, v46, v47
	s_nop 1
	v_addc_co_u32_e32 v45, vcc, 0, v151, vcc
	global_store_dwordx4 v[44:45], v[40:43], off sc1
	v_cvt_pk_bf16_f32 v32, v32, v33
	v_cvt_pk_bf16_f32 v33, v34, v35
	v_cvt_pk_bf16_f32 v34, v24, v25
	v_cvt_pk_bf16_f32 v35, v26, v27
	global_store_dwordx4 v[44:45], v[32:35], off offset:256 sc1
	v_cvt_pk_bf16_f32 v24, v36, v37
	v_cvt_pk_bf16_f32 v25, v38, v39
	v_cvt_pk_bf16_f32 v26, v28, v29
	v_add_co_u32_e32 v28, vcc, s79, v150
	v_cvt_pk_bf16_f32 v27, v30, v31
	s_nop 1
	v_addc_co_u32_e32 v29, vcc, 0, v151, vcc
	global_store_dwordx4 v[28:29], v[24:27], off sc1
	v_cvt_pk_bf16_f32 v16, v16, v17
	v_cvt_pk_bf16_f32 v17, v18, v19
	v_cvt_pk_bf16_f32 v18, v8, v9
	v_cvt_pk_bf16_f32 v19, v10, v11
	global_store_dwordx4 v[28:29], v[16:19], off offset:256 sc1
	v_cvt_pk_bf16_f32 v8, v20, v21
	v_cvt_pk_bf16_f32 v9, v22, v23
	v_cvt_pk_bf16_f32 v10, v12, v13
	v_add_co_u32_e32 v12, vcc, s80, v150
	v_cvt_pk_bf16_f32 v11, v14, v15
	s_nop 1
	v_addc_co_u32_e32 v13, vcc, 0, v151, vcc
	s_and_b64 vcc, exec, s[42:43]
	global_store_dwordx4 v[12:13], v[8:11], off sc1
	v_cvt_pk_bf16_f32 v4, v4, v5
	v_cvt_pk_bf16_f32 v5, v6, v7
	v_cvt_pk_bf16_f32 v6, v0, v1
	v_cvt_pk_bf16_f32 v7, v2, v3
	global_store_dwordx4 v[12:13], v[4:7], off offset:256 sc1
	s_cbranch_vccz .LBB0_292
	s_waitcnt vmcnt(0)
	s_cmpk_gt_u32 s5, 0xff
	s_cbranch_scc1 .LBB0_303
	s_barrier

; #define PG8_STAGE(bufoff, gbase, voff) do { _Pragma("unroll") for (int _i = 0; _i < 2; ++_i) \
;         __builtin_amdgcn_global_load_lds((const unsigned*)((const char*)(gbase) + (voff)[_i]), (LAS unsigned*)(lds + (bufoff) + ldsw + _i * 8192), 16, 0, 0); } while (0)
; #define PG8_LDA(dst, b, h) do { _Pragma("unroll") for (int m = 0; m < 4; ++m) _Pragma("unroll") for (int k = 0; k < 2; ++k) dst[m][k] = *(const LAS bf16x8*)(lds + PG8_SA(b, h) + aoff + m * 2048 + k * 1024); } while (0)
; #define PG8_LDB(dst, b, h) do { _Pragma("unroll") for (int n = 0; n < 2; ++n) _Pragma("unroll") for (int k = 0; k < 2; ++k) dst[n][k] = *(const LAS bf16x8*)(lds + PG8_SB(b, h) + boff + n * 2048 + k * 1024); } while (0)
; #define PG8_MMA(ai, bj, At, Bt) do { __builtin_amdgcn_s_setprio(1); _Pragma("unroll") for (int m = 0; m < 4; ++m) _Pragma("unroll") for (int n = 0; n < 2; ++n) _Pragma("unroll") for (int k = 0; k < 2; ++k) \
;         acc[ai][bj][m][n] = __builtin_amdgcn_mfma_f32_16x16x32_bf16(Bt[n][k], At[m][k], acc[ai][bj][m][n], 0, 0, 0); __builtin_amdgcn_s_setprio(0); } while (0)
; #define PG8_WAIT_L(n) asm volatile("s_waitcnt lgkmcnt(" #n ")" ::: "memory")
; #define PG8_BAR __builtin_amdgcn_s_barrier()
; #define PG8_SCHED __builtin_amdgcn_sched_barrier(0)
; template <class Epi, class Sched>
; __device__ __forceinline__ void gemm_phase(LAS unsigned char* lds, const int K, const Sched& S, const Epi& E) {
;     ...
;             PG8_LDB(B0, 0, 0); PG8_SCHED; PG8_LDA(At, 0, 0); PG8_STAGE(PG8_SA(1, 1), a1 + hstepA, voffA);
;             PG8_WAIT_L(8); PG8_BAR; PG8_WAIT_L(0); PG8_MMA(0, 0, At, B0); PG8_BAR; PG8_SCHED;
;             PG8_LDB(B1, 0, 1); PG8_STAGE(PG8_SB(0, 0), b2, voffB);
;             PG8_BAR; PG8_WAIT_L(0); PG8_MMA(0, 1, At, B1); PG8_BAR;
;             PG8_LDA(At, 0, 1); PG8_STAGE(PG8_SA(0, 0), a2, voffA);
;             PG8_BAR; PG8_WAIT_L(0); PG8_MMA(1, 0, At, B0); PG8_BAR; PG8_SCHED;
.LBB0_538:
	ds_read_b128 v[96:99], v159
	ds_read_b128 v[104:107], v159 offset:1024
	ds_read_b128 v[108:111], v159 offset:2048
	ds_read_b128 v[116:119], v159 offset:3072
	s_add_u32 s40, s38, 0xfffc0080
	s_addc_u32 s41, s39, -1
	s_cmp_eq_u32 s33, 12
	s_cselect_b32 s43, s21, s41
	s_cselect_b32 s42, s20, s40
	s_cselect_b32 s41, s27, s17
	s_cselect_b32 s40, s26, s11
	v_lshl_add_u64 v[168:169], s[38:39], 0, v[148:149]
	s_add_i32 m0, s50, 0xc000
	ds_read_b128 v[152:155], v160
	ds_read_b128 v[164:167], v160 offset:1024
	ds_read_b128 v[172:175], v160 offset:2048
	ds_read_b128 v[176:179], v160 offset:3072
	ds_read_b128 v[180:183], v160 offset:4096
	ds_read_b128 v[184:187], v160 offset:5120
	ds_read_b128 v[188:191], v160 offset:6144
	ds_read_b128 v[192:195], v160 offset:7168
	global_load_lds_dwordx4 v[168:169], off
	v_lshl_add_u64 v[168:169], s[38:39], 0, v[150:151]
	s_add_i32 m0, s50, 0xe000
	s_nop 0
	global_load_lds_dwordx4 v[168:169], off
	s_waitcnt lgkmcnt(8)
	s_barrier
	s_waitcnt lgkmcnt(0)
	s_setprio 1
	v_mfma_f32_16x16x32_bf16 v[140:143], v[96:99], v[152:155], v[140:143]
	v_mfma_f32_16x16x32_bf16 v[136:139], v[108:111], v[152:155], v[136:139]
	v_mfma_f32_16x16x32_bf16 v[124:127], v[96:99], v[172:175], v[124:127]
	v_mfma_f32_16x16x32_bf16 v[120:123], v[108:111], v[172:175], v[120:123]
	v_mfma_f32_16x16x32_bf16 v[92:95], v[96:99], v[180:183], v[92:95]
	v_mfma_f32_16x16x32_bf16 v[88:91], v[108:111], v[180:183], v[88:91]
	v_mfma_f32_16x16x32_bf16 v[76:79], v[96:99], v[188:191], v[76:79]
	v_mfma_f32_16x16x32_bf16 v[72:75], v[108:111], v[188:191], v[72:75]
	v_mfma_f32_16x16x32_bf16 v[140:143], v[104:107], v[164:167], v[140:143]
	v_mfma_f32_16x16x32_bf16 v[136:139], v[116:119], v[164:167], v[136:139]
	v_mfma_f32_16x16x32_bf16 v[124:127], v[104:107], v[176:179], v[124:127]
	v_mfma_f32_16x16x32_bf16 v[120:123], v[116:119], v[176:179], v[120:123]
	v_mfma_f32_16x16x32_bf16 v[92:95], v[104:107], v[184:187], v[92:95]
	v_mfma_f32_16x16x32_bf16 v[88:91], v[116:119], v[184:187], v[88:91]
	v_mfma_f32_16x16x32_bf16 v[76:79], v[104:107], v[192:195], v[76:79]
	v_mfma_f32_16x16x32_bf16 v[72:75], v[116:119], v[192:195], v[72:75]
	s_setprio 0
	s_barrier
	s_add_i32 s52, s69, s45
	v_lshl_add_u64 v[168:169], s[40:41], 0, v[144:145]
	s_mov_b32 m0, s52
	ds_read_b128 v[196:199], v161
	ds_read_b128 v[200:203], v161 offset:1024
	ds_read_b128 v[204:207], v161 offset:2048
	ds_read_b128 v[208:211], v161 offset:3072
	global_load_lds_dwordx4 v[168:169], off
	v_lshl_add_u64 v[212:213], s[40:41], 0, v[146:147]
	s_add_i32 m0, s52, 0x2000
	s_nop 0
	global_load_lds_dwordx4 v[212:213], off
	s_barrier
	s_waitcnt lgkmcnt(0)
	s_setprio 1
	v_mfma_f32_16x16x32_bf16 v[132:135], v[196:199], v[152:155], v[132:135]
	v_mfma_f32_16x16x32_bf16 v[128:131], v[204:207], v[152:155], v[128:131]
	v_mfma_f32_16x16x32_bf16 v[112:115], v[196:199], v[172:175], v[112:115]
	v_mfma_f32_16x16x32_bf16 v[100:103], v[204:207], v[172:175], v[100:103]
	v_mfma_f32_16x16x32_bf16 v[84:87], v[196:199], v[180:183], v[84:87]
	v_mfma_f32_16x16x32_bf16 v[80:83], v[204:207], v[180:183], v[80:83]
	v_mfma_f32_16x16x32_bf16 v[68:71], v[196:199], v[188:191], v[68:71]
	v_mfma_f32_16x16x32_bf16 v[64:67], v[204:207], v[188:191], v[64:67]
	v_mfma_f32_16x16x32_bf16 v[132:135], v[200:203], v[164:167], v[132:135]
	v_mfma_f32_16x16x32_bf16 v[128:131], v[208:211], v[164:167], v[128:131]
	v_mfma_f32_16x16x32_bf16 v[112:115], v[200:203], v[176:179], v[112:115]
	v_mfma_f32_16x16x32_bf16 v[100:103], v[208:211], v[176:179], v[100:103]
	v_mfma_f32_16x16x32_bf16 v[84:87], v[200:203], v[184:187], v[84:87]
	v_mfma_f32_16x16x32_bf16 v[80:83], v[208:211], v[184:187], v[80:83]
	v_mfma_f32_16x16x32_bf16 v[68:71], v[200:203], v[192:195], v[68:71]
	v_mfma_f32_16x16x32_bf16 v[64:67], v[208:211], v[192:195], v[64:67]
	s_setprio 0
	s_mov_b32 m0, s50
	v_lshl_add_u64 v[214:215], s[42:43], 0, v[144:145]
	s_barrier
	ds_read_b128 v[152:155], v160 offset:16384
	ds_read_b128 v[164:167], v160 offset:17408
	ds_read_b128 v[172:175], v160 offset:18432
	ds_read_b128 v[176:179], v160 offset:19456
	ds_read_b128 v[180:183], v160 offset:20480
	ds_read_b128 v[184:187], v160 offset:21504
	ds_read_b128 v[188:191], v160 offset:22528
	ds_read_b128 v[192:195], v160 offset:23552
	global_load_lds_dwordx4 v[214:215], off
	v_lshl_add_u64 v[216:217], s[42:43], 0, v[146:147]
	s_mov_b32 m0, s51
	s_nop 0
	global_load_lds_dwordx4 v[216:217], off
	s_barrier
	s_waitcnt lgkmcnt(0)
	s_setprio 1
	v_mfma_f32_16x16x32_bf16 v[60:63], v[96:99], v[152:155], v[60:63]
	v_mfma_f32_16x16x32_bf16 v[56:59], v[108:111], v[152:155], v[56:59]
	v_mfma_f32_16x16x32_bf16 v[44:47], v[96:99], v[172:175], v[44:47]
	v_mfma_f32_16x16x32_bf16 v[40:43], v[108:111], v[172:175], v[40:43]
	v_mfma_f32_16x16x32_bf16 v[28:31], v[96:99], v[180:183], v[28:31]
	v_mfma_f32_16x16x32_bf16 v[24:27], v[108:111], v[180:183], v[24:27]
	v_mfma_f32_16x16x32_bf16 v[12:15], v[96:99], v[188:191], v[12:15]
	v_mfma_f32_16x16x32_bf16 v[8:11], v[108:111], v[188:191], v[8:11]
	v_mfma_f32_16x16x32_bf16 v[60:63], v[104:107], v[164:167], v[60:63]
	v_mfma_f32_16x16x32_bf16 v[56:59], v[116:119], v[164:167], v[56:59]
	v_mfma_f32_16x16x32_bf16 v[44:47], v[104:107], v[176:179], v[44:47]
	v_mfma_f32_16x16x32_bf16 v[40:43], v[116:119], v[176:179], v[40:43]
	v_mfma_f32_16x16x32_bf16 v[28:31], v[104:107], v[184:187], v[28:31]
	v_mfma_f32_16x16x32_bf16 v[24:27], v[116:119], v[184:187], v[24:27]
	v_mfma_f32_16x16x32_bf16 v[12:15], v[104:107], v[192:195], v[12:15]
	v_mfma_f32_16x16x32_bf16 v[8:11], v[116:119], v[192:195], v[8:11]
	s_setprio 0
	s_barrier
; #define PG8_STAGE(bufoff, gbase, voff) do { _Pragma("unroll") for (int _i = 0; _i < 2; ++_i) \
;         __builtin_amdgcn_global_load_lds((const unsigned*)((const char*)(gbase) + (voff)[_i]), (LAS unsigned*)(lds + (bufoff) + ldsw + _i * 8192), 16, 0, 0); } while (0)
; #define PG8_LDA(dst, b, h) do { _Pragma("unroll") for (int m = 0; m < 4; ++m) _Pragma("unroll") for (int k = 0; k < 2; ++k) dst[m][k] = *(const LAS bf16x8*)(lds + PG8_SA(b, h) + aoff + m * 2048 + k * 1024); } while (0)
; #define PG8_LDB(dst, b, h) do { _Pragma("unroll") for (int n = 0; n < 2; ++n) _Pragma("unroll") for (int k = 0; k < 2; ++k) dst[n][k] = *(const LAS bf16x8*)(lds + PG8_SB(b, h) + boff + n * 2048 + k * 1024); } while (0)
; #define PG8_MMA(ai, bj, At, Bt) do { __builtin_amdgcn_s_setprio(1); _Pragma("unroll") for (int m = 0; m < 4; ++m) _Pragma("unroll") for (int n = 0; n < 2; ++n) _Pragma("unroll") for (int k = 0; k < 2; ++k) \
;         acc[ai][bj][m][n] = __builtin_amdgcn_mfma_f32_16x16x32_bf16(Bt[n][k], At[m][k], acc[ai][bj][m][n], 0, 0, 0); __builtin_amdgcn_s_setprio(0); } while (0)
; #define PG8_WAIT_V(n) asm volatile("s_waitcnt vmcnt(" #n ")" ::: "memory")
; #define PG8_WAIT_L(n) asm volatile("s_waitcnt lgkmcnt(" #n ")" ::: "memory")
; #define PG8_BAR __builtin_amdgcn_s_barrier()
; #define PG8_SCHED __builtin_amdgcn_sched_barrier(0)
; template <class Epi, class Sched>
; __device__ __forceinline__ void gemm_phase(LAS unsigned char* lds, const int K, const Sched& S, const Epi& E) {
;     ...
;             PG8_STAGE(PG8_SB(0, 1), b2 + hstep, voffB);
;             PG8_WAIT_V(6); PG8_BAR; PG8_MMA(1, 1, At, B1); PG8_BAR;
;             PG8_LDB(B0, 1, 0); PG8_SCHED; PG8_LDA(At, 1, 0); PG8_STAGE(PG8_SA(0, 1), a2 + hstepA, voffA);
;             PG8_WAIT_L(8); PG8_BAR; PG8_WAIT_L(0); PG8_MMA(0, 0, At, B0); PG8_BAR; PG8_SCHED;
;             PG8_LDB(B1, 1, 1); PG8_STAGE(PG8_SB(1, 0), b3, voffB);
;             PG8_BAR; PG8_WAIT_L(0); PG8_MMA(0, 1, At, B1); PG8_BAR;
;             PG8_LDA(At, 1, 1); PG8_STAGE(PG8_SA(1, 0), a3, voffA);
	s_add_u32 s52, s40, 0x40000
	s_addc_u32 s53, s41, 0
	s_add_i32 s54, s70, s45
	v_lshl_add_u64 v[96:97], s[52:53], 0, v[144:145]
	s_mov_b32 m0, s54
	s_nop 0
	global_load_lds_dwordx4 v[96:97], off
	v_lshl_add_u64 v[96:97], s[52:53], 0, v[146:147]
	s_add_i32 m0, s54, 0x2000
	s_nop 0
	global_load_lds_dwordx4 v[96:97], off
	s_waitcnt vmcnt(6)
	s_barrier
	s_setprio 1
	v_mfma_f32_16x16x32_bf16 v[52:55], v[196:199], v[152:155], v[52:55]
	v_mfma_f32_16x16x32_bf16 v[48:51], v[204:207], v[152:155], v[48:51]
	v_mfma_f32_16x16x32_bf16 v[36:39], v[196:199], v[172:175], v[36:39]
	v_mfma_f32_16x16x32_bf16 v[32:35], v[204:207], v[172:175], v[32:35]
	v_mfma_f32_16x16x32_bf16 v[20:23], v[196:199], v[180:183], v[20:23]
	v_mfma_f32_16x16x32_bf16 v[16:19], v[204:207], v[180:183], v[16:19]
	v_mfma_f32_16x16x32_bf16 v[4:7], v[196:199], v[188:191], v[4:7]
	v_mfma_f32_16x16x32_bf16 v[0:3], v[204:207], v[188:191], v[0:3]
	v_mfma_f32_16x16x32_bf16 v[52:55], v[200:203], v[164:167], v[52:55]
	v_mfma_f32_16x16x32_bf16 v[48:51], v[208:211], v[164:167], v[48:51]
	v_mfma_f32_16x16x32_bf16 v[36:39], v[200:203], v[176:179], v[36:39]
	v_mfma_f32_16x16x32_bf16 v[32:35], v[208:211], v[176:179], v[32:35]
	v_mfma_f32_16x16x32_bf16 v[20:23], v[200:203], v[184:187], v[20:23]
	v_mfma_f32_16x16x32_bf16 v[16:19], v[208:211], v[184:187], v[16:19]
	v_mfma_f32_16x16x32_bf16 v[4:7], v[200:203], v[192:195], v[4:7]
	v_mfma_f32_16x16x32_bf16 v[0:3], v[208:211], v[192:195], v[0:3]
	s_setprio 0
	s_add_i32 s52, 0, 0x18000
	v_add_u32_e32 v116, s52, v157
	s_barrier
	ds_read_b128 v[96:99], v116
	ds_read_b128 v[104:107], v116 offset:1024
	ds_read_b128 v[108:111], v116 offset:2048
	ds_read_b128 v[116:119], v116 offset:3072
	s_add_u32 s42, s42, 0x40000
	s_addc_u32 s43, s43, 0
	s_mov_b32 m0, s62
	v_lshl_add_u64 v[196:197], s[42:43], 0, v[144:145]
	ds_read_b128 v[152:155], v160 offset:32768
	ds_read_b128 v[164:167], v160 offset:33792
	ds_read_b128 v[172:175], v160 offset:34816
	ds_read_b128 v[176:179], v160 offset:35840
	ds_read_b128 v[180:183], v160 offset:36864
	ds_read_b128 v[184:187], v160 offset:37888
	ds_read_b128 v[188:191], v160 offset:38912
	ds_read_b128 v[192:195], v160 offset:39936
	global_load_lds_dwordx4 v[196:197], off
	v_lshl_add_u64 v[196:197], s[42:43], 0, v[146:147]
	s_mov_b32 m0, s63
	s_nop 0
	global_load_lds_dwordx4 v[196:197], off
	s_waitcnt lgkmcnt(8)
	s_barrier
	s_waitcnt lgkmcnt(0)
	s_setprio 1
	v_mfma_f32_16x16x32_bf16 v[140:143], v[96:99], v[152:155], v[140:143]
	v_mfma_f32_16x16x32_bf16 v[136:139], v[108:111], v[152:155], v[136:139]
	v_mfma_f32_16x16x32_bf16 v[124:127], v[96:99], v[172:175], v[124:127]
	v_mfma_f32_16x16x32_bf16 v[120:123], v[108:111], v[172:175], v[120:123]
	v_mfma_f32_16x16x32_bf16 v[92:95], v[96:99], v[180:183], v[92:95]
	v_mfma_f32_16x16x32_bf16 v[88:91], v[108:111], v[180:183], v[88:91]
	v_mfma_f32_16x16x32_bf16 v[76:79], v[96:99], v[188:191], v[76:79]
	v_mfma_f32_16x16x32_bf16 v[72:75], v[108:111], v[188:191], v[72:75]
	v_mfma_f32_16x16x32_bf16 v[140:143], v[104:107], v[164:167], v[140:143]
	v_mfma_f32_16x16x32_bf16 v[136:139], v[116:119], v[164:167], v[136:139]
	v_mfma_f32_16x16x32_bf16 v[124:127], v[104:107], v[176:179], v[124:127]
	v_mfma_f32_16x16x32_bf16 v[120:123], v[116:119], v[176:179], v[120:123]
	v_mfma_f32_16x16x32_bf16 v[92:95], v[104:107], v[184:187], v[92:95]
	v_mfma_f32_16x16x32_bf16 v[88:91], v[116:119], v[184:187], v[88:91]
	v_mfma_f32_16x16x32_bf16 v[76:79], v[104:107], v[192:195], v[76:79]
	v_mfma_f32_16x16x32_bf16 v[72:75], v[116:119], v[192:195], v[72:75]
	s_setprio 0
	s_barrier
	s_add_i32 s42, 0, 0x1c000
	s_add_i32 s43, s52, s45
	v_add_u32_e32 v163, s42, v157
	v_lshl_add_u64 v[168:169], v[168:169], 0, s[12:13]
	s_mov_b32 m0, s43
	ds_read_b128 v[196:199], v163
	ds_read_b128 v[200:203], v163 offset:1024
	ds_read_b128 v[204:207], v163 offset:2048
	ds_read_b128 v[208:211], v163 offset:3072
	global_load_lds_dwordx4 v[168:169], off
	v_lshl_add_u64 v[168:169], v[212:213], 0, s[12:13]
	s_add_i32 m0, s43, 0x2000
	s_nop 0
	global_load_lds_dwordx4 v[168:169], off
	s_barrier
	s_waitcnt lgkmcnt(0)
	s_setprio 1
	v_mfma_f32_16x16x32_bf16 v[132:135], v[196:199], v[152:155], v[132:135]
	v_mfma_f32_16x16x32_bf16 v[128:131], v[204:207], v[152:155], v[128:131]
	v_mfma_f32_16x16x32_bf16 v[112:115], v[196:199], v[172:175], v[112:115]
	v_mfma_f32_16x16x32_bf16 v[100:103], v[204:207], v[172:175], v[100:103]
	v_mfma_f32_16x16x32_bf16 v[84:87], v[196:199], v[180:183], v[84:87]
	v_mfma_f32_16x16x32_bf16 v[80:83], v[204:207], v[180:183], v[80:83]
	v_mfma_f32_16x16x32_bf16 v[68:71], v[196:199], v[188:191], v[68:71]
	v_mfma_f32_16x16x32_bf16 v[64:67], v[204:207], v[188:191], v[64:67]
	v_mfma_f32_16x16x32_bf16 v[132:135], v[200:203], v[164:167], v[132:135]
	v_mfma_f32_16x16x32_bf16 v[128:131], v[208:211], v[164:167], v[128:131]
	v_mfma_f32_16x16x32_bf16 v[112:115], v[200:203], v[176:179], v[112:115]
	v_mfma_f32_16x16x32_bf16 v[100:103], v[208:211], v[176:179], v[100:103]
	v_mfma_f32_16x16x32_bf16 v[84:87], v[200:203], v[184:187], v[84:87]
	v_mfma_f32_16x16x32_bf16 v[80:83], v[208:211], v[184:187], v[80:83]
	v_mfma_f32_16x16x32_bf16 v[68:71], v[200:203], v[192:195], v[68:71]
	v_mfma_f32_16x16x32_bf16 v[64:67], v[208:211], v[192:195], v[64:67]
	s_setprio 0
	s_mov_b32 m0, s67
	v_lshl_add_u64 v[168:169], v[214:215], 0, s[12:13]
	s_barrier
	ds_read_b128 v[152:155], v160 offset:49152
	ds_read_b128 v[164:167], v160 offset:50176
	ds_read_b128 v[172:175], v160 offset:51200
	ds_read_b128 v[176:179], v160 offset:52224
	ds_read_b128 v[180:183], v160 offset:53248
	ds_read_b128 v[184:187], v160 offset:54272
	ds_read_b128 v[188:191], v160 offset:55296
	ds_read_b128 v[192:195], v160 offset:56320
	global_load_lds_dwordx4 v[168:169], off
	v_lshl_add_u64 v[168:169], v[216:217], 0, s[12:13]
	s_mov_b32 m0, s68
	s_nop 0
	global_load_lds_dwordx4 v[168:169], off
	s_barrier
; #define PG8_STAGE(bufoff, gbase, voff) do { _Pragma("unroll") for (int _i = 0; _i < 2; ++_i) \
;         __builtin_amdgcn_global_load_lds((const unsigned*)((const char*)(gbase) + (voff)[_i]), (LAS unsigned*)(lds + (bufoff) + ldsw + _i * 8192), 16, 0, 0); } while (0)
; #define PG8_MMA(ai, bj, At, Bt) do { __builtin_amdgcn_s_setprio(1); _Pragma("unroll") for (int m = 0; m < 4; ++m) _Pragma("unroll") for (int n = 0; n < 2; ++n) _Pragma("unroll") for (int k = 0; k < 2; ++k) \
;         acc[ai][bj][m][n] = __builtin_amdgcn_mfma_f32_16x16x32_bf16(Bt[n][k], At[m][k], acc[ai][bj][m][n], 0, 0, 0); __builtin_amdgcn_s_setprio(0); } while (0)
; #define PG8_WAIT_V(n) asm volatile("s_waitcnt vmcnt(" #n ")" ::: "memory")
; #define PG8_WAIT_L(n) asm volatile("s_waitcnt lgkmcnt(" #n ")" ::: "memory")
; template <class Epi, class Sched>
; __device__ __forceinline__ void gemm_phase(LAS unsigned char* lds, const int K, const Sched& S, const Epi& E) {
;     ...
;             PG8_BAR; PG8_WAIT_L(0); PG8_MMA(1, 0, At, B0); PG8_BAR; PG8_SCHED;
;             PG8_STAGE(PG8_SB(1, 1), b3 + hstep, voffB);
;             PG8_WAIT_V(6); PG8_BAR; PG8_MMA(1, 1, At, B1); PG8_BAR;
;     __device__ __forceinline__ void operator()(const f32x4 (&acc)[2][2][4][2], const Unit& u, int wr, int wc, int fr, int fq) const {
;         const int row0 = u.pm * BM + wr * 64 + fr, col0 = u.pn * BM + wc * 32 + 4 * fq, b = u.pm >> 3;
;         f32x4 gv[2][2];
; #pragma unroll
;         for (int bj = 0; bj < 2; ++bj)
; #pragma unroll
;             for (int n = 0; n < 2; ++n) gv[bj][n] = *(const f32x4*)(gate + (size_t)b * NMOD + col0 + bj * HALF + n * 16);
; #pragma unroll
;         for (int ai = 0; ai < 2; ++ai)
; #pragma unroll
;             for (int m = 0; m < 4; ++m) { const int row = row0 + ai * HALF + m * 16; const size_t off = (size_t)row * DM + col0; float s = 0.f;
; #pragma unroll
;                 for (int bj = 0; bj < 2; ++bj)
; #pragma unroll
;                     for (int n = 0; n < 2; ++n) { const f32x4 xv = *(const f32x4*)(base + off + bj * HALF + n * 16); const f32x4 o = xv + gv[bj][n] * acc[ai][bj][m][n];
;                         *(f32x4*)(out + off + bj * HALF + n * 16) = o; s += (o[0] * o[0] + o[1] * o[1]) + (o[2] * o[2] + o[3] * o[3]); }
;                 s += __shfl_xor(s, 16); s += __shfl_xor(s, 32);
;                 if (fq == 0) ssq[(size_t)row * 16 + u.pn * 4 + wc] = s; }
	s_waitcnt lgkmcnt(0)
	s_setprio 1
	v_mfma_f32_16x16x32_bf16 v[60:63], v[96:99], v[152:155], v[60:63]
	v_mfma_f32_16x16x32_bf16 v[56:59], v[108:111], v[152:155], v[56:59]
	v_mfma_f32_16x16x32_bf16 v[44:47], v[96:99], v[172:175], v[44:47]
	v_mfma_f32_16x16x32_bf16 v[40:43], v[108:111], v[172:175], v[40:43]
	v_mfma_f32_16x16x32_bf16 v[28:31], v[96:99], v[180:183], v[28:31]
	v_mfma_f32_16x16x32_bf16 v[24:27], v[108:111], v[180:183], v[24:27]
	v_mfma_f32_16x16x32_bf16 v[12:15], v[96:99], v[188:191], v[12:15]
	v_mfma_f32_16x16x32_bf16 v[8:11], v[108:111], v[188:191], v[8:11]
	v_mfma_f32_16x16x32_bf16 v[60:63], v[104:107], v[164:167], v[60:63]
	v_mfma_f32_16x16x32_bf16 v[56:59], v[116:119], v[164:167], v[56:59]
	v_mfma_f32_16x16x32_bf16 v[44:47], v[104:107], v[176:179], v[44:47]
	v_mfma_f32_16x16x32_bf16 v[40:43], v[116:119], v[176:179], v[40:43]
	v_mfma_f32_16x16x32_bf16 v[28:31], v[104:107], v[184:187], v[28:31]
	v_mfma_f32_16x16x32_bf16 v[24:27], v[116:119], v[184:187], v[24:27]
	v_mfma_f32_16x16x32_bf16 v[12:15], v[104:107], v[192:195], v[12:15]
	v_mfma_f32_16x16x32_bf16 v[8:11], v[116:119], v[192:195], v[8:11]
	s_setprio 0
	s_barrier
	s_add_u32 s40, s40, 0x40080
	s_addc_u32 s41, s41, 0
	s_add_i32 s42, s42, s45
	v_lshl_add_u64 v[96:97], s[40:41], 0, v[144:145]
	s_mov_b32 m0, s42
	s_nop 0
	global_load_lds_dwordx4 v[96:97], off
	v_lshl_add_u64 v[96:97], s[40:41], 0, v[146:147]
	s_add_i32 m0, s42, 0x2000
	s_nop 0
	global_load_lds_dwordx4 v[96:97], off
	s_waitcnt vmcnt(6)
	s_barrier
	s_setprio 1
	v_mfma_f32_16x16x32_bf16 v[52:55], v[196:199], v[152:155], v[52:55]
	v_mfma_f32_16x16x32_bf16 v[48:51], v[204:207], v[152:155], v[48:51]
	v_mfma_f32_16x16x32_bf16 v[36:39], v[196:199], v[172:175], v[36:39]
	v_mfma_f32_16x16x32_bf16 v[32:35], v[204:207], v[172:175], v[32:35]
	v_mfma_f32_16x16x32_bf16 v[20:23], v[196:199], v[180:183], v[20:23]
	v_mfma_f32_16x16x32_bf16 v[16:19], v[204:207], v[180:183], v[16:19]
	v_mfma_f32_16x16x32_bf16 v[4:7], v[196:199], v[188:191], v[4:7]
	v_mfma_f32_16x16x32_bf16 v[0:3], v[204:207], v[188:191], v[0:3]
	v_mfma_f32_16x16x32_bf16 v[52:55], v[200:203], v[164:167], v[52:55]
	v_mfma_f32_16x16x32_bf16 v[48:51], v[208:211], v[164:167], v[48:51]
	v_mfma_f32_16x16x32_bf16 v[36:39], v[200:203], v[176:179], v[36:39]
	v_mfma_f32_16x16x32_bf16 v[32:35], v[208:211], v[176:179], v[32:35]
	v_mfma_f32_16x16x32_bf16 v[20:23], v[200:203], v[184:187], v[20:23]
	v_mfma_f32_16x16x32_bf16 v[16:19], v[208:211], v[184:187], v[16:19]
	v_mfma_f32_16x16x32_bf16 v[4:7], v[200:203], v[192:195], v[4:7]
	v_mfma_f32_16x16x32_bf16 v[0:3], v[208:211], v[192:195], v[0:3]
	s_setprio 0
	s_add_i32 s33, s33, 2
	s_add_u32 s38, s38, 0x100
	s_addc_u32 s39, s39, 0
	s_add_u32 s11, s11, 0x100
	s_addc_u32 s17, s17, 0
	s_cmp_gt_u32 s33, 13
	s_barrier
	s_cbranch_scc0 .LBB0_538
	v_lshl_add_u32 v154, s6, 8, v156
	v_lshl_or_b32 v152, s10, 8, v158
	s_ashr_i32 s11, s6, 3
	v_ashrrev_i32_e32 v155, 31, v154
	s_mul_hi_i32 s17, s11, 0x6000
	s_mulk_i32 s11, 0x6000
	v_ashrrev_i32_e32 v153, 31, v152
	v_lshlrev_b64 v[98:99], 10, v[154:155]
	s_add_u32 s38, s64, s11
	v_lshl_add_u64 v[98:99], v[98:99], 0, v[152:153]
	s_addc_u32 s39, s65, s17
	v_lshlrev_b64 v[168:169], 2, v[98:99]
	v_lshl_add_u64 v[96:97], v[152:153], 2, s[38:39]
	v_lshl_add_u64 v[172:173], s[36:37], 0, v[168:169]
	global_load_dwordx4 v[164:167], v[172:173], off
	global_load_dwordx4 v[116:119], v[96:97], off
	global_load_dwordx4 v[108:111], v[96:97], off offset:64
	global_load_dwordx4 v[104:107], v[96:97], off offset:512
	s_nop 0
	global_load_dwordx4 v[96:99], v[96:97], off offset:576
	v_lshl_add_u64 v[168:169], s[30:31], 0, v[168:169]
	s_lshl_b32 s38, s10, 2
	s_ashr_i32 s39, s38, 31
	s_waitcnt vmcnt(0)
	v_pk_fma_f32 v[142:143], v[142:143], v[118:119], v[166:167]
	v_pk_fma_f32 v[140:141], v[140:141], v[116:117], v[164:165]
	global_store_dwordx4 v[168:169], v[140:143], off
	global_load_dwordx4 v[164:167], v[172:173], off offset:64
	s_waitcnt vmcnt(0)
	v_pk_fma_f32 v[138:139], v[138:139], v[110:111], v[166:167]
	v_pk_fma_f32 v[136:137], v[136:137], v[108:109], v[164:165]
	global_store_dwordx4 v[168:169], v[136:139], off offset:64
	global_load_dwordx4 v[164:167], v[172:173], off offset:512
	s_waitcnt vmcnt(0)
	v_pk_fma_f32 v[166:167], v[134:135], v[106:107], v[166:167]
	v_pk_fma_f32 v[164:165], v[132:133], v[104:105], v[164:165]
	global_store_dwordx4 v[168:169], v[164:167], off offset:512
	global_load_dwordx4 v[172:175], v[172:173], off offset:576
	v_mul_f32_e32 v134, v141, v141
	v_mul_f32_e32 v135, v143, v143
	v_fmac_f32_e32 v134, v140, v140
	v_fmac_f32_e32 v135, v142, v142
	v_add_f32_e32 v134, v134, v135
	v_mul_f32_e32 v135, v137, v137
	v_mul_f32_e32 v137, v139, v139
	v_fmac_f32_e32 v135, v136, v136
	v_fmac_f32_e32 v137, v138, v138
	v_add_f32_e32 v135, v135, v137
	v_add_f32_e32 v134, v134, v135
	v_mul_f32_e32 v135, v165, v165
	v_mul_f32_e32 v136, v167, v167
	v_fmac_f32_e32 v135, v164, v164
	v_fmac_f32_e32 v136, v166, v166
	v_add_f32_e32 v135, v135, v136
	v_and_b32_e32 v133, 64, v162
	v_add_f32_e32 v138, v134, v135
	v_xor_b32_e32 v132, 16, v162
	v_add_u32_e32 v133, 64, v133
	v_cmp_lt_i32_e32 vcc, v132, v133
	s_waitcnt vmcnt(0)
	v_pk_fma_f32 v[136:137], v[130:131], v[98:99], v[174:175]
	v_pk_fma_f32 v[134:135], v[128:129], v[96:97], v[172:173]
	v_mul_f32_e32 v129, v137, v137
	v_mul_f32_e32 v128, v135, v135
	v_fmac_f32_e32 v128, v134, v134
	v_fmac_f32_e32 v129, v136, v136
	v_cndmask_b32_e32 v132, v162, v132, vcc
	v_add_f32_e32 v128, v128, v129
	v_lshlrev_b32_e32 v132, 2, v132
	v_add_f32_e32 v128, v138, v128
	ds_bpermute_b32 v129, v132, v128
	v_xor_b32_e32 v130, 32, v162
	v_cmp_lt_i32_e32 vcc, v130, v133
	global_store_dwordx4 v[168:169], v[134:137], off offset:576
	s_waitcnt lgkmcnt(0)
	v_add_f32_e32 v128, v128, v129
	v_cndmask_b32_e32 v130, v162, v130, vcc
	v_lshlrev_b32_e32 v130, 2, v130
	ds_bpermute_b32 v129, v130, v128
	s_and_saveexec_b64 s[40:41], s[0:1]
	s_cbranch_execz .LBB0_541
	v_lshlrev_b64 v[134:135], 6, v[154:155]
	v_lshl_add_u64 v[134:135], s[8:9], 0, v[134:135]
	v_lshl_add_u64 v[134:135], s[38:39], 2, v[134:135]
	s_lshl_b32 s6, s66, 2
	v_lshl_add_u64 v[134:135], v[134:135], 0, s[6:7]
	s_waitcnt lgkmcnt(0)
	v_add_f32_e32 v128, v128, v129
	global_store_dword v[134:135], v128, off

; #define PG8_STAGE(bufoff, gbase, voff) do { _Pragma("unroll") for (int _i = 0; _i < 2; ++_i) \
;         __builtin_amdgcn_global_load_lds((const unsigned*)((const char*)(gbase) + (voff)[_i]), (LAS unsigned*)(lds + (bufoff) + ldsw + _i * 8192), 16, 0, 0); } while (0)
; #define PG8_LDA(dst, b, h) do { _Pragma("unroll") for (int m = 0; m < 4; ++m) _Pragma("unroll") for (int k = 0; k < 2; ++k) dst[m][k] = *(const LAS bf16x8*)(lds + PG8_SA(b, h) + aoff + m * 2048 + k * 1024); } while (0)
; #define PG8_LDB(dst, b, h) do { _Pragma("unroll") for (int n = 0; n < 2; ++n) _Pragma("unroll") for (int k = 0; k < 2; ++k) dst[n][k] = *(const LAS bf16x8*)(lds + PG8_SB(b, h) + boff + n * 2048 + k * 1024); } while (0)
; #define PG8_MMA(ai, bj, At, Bt) do { __builtin_amdgcn_s_setprio(1); _Pragma("unroll") for (int m = 0; m < 4; ++m) _Pragma("unroll") for (int n = 0; n < 2; ++n) _Pragma("unroll") for (int k = 0; k < 2; ++k) \
;         acc[ai][bj][m][n] = __builtin_amdgcn_mfma_f32_16x16x32_bf16(Bt[n][k], At[m][k], acc[ai][bj][m][n], 0, 0, 0); __builtin_amdgcn_s_setprio(0); } while (0)
; #define PG8_WAIT_L(n) asm volatile("s_waitcnt lgkmcnt(" #n ")" ::: "memory")
; #define PG8_BAR __builtin_amdgcn_s_barrier()
; #define PG8_SCHED __builtin_amdgcn_sched_barrier(0)
; template <class Epi, class Sched>
; __device__ __forceinline__ void gemm_phase(LAS unsigned char* lds, const int K, const Sched& S, const Epi& E) {
;     ...
;             PG8_LDB(B0, 0, 0); PG8_SCHED; PG8_LDA(At, 0, 0); PG8_STAGE(PG8_SA(1, 1), a1 + hstepA, voffA);
;             PG8_WAIT_L(8); PG8_BAR; PG8_WAIT_L(0); PG8_MMA(0, 0, At, B0); PG8_BAR; PG8_SCHED;
;             PG8_LDB(B1, 0, 1); PG8_STAGE(PG8_SB(0, 0), b2, voffB);
;             PG8_BAR; PG8_WAIT_L(0); PG8_MMA(0, 1, At, B1); PG8_BAR;
;             PG8_LDA(At, 0, 1); PG8_STAGE(PG8_SA(0, 0), a2, voffA);
;             PG8_BAR; PG8_WAIT_L(0); PG8_MMA(1, 0, At, B0); PG8_BAR; PG8_SCHED;
.LBB0_575:
	v_add_u32_e32 v143, s57, v141
	s_add_u32 s42, s0, s40
	ds_read_b128 v[144:147], v143
	ds_read_b128 v[148:151], v143 offset:1024
	ds_read_b128 v[154:157], v143 offset:2048
	ds_read_b128 v[158:161], v143 offset:3072
	s_addc_u32 s43, s1, s41
	s_add_u32 s42, s42, 0x100
	s_addc_u32 s43, s43, 0
	s_add_u32 s71, s15, s40
	s_addc_u32 s72, s69, s41
	s_cmpk_eq_i32 s40, 0x700
	s_cselect_b32 s45, s39, s43
	s_cselect_b32 s44, s38, s42
	s_cselect_b32 s43, s21, s72
	s_cselect_b32 s42, s20, s71
	s_mov_b32 m0, s62
	v_lshl_add_u64 v[196:197], v[136:137], 0, s[40:41]
	ds_read_b128 v[162:165], v142
	ds_read_b128 v[166:169], v142 offset:1024
	ds_read_b128 v[172:175], v142 offset:2048
	ds_read_b128 v[176:179], v142 offset:3072
	ds_read_b128 v[180:183], v142 offset:4096
	ds_read_b128 v[184:187], v142 offset:5120
	ds_read_b128 v[188:191], v142 offset:6144
	ds_read_b128 v[192:195], v142 offset:7168
	global_load_lds_dwordx4 v[196:197], off
	v_lshl_add_u64 v[196:197], v[138:139], 0, s[40:41]
	s_mov_b32 m0, s63
	s_nop 0
	global_load_lds_dwordx4 v[196:197], off
	s_waitcnt lgkmcnt(8)
	s_barrier
	s_waitcnt lgkmcnt(0)
	s_setprio 1
	v_mfma_f32_16x16x32_bf16 v[124:127], v[144:147], v[162:165], v[124:127]
	v_mfma_f32_16x16x32_bf16 v[120:123], v[154:157], v[162:165], v[120:123]
	v_mfma_f32_16x16x32_bf16 v[112:115], v[144:147], v[172:175], v[112:115]
	v_mfma_f32_16x16x32_bf16 v[104:107], v[154:157], v[172:175], v[104:107]
	v_mfma_f32_16x16x32_bf16 v[96:99], v[144:147], v[180:183], v[96:99]
	v_mfma_f32_16x16x32_bf16 v[88:91], v[154:157], v[180:183], v[88:91]
	v_mfma_f32_16x16x32_bf16 v[80:83], v[144:147], v[188:191], v[80:83]
	v_mfma_f32_16x16x32_bf16 v[72:75], v[154:157], v[188:191], v[72:75]
	v_mfma_f32_16x16x32_bf16 v[124:127], v[148:151], v[166:169], v[124:127]
	v_mfma_f32_16x16x32_bf16 v[120:123], v[158:161], v[166:169], v[120:123]
	v_mfma_f32_16x16x32_bf16 v[112:115], v[148:151], v[176:179], v[112:115]
	v_mfma_f32_16x16x32_bf16 v[104:107], v[158:161], v[176:179], v[104:107]
	v_mfma_f32_16x16x32_bf16 v[96:99], v[148:151], v[184:187], v[96:99]
	v_mfma_f32_16x16x32_bf16 v[88:91], v[158:161], v[184:187], v[88:91]
	v_mfma_f32_16x16x32_bf16 v[80:83], v[148:151], v[192:195], v[80:83]
	v_mfma_f32_16x16x32_bf16 v[72:75], v[158:161], v[192:195], v[72:75]
	s_setprio 0
	s_barrier
	s_mov_b32 m0, s64
	v_add_u32_e32 v143, s59, v141
	v_lshl_add_u64 v[212:213], s[42:43], 0, v[128:129]
	ds_read_b128 v[196:199], v143
	ds_read_b128 v[200:203], v143 offset:1024
	ds_read_b128 v[204:207], v143 offset:2048
	ds_read_b128 v[208:211], v143 offset:3072
	global_load_lds_dwordx4 v[212:213], off
	v_lshl_add_u64 v[214:215], s[42:43], 0, v[130:131]
	s_mov_b32 m0, s65
	s_nop 0
	global_load_lds_dwordx4 v[214:215], off
	s_barrier
	s_waitcnt lgkmcnt(0)
	s_setprio 1
	v_mfma_f32_16x16x32_bf16 v[116:119], v[196:199], v[162:165], v[116:119]
	v_mfma_f32_16x16x32_bf16 v[108:111], v[204:207], v[162:165], v[108:111]
	v_mfma_f32_16x16x32_bf16 v[100:103], v[196:199], v[172:175], v[100:103]
	v_mfma_f32_16x16x32_bf16 v[92:95], v[204:207], v[172:175], v[92:95]
	v_mfma_f32_16x16x32_bf16 v[84:87], v[196:199], v[180:183], v[84:87]
	v_mfma_f32_16x16x32_bf16 v[76:79], v[204:207], v[180:183], v[76:79]
	v_mfma_f32_16x16x32_bf16 v[68:71], v[196:199], v[188:191], v[68:71]
	v_mfma_f32_16x16x32_bf16 v[64:67], v[204:207], v[188:191], v[64:67]
	v_mfma_f32_16x16x32_bf16 v[116:119], v[200:203], v[166:169], v[116:119]
	v_mfma_f32_16x16x32_bf16 v[108:111], v[208:211], v[166:169], v[108:111]
	v_mfma_f32_16x16x32_bf16 v[100:103], v[200:203], v[176:179], v[100:103]
	v_mfma_f32_16x16x32_bf16 v[92:95], v[208:211], v[176:179], v[92:95]
	v_mfma_f32_16x16x32_bf16 v[84:87], v[200:203], v[184:187], v[84:87]
	v_mfma_f32_16x16x32_bf16 v[76:79], v[208:211], v[184:187], v[76:79]
	v_mfma_f32_16x16x32_bf16 v[68:71], v[200:203], v[192:195], v[68:71]
	v_mfma_f32_16x16x32_bf16 v[64:67], v[208:211], v[192:195], v[64:67]
	s_setprio 0
	s_mov_b32 m0, s11
	v_lshl_add_u64 v[216:217], s[44:45], 0, v[128:129]
	s_barrier
	ds_read_b128 v[162:165], v142 offset:16384
	ds_read_b128 v[166:169], v142 offset:17408
	ds_read_b128 v[172:175], v142 offset:18432
	ds_read_b128 v[176:179], v142 offset:19456
	ds_read_b128 v[180:183], v142 offset:20480
	ds_read_b128 v[184:187], v142 offset:21504
	ds_read_b128 v[188:191], v142 offset:22528
	ds_read_b128 v[192:195], v142 offset:23552
	global_load_lds_dwordx4 v[216:217], off
	v_lshl_add_u64 v[218:219], s[44:45], 0, v[130:131]
	s_mov_b32 m0, s33
	s_nop 0
	global_load_lds_dwordx4 v[218:219], off
	s_barrier
	s_waitcnt lgkmcnt(0)
	s_setprio 1
	v_mfma_f32_16x16x32_bf16 v[60:63], v[144:147], v[162:165], v[60:63]
	v_mfma_f32_16x16x32_bf16 v[56:59], v[154:157], v[162:165], v[56:59]
	v_mfma_f32_16x16x32_bf16 v[48:51], v[144:147], v[172:175], v[48:51]
	v_mfma_f32_16x16x32_bf16 v[40:43], v[154:157], v[172:175], v[40:43]
	v_mfma_f32_16x16x32_bf16 v[32:35], v[144:147], v[180:183], v[32:35]
	v_mfma_f32_16x16x32_bf16 v[24:27], v[154:157], v[180:183], v[24:27]
	v_mfma_f32_16x16x32_bf16 v[16:19], v[144:147], v[188:191], v[16:19]
	v_mfma_f32_16x16x32_bf16 v[8:11], v[154:157], v[188:191], v[8:11]
	v_mfma_f32_16x16x32_bf16 v[60:63], v[148:151], v[166:169], v[60:63]
	v_mfma_f32_16x16x32_bf16 v[56:59], v[158:161], v[166:169], v[56:59]
	v_mfma_f32_16x16x32_bf16 v[48:51], v[148:151], v[176:179], v[48:51]
	v_mfma_f32_16x16x32_bf16 v[40:43], v[158:161], v[176:179], v[40:43]
	v_mfma_f32_16x16x32_bf16 v[32:35], v[148:151], v[184:187], v[32:35]
	v_mfma_f32_16x16x32_bf16 v[24:27], v[158:161], v[184:187], v[24:27]
	v_mfma_f32_16x16x32_bf16 v[16:19], v[148:151], v[192:195], v[16:19]
	v_mfma_f32_16x16x32_bf16 v[8:11], v[158:161], v[192:195], v[8:11]
	s_setprio 0
	s_barrier
; #define PG8_STAGE(bufoff, gbase, voff) do { _Pragma("unroll") for (int _i = 0; _i < 2; ++_i) \
;         __builtin_amdgcn_global_load_lds((const unsigned*)((const char*)(gbase) + (voff)[_i]), (LAS unsigned*)(lds + (bufoff) + ldsw + _i * 8192), 16, 0, 0); } while (0)
; #define PG8_LDA(dst, b, h) do { _Pragma("unroll") for (int m = 0; m < 4; ++m) _Pragma("unroll") for (int k = 0; k < 2; ++k) dst[m][k] = *(const LAS bf16x8*)(lds + PG8_SA(b, h) + aoff + m * 2048 + k * 1024); } while (0)
; #define PG8_LDB(dst, b, h) do { _Pragma("unroll") for (int n = 0; n < 2; ++n) _Pragma("unroll") for (int k = 0; k < 2; ++k) dst[n][k] = *(const LAS bf16x8*)(lds + PG8_SB(b, h) + boff + n * 2048 + k * 1024); } while (0)
; #define PG8_MMA(ai, bj, At, Bt) do { __builtin_amdgcn_s_setprio(1); _Pragma("unroll") for (int m = 0; m < 4; ++m) _Pragma("unroll") for (int n = 0; n < 2; ++n) _Pragma("unroll") for (int k = 0; k < 2; ++k) \
;         acc[ai][bj][m][n] = __builtin_amdgcn_mfma_f32_16x16x32_bf16(Bt[n][k], At[m][k], acc[ai][bj][m][n], 0, 0, 0); __builtin_amdgcn_s_setprio(0); } while (0)
; #define PG8_WAIT_V(n) asm volatile("s_waitcnt vmcnt(" #n ")" ::: "memory")
; #define PG8_WAIT_L(n) asm volatile("s_waitcnt lgkmcnt(" #n ")" ::: "memory")
; #define PG8_BAR __builtin_amdgcn_s_barrier()
; #define PG8_SCHED __builtin_amdgcn_sched_barrier(0)
; template <class Epi, class Sched>
; __device__ __forceinline__ void gemm_phase(LAS unsigned char* lds, const int K, const Sched& S, const Epi& E) {
;     ...
;             PG8_STAGE(PG8_SB(0, 1), b2 + hstep, voffB);
;             PG8_WAIT_V(6); PG8_BAR; PG8_MMA(1, 1, At, B1); PG8_BAR;
;             PG8_LDB(B0, 1, 0); PG8_SCHED; PG8_LDA(At, 1, 0); PG8_STAGE(PG8_SA(0, 1), a2 + hstepA, voffA);
;             PG8_WAIT_L(8); PG8_BAR; PG8_WAIT_L(0); PG8_MMA(0, 0, At, B0); PG8_BAR; PG8_SCHED;
;             PG8_LDB(B1, 1, 1); PG8_STAGE(PG8_SB(1, 0), b3, voffB);
;             PG8_BAR; PG8_WAIT_L(0); PG8_MMA(0, 1, At, B1); PG8_BAR;
;             PG8_LDA(At, 1, 1); PG8_STAGE(PG8_SA(1, 0), a3, voffA);
	s_add_u32 s72, s42, 0x40000
	s_addc_u32 s73, s43, 0
	s_mov_b32 m0, s66
	v_lshl_add_u64 v[144:145], s[72:73], 0, v[128:129]
	global_load_lds_dwordx4 v[144:145], off
	v_lshl_add_u64 v[144:145], s[72:73], 0, v[130:131]
	s_add_i32 m0, s66, 0x2000
	s_nop 0
	global_load_lds_dwordx4 v[144:145], off
	s_waitcnt vmcnt(6)
	s_barrier
	s_setprio 1
	v_mfma_f32_16x16x32_bf16 v[52:55], v[196:199], v[162:165], v[52:55]
	v_mfma_f32_16x16x32_bf16 v[44:47], v[204:207], v[162:165], v[44:47]
	v_mfma_f32_16x16x32_bf16 v[36:39], v[196:199], v[172:175], v[36:39]
	v_mfma_f32_16x16x32_bf16 v[28:31], v[204:207], v[172:175], v[28:31]
	v_mfma_f32_16x16x32_bf16 v[20:23], v[196:199], v[180:183], v[20:23]
	v_mfma_f32_16x16x32_bf16 v[12:15], v[204:207], v[180:183], v[12:15]
	v_mfma_f32_16x16x32_bf16 v[4:7], v[196:199], v[188:191], v[4:7]
	v_mfma_f32_16x16x32_bf16 v[0:3], v[204:207], v[188:191], v[0:3]
	v_mfma_f32_16x16x32_bf16 v[52:55], v[200:203], v[166:169], v[52:55]
	v_mfma_f32_16x16x32_bf16 v[44:47], v[208:211], v[166:169], v[44:47]
	v_mfma_f32_16x16x32_bf16 v[36:39], v[200:203], v[176:179], v[36:39]
	v_mfma_f32_16x16x32_bf16 v[28:31], v[208:211], v[176:179], v[28:31]
	v_mfma_f32_16x16x32_bf16 v[20:23], v[200:203], v[184:187], v[20:23]
	v_mfma_f32_16x16x32_bf16 v[12:15], v[208:211], v[184:187], v[12:15]
	v_mfma_f32_16x16x32_bf16 v[4:7], v[200:203], v[192:195], v[4:7]
	v_mfma_f32_16x16x32_bf16 v[0:3], v[208:211], v[192:195], v[0:3]
	s_setprio 0
	s_add_i32 s71, 0, 0x18000
	v_add_u32_e32 v143, s71, v141
	s_barrier
	ds_read_b128 v[144:147], v143
	ds_read_b128 v[148:151], v143 offset:1024
	ds_read_b128 v[154:157], v143 offset:2048
	ds_read_b128 v[158:161], v143 offset:3072
	s_add_u32 s44, s44, 0x40000
	s_addc_u32 s45, s45, 0
	s_mov_b32 m0, s52
	v_lshl_add_u64 v[196:197], s[44:45], 0, v[128:129]
	ds_read_b128 v[162:165], v142 offset:32768
	ds_read_b128 v[166:169], v142 offset:33792
	ds_read_b128 v[172:175], v142 offset:34816
	ds_read_b128 v[176:179], v142 offset:35840
	ds_read_b128 v[180:183], v142 offset:36864
	ds_read_b128 v[184:187], v142 offset:37888
	ds_read_b128 v[188:191], v142 offset:38912
	ds_read_b128 v[192:195], v142 offset:39936
	global_load_lds_dwordx4 v[196:197], off
	v_lshl_add_u64 v[196:197], s[44:45], 0, v[130:131]
	s_mov_b32 m0, s53
	s_nop 0
	global_load_lds_dwordx4 v[196:197], off
	s_waitcnt lgkmcnt(8)
	s_barrier
	s_waitcnt lgkmcnt(0)
	s_setprio 1
	v_mfma_f32_16x16x32_bf16 v[124:127], v[144:147], v[162:165], v[124:127]
	v_mfma_f32_16x16x32_bf16 v[120:123], v[154:157], v[162:165], v[120:123]
	v_mfma_f32_16x16x32_bf16 v[112:115], v[144:147], v[172:175], v[112:115]
	v_mfma_f32_16x16x32_bf16 v[104:107], v[154:157], v[172:175], v[104:107]
	v_mfma_f32_16x16x32_bf16 v[96:99], v[144:147], v[180:183], v[96:99]
	v_mfma_f32_16x16x32_bf16 v[88:91], v[154:157], v[180:183], v[88:91]
	v_mfma_f32_16x16x32_bf16 v[80:83], v[144:147], v[188:191], v[80:83]
	v_mfma_f32_16x16x32_bf16 v[72:75], v[154:157], v[188:191], v[72:75]
	v_mfma_f32_16x16x32_bf16 v[124:127], v[148:151], v[166:169], v[124:127]
	v_mfma_f32_16x16x32_bf16 v[120:123], v[158:161], v[166:169], v[120:123]
	v_mfma_f32_16x16x32_bf16 v[112:115], v[148:151], v[176:179], v[112:115]
	v_mfma_f32_16x16x32_bf16 v[104:107], v[158:161], v[176:179], v[104:107]
	v_mfma_f32_16x16x32_bf16 v[96:99], v[148:151], v[184:187], v[96:99]
	v_mfma_f32_16x16x32_bf16 v[88:91], v[158:161], v[184:187], v[88:91]
	v_mfma_f32_16x16x32_bf16 v[80:83], v[148:151], v[192:195], v[80:83]
	v_mfma_f32_16x16x32_bf16 v[72:75], v[158:161], v[192:195], v[72:75]
	s_setprio 0
	s_barrier
	s_add_i32 s44, 0, 0x1c000
	s_add_i32 s45, s71, s10
	v_add_u32_e32 v143, s44, v141
	v_lshl_add_u64 v[212:213], v[212:213], 0, s[12:13]
	s_mov_b32 m0, s45
	ds_read_b128 v[196:199], v143
	ds_read_b128 v[200:203], v143 offset:1024
	ds_read_b128 v[204:207], v143 offset:2048
	ds_read_b128 v[208:211], v143 offset:3072
	global_load_lds_dwordx4 v[212:213], off
	v_lshl_add_u64 v[212:213], v[214:215], 0, s[12:13]
	s_add_i32 m0, s45, 0x2000
	s_nop 0
	global_load_lds_dwordx4 v[212:213], off
	s_barrier
	s_waitcnt lgkmcnt(0)
	s_setprio 1
	v_mfma_f32_16x16x32_bf16 v[116:119], v[196:199], v[162:165], v[116:119]
	v_mfma_f32_16x16x32_bf16 v[108:111], v[204:207], v[162:165], v[108:111]
	v_mfma_f32_16x16x32_bf16 v[100:103], v[196:199], v[172:175], v[100:103]
	v_mfma_f32_16x16x32_bf16 v[92:95], v[204:207], v[172:175], v[92:95]
	v_mfma_f32_16x16x32_bf16 v[84:87], v[196:199], v[180:183], v[84:87]
	v_mfma_f32_16x16x32_bf16 v[76:79], v[204:207], v[180:183], v[76:79]
	v_mfma_f32_16x16x32_bf16 v[68:71], v[196:199], v[188:191], v[68:71]
	v_mfma_f32_16x16x32_bf16 v[64:67], v[204:207], v[188:191], v[64:67]
	v_mfma_f32_16x16x32_bf16 v[116:119], v[200:203], v[166:169], v[116:119]
	v_mfma_f32_16x16x32_bf16 v[108:111], v[208:211], v[166:169], v[108:111]
	v_mfma_f32_16x16x32_bf16 v[100:103], v[200:203], v[176:179], v[100:103]
	v_mfma_f32_16x16x32_bf16 v[92:95], v[208:211], v[176:179], v[92:95]
	v_mfma_f32_16x16x32_bf16 v[84:87], v[200:203], v[184:187], v[84:87]
	v_mfma_f32_16x16x32_bf16 v[76:79], v[208:211], v[184:187], v[76:79]
	v_mfma_f32_16x16x32_bf16 v[68:71], v[200:203], v[192:195], v[68:71]
	v_mfma_f32_16x16x32_bf16 v[64:67], v[208:211], v[192:195], v[64:67]
	s_setprio 0
	s_mov_b32 m0, s55
	v_lshl_add_u64 v[212:213], v[216:217], 0, s[12:13]
	s_barrier
	ds_read_b128 v[162:165], v142 offset:49152
	ds_read_b128 v[166:169], v142 offset:50176
	ds_read_b128 v[172:175], v142 offset:51200
	ds_read_b128 v[176:179], v142 offset:52224
	ds_read_b128 v[180:183], v142 offset:53248
	ds_read_b128 v[184:187], v142 offset:54272
	ds_read_b128 v[188:191], v142 offset:55296
	ds_read_b128 v[192:195], v142 offset:56320
	global_load_lds_dwordx4 v[212:213], off
	v_lshl_add_u64 v[212:213], v[218:219], 0, s[12:13]
	s_mov_b32 m0, s56
	s_nop 0
	global_load_lds_dwordx4 v[212:213], off
	s_barrier
; #define PG8_STAGE(bufoff, gbase, voff) do { _Pragma("unroll") for (int _i = 0; _i < 2; ++_i) \
;         __builtin_amdgcn_global_load_lds((const unsigned*)((const char*)(gbase) + (voff)[_i]), (LAS unsigned*)(lds + (bufoff) + ldsw + _i * 8192), 16, 0, 0); } while (0)
; #define PG8_MMA(ai, bj, At, Bt) do { __builtin_amdgcn_s_setprio(1); _Pragma("unroll") for (int m = 0; m < 4; ++m) _Pragma("unroll") for (int n = 0; n < 2; ++n) _Pragma("unroll") for (int k = 0; k < 2; ++k) \
;         acc[ai][bj][m][n] = __builtin_amdgcn_mfma_f32_16x16x32_bf16(Bt[n][k], At[m][k], acc[ai][bj][m][n], 0, 0, 0); __builtin_amdgcn_s_setprio(0); } while (0)
; #define PG8_WAIT_V(n) asm volatile("s_waitcnt vmcnt(" #n ")" ::: "memory")
; #define PG8_WAIT_L(n) asm volatile("s_waitcnt lgkmcnt(" #n ")" ::: "memory")
; #define PG8_BAR __builtin_amdgcn_s_barrier()
; #define PG8_SCHED __builtin_amdgcn_sched_barrier(0)
; template <class Epi, class Sched>
; __device__ __forceinline__ void gemm_phase(LAS unsigned char* lds, const int K, const Sched& S, const Epi& E) {
;     ...
;             PG8_BAR; PG8_WAIT_L(0); PG8_MMA(1, 0, At, B0); PG8_BAR; PG8_SCHED;
;             PG8_STAGE(PG8_SB(1, 1), b3 + hstep, voffB);
;             PG8_WAIT_V(6); PG8_BAR; PG8_MMA(1, 1, At, B1); PG8_BAR;
;         }
;         if constexpr (!Epi::AFTER_DRAIN) E(acc, cur, wr, wc, fr, fq);
;         if (!has_next) break;
; #pragma unroll
;         for (int a = 0; a < 2; ++a)
; #pragma unroll
;             for (int b = 0; b < 2; ++b)
; #pragma unroll
;                 for (int m = 0; m < 4; ++m)
; #pragma unroll
;                     for (int n = 0; n < 2; ++n) acc[a][b][m][n] = (f32x4){0.f, 0.f, 0.f, 0.f};
;         cur = nxt; cA = nA; cB = nB; ++ui;
	s_waitcnt lgkmcnt(0)
	s_setprio 1
	v_mfma_f32_16x16x32_bf16 v[60:63], v[144:147], v[162:165], v[60:63]
	v_mfma_f32_16x16x32_bf16 v[56:59], v[154:157], v[162:165], v[56:59]
	v_mfma_f32_16x16x32_bf16 v[48:51], v[144:147], v[172:175], v[48:51]
	v_mfma_f32_16x16x32_bf16 v[40:43], v[154:157], v[172:175], v[40:43]
	v_mfma_f32_16x16x32_bf16 v[32:35], v[144:147], v[180:183], v[32:35]
	v_mfma_f32_16x16x32_bf16 v[24:27], v[154:157], v[180:183], v[24:27]
	v_mfma_f32_16x16x32_bf16 v[16:19], v[144:147], v[188:191], v[16:19]
	v_mfma_f32_16x16x32_bf16 v[8:11], v[154:157], v[188:191], v[8:11]
	v_mfma_f32_16x16x32_bf16 v[60:63], v[148:151], v[166:169], v[60:63]
	v_mfma_f32_16x16x32_bf16 v[56:59], v[158:161], v[166:169], v[56:59]
	v_mfma_f32_16x16x32_bf16 v[48:51], v[148:151], v[176:179], v[48:51]
	v_mfma_f32_16x16x32_bf16 v[40:43], v[158:161], v[176:179], v[40:43]
	v_mfma_f32_16x16x32_bf16 v[32:35], v[148:151], v[184:187], v[32:35]
	v_mfma_f32_16x16x32_bf16 v[24:27], v[158:161], v[184:187], v[24:27]
	v_mfma_f32_16x16x32_bf16 v[16:19], v[148:151], v[192:195], v[16:19]
	v_mfma_f32_16x16x32_bf16 v[8:11], v[158:161], v[192:195], v[8:11]
	s_setprio 0
	s_barrier
	s_add_u32 s42, s42, 0x40080
	s_addc_u32 s43, s43, 0
	s_add_i32 s44, s44, s10
	v_lshl_add_u64 v[144:145], s[42:43], 0, v[128:129]
	s_mov_b32 m0, s44
	s_nop 0
	global_load_lds_dwordx4 v[144:145], off
	v_lshl_add_u64 v[144:145], s[42:43], 0, v[130:131]
	s_add_i32 m0, s44, 0x2000
	s_nop 0
	global_load_lds_dwordx4 v[144:145], off
	s_waitcnt vmcnt(6)
	s_barrier
	s_setprio 1
	v_mfma_f32_16x16x32_bf16 v[52:55], v[196:199], v[162:165], v[52:55]
	v_mfma_f32_16x16x32_bf16 v[44:47], v[204:207], v[162:165], v[44:47]
	v_mfma_f32_16x16x32_bf16 v[36:39], v[196:199], v[172:175], v[36:39]
	v_mfma_f32_16x16x32_bf16 v[28:31], v[204:207], v[172:175], v[28:31]
	v_mfma_f32_16x16x32_bf16 v[20:23], v[196:199], v[180:183], v[20:23]
	v_mfma_f32_16x16x32_bf16 v[12:15], v[204:207], v[180:183], v[12:15]
	v_mfma_f32_16x16x32_bf16 v[4:7], v[196:199], v[188:191], v[4:7]
	v_mfma_f32_16x16x32_bf16 v[0:3], v[204:207], v[188:191], v[0:3]
	v_mfma_f32_16x16x32_bf16 v[52:55], v[200:203], v[166:169], v[52:55]
	v_mfma_f32_16x16x32_bf16 v[44:47], v[208:211], v[166:169], v[44:47]
	v_mfma_f32_16x16x32_bf16 v[36:39], v[200:203], v[176:179], v[36:39]
	v_mfma_f32_16x16x32_bf16 v[28:31], v[208:211], v[176:179], v[28:31]
	v_mfma_f32_16x16x32_bf16 v[20:23], v[200:203], v[184:187], v[20:23]
	v_mfma_f32_16x16x32_bf16 v[12:15], v[208:211], v[184:187], v[12:15]
	v_mfma_f32_16x16x32_bf16 v[4:7], v[200:203], v[192:195], v[4:7]
	v_mfma_f32_16x16x32_bf16 v[0:3], v[208:211], v[192:195], v[0:3]
	s_setprio 0
	s_add_i32 s70, s70, 2
	s_add_u32 s40, s40, 0x100
	s_addc_u32 s41, s41, 0
	s_cmp_gt_u32 s70, 13
	s_barrier
	s_cbranch_scc0 .LBB0_575
	s_add_u32 s40, s15, 0xffffff00
	s_addc_u32 s41, s69, -1
	s_andn2_b64 vcc, exec, s[26:27]
	s_cbranch_vccnz .LBB0_578
	v_mov_b32_e32 v0, 0
	s_mov_b32 s6, s14
	s_mov_b32 s8, s67
	s_mov_b64 s[0:1], s[38:39]
	s_mov_b32 s58, s68
	v_mov_b32_e32 v1, v0
	v_mov_b32_e32 v2, v0
	v_mov_b32_e32 v3, v0
	v_mov_b32_e32 v4, v0
	v_mov_b32_e32 v5, v0
	v_mov_b32_e32 v6, v0
	v_mov_b32_e32 v7, v0
	v_mov_b32_e32 v12, v0
	v_mov_b32_e32 v13, v0
	v_mov_b32_e32 v14, v0
	v_mov_b32_e32 v15, v0
	v_mov_b32_e32 v20, v0
	v_mov_b32_e32 v21, v0
	v_mov_b32_e32 v22, v0
	v_mov_b32_e32 v23, v0
	v_mov_b32_e32 v28, v0
	v_mov_b32_e32 v29, v0
	v_mov_b32_e32 v30, v0
	v_mov_b32_e32 v31, v0
	v_mov_b32_e32 v36, v0
	v_mov_b32_e32 v37, v0
	v_mov_b32_e32 v38, v0
	v_mov_b32_e32 v39, v0
	v_mov_b32_e32 v44, v0
	v_mov_b32_e32 v45, v0
	v_mov_b32_e32 v46, v0
	v_mov_b32_e32 v47, v0
	v_mov_b32_e32 v52, v0
	v_mov_b32_e32 v53, v0
	v_mov_b32_e32 v54, v0
	v_mov_b32_e32 v55, v0
	v_mov_b32_e32 v8, v0
	v_mov_b32_e32 v9, v0
	v_mov_b32_e32 v10, v0
	v_mov_b32_e32 v11, v0
	v_mov_b32_e32 v16, v0
	v_mov_b32_e32 v17, v0
	v_mov_b32_e32 v18, v0
	v_mov_b32_e32 v19, v0
	v_mov_b32_e32 v24, v0
	v_mov_b32_e32 v25, v0
	v_mov_b32_e32 v26, v0
	v_mov_b32_e32 v27, v0
	v_mov_b32_e32 v32, v0
	v_mov_b32_e32 v33, v0
	v_mov_b32_e32 v34, v0
	v_mov_b32_e32 v35, v0
	v_mov_b32_e32 v40, v0
	v_mov_b32_e32 v41, v0
	v_mov_b32_e32 v42, v0
	v_mov_b32_e32 v43, v0
	v_mov_b32_e32 v48, v0
	v_mov_b32_e32 v49, v0
	v_mov_b32_e32 v50, v0
	v_mov_b32_e32 v51, v0
	v_mov_b32_e32 v56, v0
	v_mov_b32_e32 v57, v0
	v_mov_b32_e32 v58, v0
	v_mov_b32_e32 v59, v0
	v_mov_b32_e32 v60, v0
	v_mov_b32_e32 v61, v0
	v_mov_b32_e32 v62, v0
	v_mov_b32_e32 v63, v0
	v_mov_b32_e32 v64, v0
	v_mov_b32_e32 v65, v0
	v_mov_b32_e32 v66, v0
	v_mov_b32_e32 v67, v0
	v_mov_b32_e32 v68, v0
	v_mov_b32_e32 v69, v0
	v_mov_b32_e32 v70, v0
	v_mov_b32_e32 v71, v0
	v_mov_b32_e32 v76, v0
	v_mov_b32_e32 v77, v0
	v_mov_b32_e32 v78, v0
	v_mov_b32_e32 v79, v0
	v_mov_b32_e32 v84, v0
	v_mov_b32_e32 v85, v0
	v_mov_b32_e32 v86, v0
	v_mov_b32_e32 v87, v0
	v_mov_b32_e32 v92, v0
	v_mov_b32_e32 v93, v0
	v_mov_b32_e32 v94, v0
	v_mov_b32_e32 v95, v0
	v_mov_b32_e32 v100, v0
	v_mov_b32_e32 v101, v0
	v_mov_b32_e32 v102, v0
	v_mov_b32_e32 v103, v0
	v_mov_b32_e32 v108, v0
	v_mov_b32_e32 v109, v0
	v_mov_b32_e32 v110, v0
	v_mov_b32_e32 v111, v0
	v_mov_b32_e32 v116, v0
	v_mov_b32_e32 v117, v0
	v_mov_b32_e32 v118, v0
	v_mov_b32_e32 v119, v0
	v_mov_b32_e32 v72, v0
	v_mov_b32_e32 v73, v0
	v_mov_b32_e32 v74, v0
	v_mov_b32_e32 v75, v0
	v_mov_b32_e32 v80, v0
	v_mov_b32_e32 v81, v0
	v_mov_b32_e32 v82, v0
	v_mov_b32_e32 v83, v0
	v_mov_b32_e32 v88, v0
	v_mov_b32_e32 v89, v0
	v_mov_b32_e32 v90, v0
	v_mov_b32_e32 v91, v0
	v_mov_b32_e32 v96, v0
	v_mov_b32_e32 v97, v0
	v_mov_b32_e32 v98, v0
	v_mov_b32_e32 v99, v0
	v_mov_b32_e32 v104, v0
	v_mov_b32_e32 v105, v0
	v_mov_b32_e32 v106, v0
	v_mov_b32_e32 v107, v0
	v_mov_b32_e32 v112, v0
	v_mov_b32_e32 v113, v0
	v_mov_b32_e32 v114, v0
	v_mov_b32_e32 v115, v0
	v_mov_b32_e32 v120, v0
	v_mov_b32_e32 v121, v0
	v_mov_b32_e32 v122, v0
	v_mov_b32_e32 v123, v0
	v_mov_b32_e32 v124, v0
	v_mov_b32_e32 v125, v0
	v_mov_b32_e32 v126, v0
	v_mov_b32_e32 v127, v0
	s_andn2_b64 vcc, exec, s[16:17]
	s_cbranch_vccnz .LBB0_579
	s_branch .LBB0_580

; #define PG8_STAGE(bufoff, gbase, voff) do { _Pragma("unroll") for (int _i = 0; _i < 2; ++_i) \
;         __builtin_amdgcn_global_load_lds((const unsigned*)((const char*)(gbase) + (voff)[_i]), (LAS unsigned*)(lds + (bufoff) + ldsw + _i * 8192), 16, 0, 0); } while (0)
; #define PG8_LDA(dst, b, h) do { _Pragma("unroll") for (int m = 0; m < 4; ++m) _Pragma("unroll") for (int k = 0; k < 2; ++k) dst[m][k] = *(const LAS bf16x8*)(lds + PG8_SA(b, h) + aoff + m * 2048 + k * 1024); } while (0)
; #define PG8_LDB(dst, b, h) do { _Pragma("unroll") for (int n = 0; n < 2; ++n) _Pragma("unroll") for (int k = 0; k < 2; ++k) dst[n][k] = *(const LAS bf16x8*)(lds + PG8_SB(b, h) + boff + n * 2048 + k * 1024); } while (0)
; #define PG8_MMA(ai, bj, At, Bt) do { __builtin_amdgcn_s_setprio(1); _Pragma("unroll") for (int m = 0; m < 4; ++m) _Pragma("unroll") for (int n = 0; n < 2; ++n) _Pragma("unroll") for (int k = 0; k < 2; ++k) \
;         acc[ai][bj][m][n] = __builtin_amdgcn_mfma_f32_16x16x32_bf16(Bt[n][k], At[m][k], acc[ai][bj][m][n], 0, 0, 0); __builtin_amdgcn_s_setprio(0); } while (0)
; #define PG8_WAIT_V(n) asm volatile("s_waitcnt vmcnt(" #n ")" ::: "memory")
; #define PG8_WAIT_L(n) asm volatile("s_waitcnt lgkmcnt(" #n ")" ::: "memory")
; #define PG8_BAR __builtin_amdgcn_s_barrier()
; #define PG8_SCHED __builtin_amdgcn_sched_barrier(0)
; template <class Epi, class Sched>
; __device__ __forceinline__ void gemm_phase(LAS unsigned char* lds, const int K, const Sched& S, const Epi& E) {
;     ...
;             PG8_LDB(B0, 0, 0); PG8_SCHED; PG8_LDA(At, 0, 0); PG8_STAGE(PG8_SA(1, 1), a1 + hstepA, voffA);
;             PG8_WAIT_L(8); PG8_BAR; PG8_WAIT_L(0); PG8_MMA(0, 0, At, B0); PG8_BAR; PG8_SCHED;
;             PG8_LDB(B1, 0, 1); PG8_STAGE(PG8_SB(0, 0), b2, voffB);
;             PG8_BAR; PG8_WAIT_L(0); PG8_MMA(0, 1, At, B1); PG8_BAR;
;             PG8_LDA(At, 0, 1); PG8_STAGE(PG8_SA(0, 0), a2, voffA);
;             PG8_BAR; PG8_WAIT_L(0); PG8_MMA(1, 0, At, B0); PG8_BAR; PG8_SCHED;
;             PG8_STAGE(PG8_SB(0, 1), b2 + hstep, voffB);
;             PG8_WAIT_V(6); PG8_BAR; PG8_MMA(1, 1, At, B1); PG8_BAR;
.Lpeel_p7:
	ds_read_b128 v[128:131], v158
	ds_read_b128 v[132:135], v158 offset:1024
	ds_read_b128 v[148:151], v158 offset:2048
	ds_read_b128 v[162:165], v158 offset:3072
	s_add_u32 s68, s12, 0x100
	s_addc_u32 s69, s13, 0
	s_cmp_eq_u32 s49, 12
	s_cselect_b32 s73, s63, s69
	s_cselect_b32 s72, s62, s68
	s_cselect_b32 s71, s65, s33
	s_cselect_b32 s70, s64, s11
	v_lshl_add_u64 v[200:201], s[12:13], 0, v[144:145]
	s_add_i32 m0, s67, 0xc000
	ds_read_b128 v[166:169], v159
	ds_read_b128 v[172:175], v159 offset:1024
	ds_read_b128 v[176:179], v159 offset:2048
	ds_read_b128 v[180:183], v159 offset:3072
	ds_read_b128 v[184:187], v159 offset:4096
	ds_read_b128 v[188:191], v159 offset:5120
	ds_read_b128 v[192:195], v159 offset:6144
	ds_read_b128 v[196:199], v159 offset:7168
	global_load_lds_dwordx4 v[200:201], off
	v_lshl_add_u64 v[200:201], s[12:13], 0, v[146:147]
	s_add_i32 m0, s67, 0xe000
	s_nop 0
	global_load_lds_dwordx4 v[200:201], off
	s_waitcnt lgkmcnt(8)
	s_barrier
	s_waitcnt lgkmcnt(0)
	s_setprio 1
	v_mfma_f32_16x16x32_bf16 v[84:87], v[128:131], v[166:169], 0
	v_mfma_f32_16x16x32_bf16 v[76:79], v[148:151], v[166:169], 0
	v_mfma_f32_16x16x32_bf16 v[124:127], v[128:131], v[176:179], 0
	v_mfma_f32_16x16x32_bf16 v[72:75], v[148:151], v[176:179], 0
	v_mfma_f32_16x16x32_bf16 v[120:123], v[128:131], v[184:187], 0
	v_mfma_f32_16x16x32_bf16 v[96:99], v[148:151], v[184:187], 0
	v_mfma_f32_16x16x32_bf16 v[116:119], v[128:131], v[192:195], 0
	v_mfma_f32_16x16x32_bf16 v[92:95], v[148:151], v[192:195], 0
	v_mfma_f32_16x16x32_bf16 v[84:87], v[132:135], v[172:175], v[84:87]
	v_mfma_f32_16x16x32_bf16 v[76:79], v[162:165], v[172:175], v[76:79]
	v_mfma_f32_16x16x32_bf16 v[124:127], v[132:135], v[180:183], v[124:127]
	v_mfma_f32_16x16x32_bf16 v[72:75], v[162:165], v[180:183], v[72:75]
	v_mfma_f32_16x16x32_bf16 v[120:123], v[132:135], v[188:191], v[120:123]
	v_mfma_f32_16x16x32_bf16 v[96:99], v[162:165], v[188:191], v[96:99]
	v_mfma_f32_16x16x32_bf16 v[116:119], v[132:135], v[196:199], v[116:119]
	v_mfma_f32_16x16x32_bf16 v[92:95], v[162:165], v[196:199], v[92:95]
	s_setprio 0
	s_barrier
	s_add_i32 s12, s88, s78
	v_lshl_add_u64 v[216:217], s[70:71], 0, v[138:139]
	s_mov_b32 m0, s12
	ds_read_b128 v[200:203], v160
	ds_read_b128 v[204:207], v160 offset:1024
	ds_read_b128 v[208:211], v160 offset:2048
	ds_read_b128 v[212:215], v160 offset:3072
	global_load_lds_dwordx4 v[216:217], off
	v_lshl_add_u64 v[218:219], s[70:71], 0, v[142:143]
	s_add_i32 m0, s12, 0x2000
	s_nop 0
	global_load_lds_dwordx4 v[218:219], off
	s_barrier
	s_waitcnt lgkmcnt(0)
	s_setprio 1
	v_mfma_f32_16x16x32_bf16 v[60:63], v[200:203], v[166:169], 0
	v_mfma_f32_16x16x32_bf16 v[16:19], v[208:211], v[166:169], 0
	v_mfma_f32_16x16x32_bf16 v[56:59], v[200:203], v[176:179], 0
	v_mfma_f32_16x16x32_bf16 v[12:15], v[208:211], v[176:179], 0
	v_mfma_f32_16x16x32_bf16 v[52:55], v[200:203], v[184:187], 0
	v_mfma_f32_16x16x32_bf16 v[28:31], v[208:211], v[184:187], 0
	v_mfma_f32_16x16x32_bf16 v[48:51], v[200:203], v[192:195], 0
	v_mfma_f32_16x16x32_bf16 v[24:27], v[208:211], v[192:195], 0
	v_mfma_f32_16x16x32_bf16 v[60:63], v[204:207], v[172:175], v[60:63]
	v_mfma_f32_16x16x32_bf16 v[16:19], v[212:215], v[172:175], v[16:19]
	v_mfma_f32_16x16x32_bf16 v[56:59], v[204:207], v[180:183], v[56:59]
	v_mfma_f32_16x16x32_bf16 v[12:15], v[212:215], v[180:183], v[12:15]
	v_mfma_f32_16x16x32_bf16 v[52:55], v[204:207], v[188:191], v[52:55]
	v_mfma_f32_16x16x32_bf16 v[28:31], v[212:215], v[188:191], v[28:31]
	v_mfma_f32_16x16x32_bf16 v[48:51], v[204:207], v[196:199], v[48:51]
	v_mfma_f32_16x16x32_bf16 v[24:27], v[212:215], v[196:199], v[24:27]
	s_setprio 0
	s_mov_b32 m0, s67
	v_lshl_add_u64 v[220:221], s[72:73], 0, v[136:137]
	s_barrier
	ds_read_b128 v[166:169], v159 offset:16384
	ds_read_b128 v[172:175], v159 offset:17408
	ds_read_b128 v[176:179], v159 offset:18432
	ds_read_b128 v[180:183], v159 offset:19456
	ds_read_b128 v[184:187], v159 offset:20480
	ds_read_b128 v[188:191], v159 offset:21504
	ds_read_b128 v[192:195], v159 offset:22528
	ds_read_b128 v[196:199], v159 offset:23552
	global_load_lds_dwordx4 v[220:221], off
	v_lshl_add_u64 v[222:223], s[72:73], 0, v[140:141]
	s_mov_b32 m0, s80
	s_nop 0
	global_load_lds_dwordx4 v[222:223], off
	s_barrier
	s_waitcnt lgkmcnt(0)
	s_setprio 1
	v_mfma_f32_16x16x32_bf16 v[112:115], v[128:131], v[166:169], 0
	v_mfma_f32_16x16x32_bf16 v[88:91], v[148:151], v[166:169], 0
	v_mfma_f32_16x16x32_bf16 v[104:107], v[128:131], v[176:179], 0
	v_mfma_f32_16x16x32_bf16 v[80:83], v[148:151], v[176:179], 0
	v_mfma_f32_16x16x32_bf16 v[100:103], v[128:131], v[184:187], 0
	v_mfma_f32_16x16x32_bf16 v[64:67], v[148:151], v[184:187], 0
	v_mfma_f32_16x16x32_bf16 v[108:111], v[128:131], v[192:195], 0
	v_mfma_f32_16x16x32_bf16 v[68:71], v[148:151], v[192:195], 0
	v_mfma_f32_16x16x32_bf16 v[112:115], v[132:135], v[172:175], v[112:115]
	v_mfma_f32_16x16x32_bf16 v[88:91], v[162:165], v[172:175], v[88:91]
	v_mfma_f32_16x16x32_bf16 v[104:107], v[132:135], v[180:183], v[104:107]
	v_mfma_f32_16x16x32_bf16 v[80:83], v[162:165], v[180:183], v[80:83]
	v_mfma_f32_16x16x32_bf16 v[100:103], v[132:135], v[188:191], v[100:103]
	v_mfma_f32_16x16x32_bf16 v[64:67], v[162:165], v[188:191], v[64:67]
	v_mfma_f32_16x16x32_bf16 v[108:111], v[132:135], v[196:199], v[108:111]
	v_mfma_f32_16x16x32_bf16 v[68:71], v[162:165], v[196:199], v[68:71]
	s_setprio 0
	s_barrier
	s_add_u32 s12, s70, 0x40000
	s_addc_u32 s13, s71, 0
	s_add_i32 s52, s89, s78
	v_lshl_add_u64 v[128:129], s[12:13], 0, v[138:139]
	s_mov_b32 m0, s52
	s_nop 0
	global_load_lds_dwordx4 v[128:129], off
	v_lshl_add_u64 v[128:129], s[12:13], 0, v[142:143]
	s_add_i32 m0, s52, 0x2000
	s_nop 0
	global_load_lds_dwordx4 v[128:129], off
	s_waitcnt vmcnt(6)
	s_barrier
; #define PG8_STAGE(bufoff, gbase, voff) do { _Pragma("unroll") for (int _i = 0; _i < 2; ++_i) \
;         __builtin_amdgcn_global_load_lds((const unsigned*)((const char*)(gbase) + (voff)[_i]), (LAS unsigned*)(lds + (bufoff) + ldsw + _i * 8192), 16, 0, 0); } while (0)
; #define PG8_LDA(dst, b, h) do { _Pragma("unroll") for (int m = 0; m < 4; ++m) _Pragma("unroll") for (int k = 0; k < 2; ++k) dst[m][k] = *(const LAS bf16x8*)(lds + PG8_SA(b, h) + aoff + m * 2048 + k * 1024); } while (0)
; #define PG8_LDB(dst, b, h) do { _Pragma("unroll") for (int n = 0; n < 2; ++n) _Pragma("unroll") for (int k = 0; k < 2; ++k) dst[n][k] = *(const LAS bf16x8*)(lds + PG8_SB(b, h) + boff + n * 2048 + k * 1024); } while (0)
; #define PG8_MMA(ai, bj, At, Bt) do { __builtin_amdgcn_s_setprio(1); _Pragma("unroll") for (int m = 0; m < 4; ++m) _Pragma("unroll") for (int n = 0; n < 2; ++n) _Pragma("unroll") for (int k = 0; k < 2; ++k) \
;         acc[ai][bj][m][n] = __builtin_amdgcn_mfma_f32_16x16x32_bf16(Bt[n][k], At[m][k], acc[ai][bj][m][n], 0, 0, 0); __builtin_amdgcn_s_setprio(0); } while (0)
; #define PG8_WAIT_V(n) asm volatile("s_waitcnt vmcnt(" #n ")" ::: "memory")
; #define PG8_WAIT_L(n) asm volatile("s_waitcnt lgkmcnt(" #n ")" ::: "memory")
; #define PG8_BAR __builtin_amdgcn_s_barrier()
; #define PG8_SCHED __builtin_amdgcn_sched_barrier(0)
; template <class Epi, class Sched>
; __device__ __forceinline__ void gemm_phase(LAS unsigned char* lds, const int K, const Sched& S, const Epi& E) {
;     ...
;             PG8_WAIT_V(6); PG8_BAR; PG8_MMA(1, 1, At, B1); PG8_BAR;
;             PG8_LDB(B0, 1, 0); PG8_SCHED; PG8_LDA(At, 1, 0); PG8_STAGE(PG8_SA(0, 1), a2 + hstepA, voffA);
;             PG8_WAIT_L(8); PG8_BAR; PG8_WAIT_L(0); PG8_MMA(0, 0, At, B0); PG8_BAR; PG8_SCHED;
;             PG8_LDB(B1, 1, 1); PG8_STAGE(PG8_SB(1, 0), b3, voffB);
;             PG8_BAR; PG8_WAIT_L(0); PG8_MMA(0, 1, At, B1); PG8_BAR;
;             PG8_LDA(At, 1, 1); PG8_STAGE(PG8_SA(1, 0), a3, voffA);
;             PG8_BAR; PG8_WAIT_L(0); PG8_MMA(1, 0, At, B0); PG8_BAR; PG8_SCHED;
	s_setprio 1
	v_mfma_f32_16x16x32_bf16 v[44:47], v[200:203], v[166:169], 0
	v_mfma_f32_16x16x32_bf16 v[20:23], v[208:211], v[166:169], 0
	v_mfma_f32_16x16x32_bf16 v[40:43], v[200:203], v[176:179], 0
	v_mfma_f32_16x16x32_bf16 v[8:11], v[208:211], v[176:179], 0
	v_mfma_f32_16x16x32_bf16 v[36:39], v[200:203], v[184:187], 0
	v_mfma_f32_16x16x32_bf16 v[0:3], v[208:211], v[184:187], 0
	v_mfma_f32_16x16x32_bf16 v[32:35], v[200:203], v[192:195], 0
	v_mfma_f32_16x16x32_bf16 v[4:7], v[208:211], v[192:195], 0
	v_mfma_f32_16x16x32_bf16 v[44:47], v[204:207], v[172:175], v[44:47]
	v_mfma_f32_16x16x32_bf16 v[20:23], v[212:215], v[172:175], v[20:23]
	v_mfma_f32_16x16x32_bf16 v[40:43], v[204:207], v[180:183], v[40:43]
	v_mfma_f32_16x16x32_bf16 v[8:11], v[212:215], v[180:183], v[8:11]
	v_mfma_f32_16x16x32_bf16 v[36:39], v[204:207], v[188:191], v[36:39]
	v_mfma_f32_16x16x32_bf16 v[0:3], v[212:215], v[188:191], v[0:3]
	v_mfma_f32_16x16x32_bf16 v[32:35], v[204:207], v[196:199], v[32:35]
	v_mfma_f32_16x16x32_bf16 v[4:7], v[212:215], v[196:199], v[4:7]
	s_setprio 0
	s_add_i32 s52, 0, 0x18000
	v_add_u32_e32 v161, s52, v156
	s_barrier
	ds_read_b128 v[128:131], v161
	ds_read_b128 v[132:135], v161 offset:1024
	ds_read_b128 v[148:151], v161 offset:2048
	ds_read_b128 v[162:165], v161 offset:3072
	s_add_u32 s12, s72, 0x20000
	s_addc_u32 s13, s73, 0
	s_mov_b32 m0, s81
	v_lshl_add_u64 v[200:201], s[12:13], 0, v[136:137]
	ds_read_b128 v[166:169], v159 offset:32768
	ds_read_b128 v[172:175], v159 offset:33792
	ds_read_b128 v[176:179], v159 offset:34816
	ds_read_b128 v[180:183], v159 offset:35840
	ds_read_b128 v[184:187], v159 offset:36864
	ds_read_b128 v[188:191], v159 offset:37888
	ds_read_b128 v[192:195], v159 offset:38912
	ds_read_b128 v[196:199], v159 offset:39936
	global_load_lds_dwordx4 v[200:201], off
	v_lshl_add_u64 v[200:201], s[12:13], 0, v[140:141]
	s_mov_b32 m0, s82
	s_nop 0
	global_load_lds_dwordx4 v[200:201], off
	s_waitcnt lgkmcnt(8)
	s_barrier
	s_waitcnt lgkmcnt(0)
	s_setprio 1
	v_mfma_f32_16x16x32_bf16 v[84:87], v[128:131], v[166:169], v[84:87]
	v_mfma_f32_16x16x32_bf16 v[76:79], v[148:151], v[166:169], v[76:79]
	v_mfma_f32_16x16x32_bf16 v[124:127], v[128:131], v[176:179], v[124:127]
	v_mfma_f32_16x16x32_bf16 v[72:75], v[148:151], v[176:179], v[72:75]
	v_mfma_f32_16x16x32_bf16 v[120:123], v[128:131], v[184:187], v[120:123]
	v_mfma_f32_16x16x32_bf16 v[96:99], v[148:151], v[184:187], v[96:99]
	v_mfma_f32_16x16x32_bf16 v[116:119], v[128:131], v[192:195], v[116:119]
	v_mfma_f32_16x16x32_bf16 v[92:95], v[148:151], v[192:195], v[92:95]
	v_mfma_f32_16x16x32_bf16 v[84:87], v[132:135], v[172:175], v[84:87]
	v_mfma_f32_16x16x32_bf16 v[76:79], v[162:165], v[172:175], v[76:79]
	v_mfma_f32_16x16x32_bf16 v[124:127], v[132:135], v[180:183], v[124:127]
	v_mfma_f32_16x16x32_bf16 v[72:75], v[162:165], v[180:183], v[72:75]
	v_mfma_f32_16x16x32_bf16 v[120:123], v[132:135], v[188:191], v[120:123]
	v_mfma_f32_16x16x32_bf16 v[96:99], v[162:165], v[188:191], v[96:99]
	v_mfma_f32_16x16x32_bf16 v[116:119], v[132:135], v[196:199], v[116:119]
	v_mfma_f32_16x16x32_bf16 v[92:95], v[162:165], v[196:199], v[92:95]
	s_setprio 0
	s_barrier
	s_add_i32 s53, 0, 0x1c000
	s_add_i32 s12, s52, s78
	v_add_u32_e32 v161, s53, v156
	v_lshl_add_u64 v[216:217], v[216:217], 0, s[38:39]
	s_mov_b32 m0, s12
	ds_read_b128 v[200:203], v161
	ds_read_b128 v[204:207], v161 offset:1024
	ds_read_b128 v[208:211], v161 offset:2048
	ds_read_b128 v[212:215], v161 offset:3072
	global_load_lds_dwordx4 v[216:217], off
	v_lshl_add_u64 v[216:217], v[218:219], 0, s[38:39]
	s_add_i32 m0, s12, 0x2000
	s_nop 0
	global_load_lds_dwordx4 v[216:217], off
	s_barrier
	s_waitcnt lgkmcnt(0)
	s_setprio 1
	v_mfma_f32_16x16x32_bf16 v[60:63], v[200:203], v[166:169], v[60:63]
	v_mfma_f32_16x16x32_bf16 v[16:19], v[208:211], v[166:169], v[16:19]
	v_mfma_f32_16x16x32_bf16 v[56:59], v[200:203], v[176:179], v[56:59]
	v_mfma_f32_16x16x32_bf16 v[12:15], v[208:211], v[176:179], v[12:15]
	v_mfma_f32_16x16x32_bf16 v[52:55], v[200:203], v[184:187], v[52:55]
	v_mfma_f32_16x16x32_bf16 v[28:31], v[208:211], v[184:187], v[28:31]
	v_mfma_f32_16x16x32_bf16 v[48:51], v[200:203], v[192:195], v[48:51]
	v_mfma_f32_16x16x32_bf16 v[24:27], v[208:211], v[192:195], v[24:27]
	v_mfma_f32_16x16x32_bf16 v[60:63], v[204:207], v[172:175], v[60:63]
	v_mfma_f32_16x16x32_bf16 v[16:19], v[212:215], v[172:175], v[16:19]
	v_mfma_f32_16x16x32_bf16 v[56:59], v[204:207], v[180:183], v[56:59]
	v_mfma_f32_16x16x32_bf16 v[12:15], v[212:215], v[180:183], v[12:15]
	v_mfma_f32_16x16x32_bf16 v[52:55], v[204:207], v[188:191], v[52:55]
	v_mfma_f32_16x16x32_bf16 v[28:31], v[212:215], v[188:191], v[28:31]
	v_mfma_f32_16x16x32_bf16 v[48:51], v[204:207], v[196:199], v[48:51]
	v_mfma_f32_16x16x32_bf16 v[24:27], v[212:215], v[196:199], v[24:27]
	s_setprio 0
	s_mov_b32 m0, s84
	v_lshl_add_u64 v[216:217], v[220:221], 0, s[38:39]
	s_barrier
	ds_read_b128 v[166:169], v159 offset:49152
	ds_read_b128 v[172:175], v159 offset:50176
	ds_read_b128 v[176:179], v159 offset:51200
	ds_read_b128 v[180:183], v159 offset:52224
	ds_read_b128 v[184:187], v159 offset:53248
	ds_read_b128 v[188:191], v159 offset:54272
	ds_read_b128 v[192:195], v159 offset:55296
	ds_read_b128 v[196:199], v159 offset:56320
	global_load_lds_dwordx4 v[216:217], off
	v_lshl_add_u64 v[216:217], v[222:223], 0, s[38:39]
	s_mov_b32 m0, s85
	s_nop 0
	global_load_lds_dwordx4 v[216:217], off
	s_barrier
; #define PG8_STAGE(bufoff, gbase, voff) do { _Pragma("unroll") for (int _i = 0; _i < 2; ++_i) \
;         __builtin_amdgcn_global_load_lds((const unsigned*)((const char*)(gbase) + (voff)[_i]), (LAS unsigned*)(lds + (bufoff) + ldsw + _i * 8192), 16, 0, 0); } while (0)
; #define PG8_LDA(dst, b, h) do { _Pragma("unroll") for (int m = 0; m < 4; ++m) _Pragma("unroll") for (int k = 0; k < 2; ++k) dst[m][k] = *(const LAS bf16x8*)(lds + PG8_SA(b, h) + aoff + m * 2048 + k * 1024); } while (0)
; #define PG8_LDB(dst, b, h) do { _Pragma("unroll") for (int n = 0; n < 2; ++n) _Pragma("unroll") for (int k = 0; k < 2; ++k) dst[n][k] = *(const LAS bf16x8*)(lds + PG8_SB(b, h) + boff + n * 2048 + k * 1024); } while (0)
; #define PG8_MMA(ai, bj, At, Bt) do { __builtin_amdgcn_s_setprio(1); _Pragma("unroll") for (int m = 0; m < 4; ++m) _Pragma("unroll") for (int n = 0; n < 2; ++n) _Pragma("unroll") for (int k = 0; k < 2; ++k) \
;         acc[ai][bj][m][n] = __builtin_amdgcn_mfma_f32_16x16x32_bf16(Bt[n][k], At[m][k], acc[ai][bj][m][n], 0, 0, 0); __builtin_amdgcn_s_setprio(0); } while (0)
; #define PG8_WAIT_V(n) asm volatile("s_waitcnt vmcnt(" #n ")" ::: "memory")
; #define PG8_WAIT_L(n) asm volatile("s_waitcnt lgkmcnt(" #n ")" ::: "memory")
; #define PG8_BAR __builtin_amdgcn_s_barrier()
; #define PG8_SCHED __builtin_amdgcn_sched_barrier(0)
; template <class Epi, class Sched>
; __device__ __forceinline__ void gemm_phase(LAS unsigned char* lds, const int K, const Sched& S, const Epi& E) {
;     ...
;             PG8_LDB(B0, 0, 0); PG8_SCHED; PG8_LDA(At, 0, 0); PG8_STAGE(PG8_SA(1, 1), a1 + hstepA, voffA);
;             PG8_WAIT_L(8); PG8_BAR; PG8_WAIT_L(0); PG8_MMA(0, 0, At, B0); PG8_BAR; PG8_SCHED;
;             PG8_LDB(B1, 0, 1); PG8_STAGE(PG8_SB(0, 0), b2, voffB);
;     ...
;             PG8_BAR; PG8_WAIT_L(0); PG8_MMA(1, 0, At, B0); PG8_BAR; PG8_SCHED;
;             PG8_STAGE(PG8_SB(1, 1), b3 + hstep, voffB);
;             PG8_WAIT_V(6); PG8_BAR; PG8_MMA(1, 1, At, B1); PG8_BAR;
	s_waitcnt lgkmcnt(0)
	s_setprio 1
	v_mfma_f32_16x16x32_bf16 v[112:115], v[128:131], v[166:169], v[112:115]
	v_mfma_f32_16x16x32_bf16 v[88:91], v[148:151], v[166:169], v[88:91]
	v_mfma_f32_16x16x32_bf16 v[104:107], v[128:131], v[176:179], v[104:107]
	v_mfma_f32_16x16x32_bf16 v[80:83], v[148:151], v[176:179], v[80:83]
	v_mfma_f32_16x16x32_bf16 v[100:103], v[128:131], v[184:187], v[100:103]
	v_mfma_f32_16x16x32_bf16 v[64:67], v[148:151], v[184:187], v[64:67]
	v_mfma_f32_16x16x32_bf16 v[108:111], v[128:131], v[192:195], v[108:111]
	v_mfma_f32_16x16x32_bf16 v[68:71], v[148:151], v[192:195], v[68:71]
	v_mfma_f32_16x16x32_bf16 v[112:115], v[132:135], v[172:175], v[112:115]
	v_mfma_f32_16x16x32_bf16 v[88:91], v[162:165], v[172:175], v[88:91]
	v_mfma_f32_16x16x32_bf16 v[104:107], v[132:135], v[180:183], v[104:107]
	v_mfma_f32_16x16x32_bf16 v[80:83], v[162:165], v[180:183], v[80:83]
	v_mfma_f32_16x16x32_bf16 v[100:103], v[132:135], v[188:191], v[100:103]
	v_mfma_f32_16x16x32_bf16 v[64:67], v[162:165], v[188:191], v[64:67]
	v_mfma_f32_16x16x32_bf16 v[108:111], v[132:135], v[196:199], v[108:111]
	v_mfma_f32_16x16x32_bf16 v[68:71], v[162:165], v[196:199], v[68:71]
	s_setprio 0
	s_barrier
	s_add_u32 s12, s70, 0x40080
	s_addc_u32 s13, s71, 0
	s_add_i32 s52, s53, s78
	v_lshl_add_u64 v[128:129], s[12:13], 0, v[138:139]
	s_mov_b32 m0, s52
	s_nop 0
	global_load_lds_dwordx4 v[128:129], off
	v_lshl_add_u64 v[128:129], s[12:13], 0, v[142:143]
	s_add_i32 m0, s52, 0x2000
	s_nop 0
	global_load_lds_dwordx4 v[128:129], off
	s_waitcnt vmcnt(6)
	s_barrier
	s_setprio 1
	v_mfma_f32_16x16x32_bf16 v[44:47], v[200:203], v[166:169], v[44:47]
	v_mfma_f32_16x16x32_bf16 v[20:23], v[208:211], v[166:169], v[20:23]
	v_mfma_f32_16x16x32_bf16 v[40:43], v[200:203], v[176:179], v[40:43]
	v_mfma_f32_16x16x32_bf16 v[8:11], v[208:211], v[176:179], v[8:11]
	v_mfma_f32_16x16x32_bf16 v[36:39], v[200:203], v[184:187], v[36:39]
	v_mfma_f32_16x16x32_bf16 v[0:3], v[208:211], v[184:187], v[0:3]
	v_mfma_f32_16x16x32_bf16 v[32:35], v[200:203], v[192:195], v[32:35]
	v_mfma_f32_16x16x32_bf16 v[4:7], v[208:211], v[192:195], v[4:7]
	v_mfma_f32_16x16x32_bf16 v[44:47], v[204:207], v[172:175], v[44:47]
	v_mfma_f32_16x16x32_bf16 v[20:23], v[212:215], v[172:175], v[20:23]
	v_mfma_f32_16x16x32_bf16 v[40:43], v[204:207], v[180:183], v[40:43]
	v_mfma_f32_16x16x32_bf16 v[8:11], v[212:215], v[180:183], v[8:11]
	v_mfma_f32_16x16x32_bf16 v[36:39], v[204:207], v[188:191], v[36:39]
	v_mfma_f32_16x16x32_bf16 v[0:3], v[212:215], v[188:191], v[0:3]
	v_mfma_f32_16x16x32_bf16 v[32:35], v[204:207], v[196:199], v[32:35]
	v_mfma_f32_16x16x32_bf16 v[4:7], v[212:215], v[196:199], v[4:7]
	s_setprio 0
	s_add_i32 s49, s49, 2
	s_add_u32 s11, s11, 0x100
	s_addc_u32 s33, s33, 0
	s_cmp_gt_u32 s49, 13
	s_mov_b64 s[12:13], s[68:69]
	s_barrier
.LBB0_800:
	ds_read_b128 v[128:131], v158
	ds_read_b128 v[132:135], v158 offset:1024
	ds_read_b128 v[148:151], v158 offset:2048
	ds_read_b128 v[162:165], v158 offset:3072
	s_add_u32 s68, s12, 0x100
	s_addc_u32 s69, s13, 0
	s_cmp_eq_u32 s49, 12
	s_cselect_b32 s73, s63, s69
	s_cselect_b32 s72, s62, s68
	s_cselect_b32 s71, s65, s33
	s_cselect_b32 s70, s64, s11
	v_lshl_add_u64 v[200:201], s[12:13], 0, v[144:145]
	s_add_i32 m0, s67, 0xc000
	ds_read_b128 v[166:169], v159
	ds_read_b128 v[172:175], v159 offset:1024
	ds_read_b128 v[176:179], v159 offset:2048
	ds_read_b128 v[180:183], v159 offset:3072
	ds_read_b128 v[184:187], v159 offset:4096
	ds_read_b128 v[188:191], v159 offset:5120
	ds_read_b128 v[192:195], v159 offset:6144
	ds_read_b128 v[196:199], v159 offset:7168
	global_load_lds_dwordx4 v[200:201], off
	v_lshl_add_u64 v[200:201], s[12:13], 0, v[146:147]
	s_add_i32 m0, s67, 0xe000
	s_nop 0
	global_load_lds_dwordx4 v[200:201], off
	s_waitcnt lgkmcnt(8)
	s_barrier
	s_waitcnt lgkmcnt(0)
	s_setprio 1
	v_mfma_f32_16x16x32_bf16 v[84:87], v[128:131], v[166:169], v[84:87]
	v_mfma_f32_16x16x32_bf16 v[76:79], v[148:151], v[166:169], v[76:79]
	v_mfma_f32_16x16x32_bf16 v[124:127], v[128:131], v[176:179], v[124:127]
	v_mfma_f32_16x16x32_bf16 v[72:75], v[148:151], v[176:179], v[72:75]
	v_mfma_f32_16x16x32_bf16 v[120:123], v[128:131], v[184:187], v[120:123]
	v_mfma_f32_16x16x32_bf16 v[96:99], v[148:151], v[184:187], v[96:99]
	v_mfma_f32_16x16x32_bf16 v[116:119], v[128:131], v[192:195], v[116:119]
	v_mfma_f32_16x16x32_bf16 v[92:95], v[148:151], v[192:195], v[92:95]
	v_mfma_f32_16x16x32_bf16 v[84:87], v[132:135], v[172:175], v[84:87]
	v_mfma_f32_16x16x32_bf16 v[76:79], v[162:165], v[172:175], v[76:79]
	v_mfma_f32_16x16x32_bf16 v[124:127], v[132:135], v[180:183], v[124:127]
	v_mfma_f32_16x16x32_bf16 v[72:75], v[162:165], v[180:183], v[72:75]
	v_mfma_f32_16x16x32_bf16 v[120:123], v[132:135], v[188:191], v[120:123]
	v_mfma_f32_16x16x32_bf16 v[96:99], v[162:165], v[188:191], v[96:99]
	v_mfma_f32_16x16x32_bf16 v[116:119], v[132:135], v[196:199], v[116:119]
	v_mfma_f32_16x16x32_bf16 v[92:95], v[162:165], v[196:199], v[92:95]
	s_setprio 0
	s_barrier
	s_add_i32 s12, s88, s78
	v_lshl_add_u64 v[216:217], s[70:71], 0, v[138:139]
	s_mov_b32 m0, s12
	ds_read_b128 v[200:203], v160
	ds_read_b128 v[204:207], v160 offset:1024
	ds_read_b128 v[208:211], v160 offset:2048
	ds_read_b128 v[212:215], v160 offset:3072
	global_load_lds_dwordx4 v[216:217], off
	v_lshl_add_u64 v[218:219], s[70:71], 0, v[142:143]
	s_add_i32 m0, s12, 0x2000
	s_nop 0
	global_load_lds_dwordx4 v[218:219], off
	s_barrier
; #define PG8_STAGE(bufoff, gbase, voff) do { _Pragma("unroll") for (int _i = 0; _i < 2; ++_i) \
;         __builtin_amdgcn_global_load_lds((const unsigned*)((const char*)(gbase) + (voff)[_i]), (LAS unsigned*)(lds + (bufoff) + ldsw + _i * 8192), 16, 0, 0); } while (0)
; #define PG8_LDA(dst, b, h) do { _Pragma("unroll") for (int m = 0; m < 4; ++m) _Pragma("unroll") for (int k = 0; k < 2; ++k) dst[m][k] = *(const LAS bf16x8*)(lds + PG8_SA(b, h) + aoff + m * 2048 + k * 1024); } while (0)
; #define PG8_LDB(dst, b, h) do { _Pragma("unroll") for (int n = 0; n < 2; ++n) _Pragma("unroll") for (int k = 0; k < 2; ++k) dst[n][k] = *(const LAS bf16x8*)(lds + PG8_SB(b, h) + boff + n * 2048 + k * 1024); } while (0)
; #define PG8_MMA(ai, bj, At, Bt) do { __builtin_amdgcn_s_setprio(1); _Pragma("unroll") for (int m = 0; m < 4; ++m) _Pragma("unroll") for (int n = 0; n < 2; ++n) _Pragma("unroll") for (int k = 0; k < 2; ++k) \
;         acc[ai][bj][m][n] = __builtin_amdgcn_mfma_f32_16x16x32_bf16(Bt[n][k], At[m][k], acc[ai][bj][m][n], 0, 0, 0); __builtin_amdgcn_s_setprio(0); } while (0)
; #define PG8_WAIT_V(n) asm volatile("s_waitcnt vmcnt(" #n ")" ::: "memory")
; #define PG8_WAIT_L(n) asm volatile("s_waitcnt lgkmcnt(" #n ")" ::: "memory")
; #define PG8_BAR __builtin_amdgcn_s_barrier()
; #define PG8_SCHED __builtin_amdgcn_sched_barrier(0)
; template <class Epi, class Sched>
; __device__ __forceinline__ void gemm_phase(LAS unsigned char* lds, const int K, const Sched& S, const Epi& E) {
;     ...
;             PG8_BAR; PG8_WAIT_L(0); PG8_MMA(0, 1, At, B1); PG8_BAR;
;             PG8_LDA(At, 0, 1); PG8_STAGE(PG8_SA(0, 0), a2, voffA);
;             PG8_BAR; PG8_WAIT_L(0); PG8_MMA(1, 0, At, B0); PG8_BAR; PG8_SCHED;
;             PG8_STAGE(PG8_SB(0, 1), b2 + hstep, voffB);
;             PG8_WAIT_V(6); PG8_BAR; PG8_MMA(1, 1, At, B1); PG8_BAR;
;             PG8_LDB(B0, 1, 0); PG8_SCHED; PG8_LDA(At, 1, 0); PG8_STAGE(PG8_SA(0, 1), a2 + hstepA, voffA);
;             PG8_WAIT_L(8); PG8_BAR; PG8_WAIT_L(0); PG8_MMA(0, 0, At, B0); PG8_BAR; PG8_SCHED;
	s_waitcnt lgkmcnt(0)
	s_setprio 1
	v_mfma_f32_16x16x32_bf16 v[60:63], v[200:203], v[166:169], v[60:63]
	v_mfma_f32_16x16x32_bf16 v[16:19], v[208:211], v[166:169], v[16:19]
	v_mfma_f32_16x16x32_bf16 v[56:59], v[200:203], v[176:179], v[56:59]
	v_mfma_f32_16x16x32_bf16 v[12:15], v[208:211], v[176:179], v[12:15]
	v_mfma_f32_16x16x32_bf16 v[52:55], v[200:203], v[184:187], v[52:55]
	v_mfma_f32_16x16x32_bf16 v[28:31], v[208:211], v[184:187], v[28:31]
	v_mfma_f32_16x16x32_bf16 v[48:51], v[200:203], v[192:195], v[48:51]
	v_mfma_f32_16x16x32_bf16 v[24:27], v[208:211], v[192:195], v[24:27]
	v_mfma_f32_16x16x32_bf16 v[60:63], v[204:207], v[172:175], v[60:63]
	v_mfma_f32_16x16x32_bf16 v[16:19], v[212:215], v[172:175], v[16:19]
	v_mfma_f32_16x16x32_bf16 v[56:59], v[204:207], v[180:183], v[56:59]
	v_mfma_f32_16x16x32_bf16 v[12:15], v[212:215], v[180:183], v[12:15]
	v_mfma_f32_16x16x32_bf16 v[52:55], v[204:207], v[188:191], v[52:55]
	v_mfma_f32_16x16x32_bf16 v[28:31], v[212:215], v[188:191], v[28:31]
	v_mfma_f32_16x16x32_bf16 v[48:51], v[204:207], v[196:199], v[48:51]
	v_mfma_f32_16x16x32_bf16 v[24:27], v[212:215], v[196:199], v[24:27]
	s_setprio 0
	s_mov_b32 m0, s67
	v_lshl_add_u64 v[220:221], s[72:73], 0, v[136:137]
	s_barrier
	ds_read_b128 v[166:169], v159 offset:16384
	ds_read_b128 v[172:175], v159 offset:17408
	ds_read_b128 v[176:179], v159 offset:18432
	ds_read_b128 v[180:183], v159 offset:19456
	ds_read_b128 v[184:187], v159 offset:20480
	ds_read_b128 v[188:191], v159 offset:21504
	ds_read_b128 v[192:195], v159 offset:22528
	ds_read_b128 v[196:199], v159 offset:23552
	global_load_lds_dwordx4 v[220:221], off
	v_lshl_add_u64 v[222:223], s[72:73], 0, v[140:141]
	s_mov_b32 m0, s80
	s_nop 0
	global_load_lds_dwordx4 v[222:223], off
	s_barrier
	s_waitcnt lgkmcnt(0)
	s_setprio 1
	v_mfma_f32_16x16x32_bf16 v[112:115], v[128:131], v[166:169], v[112:115]
	v_mfma_f32_16x16x32_bf16 v[88:91], v[148:151], v[166:169], v[88:91]
	v_mfma_f32_16x16x32_bf16 v[104:107], v[128:131], v[176:179], v[104:107]
	v_mfma_f32_16x16x32_bf16 v[80:83], v[148:151], v[176:179], v[80:83]
	v_mfma_f32_16x16x32_bf16 v[100:103], v[128:131], v[184:187], v[100:103]
	v_mfma_f32_16x16x32_bf16 v[64:67], v[148:151], v[184:187], v[64:67]
	v_mfma_f32_16x16x32_bf16 v[108:111], v[128:131], v[192:195], v[108:111]
	v_mfma_f32_16x16x32_bf16 v[68:71], v[148:151], v[192:195], v[68:71]
	v_mfma_f32_16x16x32_bf16 v[112:115], v[132:135], v[172:175], v[112:115]
	v_mfma_f32_16x16x32_bf16 v[88:91], v[162:165], v[172:175], v[88:91]
	v_mfma_f32_16x16x32_bf16 v[104:107], v[132:135], v[180:183], v[104:107]
	v_mfma_f32_16x16x32_bf16 v[80:83], v[162:165], v[180:183], v[80:83]
	v_mfma_f32_16x16x32_bf16 v[100:103], v[132:135], v[188:191], v[100:103]
	v_mfma_f32_16x16x32_bf16 v[64:67], v[162:165], v[188:191], v[64:67]
	v_mfma_f32_16x16x32_bf16 v[108:111], v[132:135], v[196:199], v[108:111]
	v_mfma_f32_16x16x32_bf16 v[68:71], v[162:165], v[196:199], v[68:71]
	s_setprio 0
	s_barrier
	s_add_u32 s12, s70, 0x40000
	s_addc_u32 s13, s71, 0
	s_add_i32 s52, s89, s78
	v_lshl_add_u64 v[128:129], s[12:13], 0, v[138:139]
	s_mov_b32 m0, s52
	s_nop 0
	global_load_lds_dwordx4 v[128:129], off
	v_lshl_add_u64 v[128:129], s[12:13], 0, v[142:143]
	s_add_i32 m0, s52, 0x2000
	s_nop 0
	global_load_lds_dwordx4 v[128:129], off
	s_waitcnt vmcnt(6)
	s_barrier
	s_setprio 1
	v_mfma_f32_16x16x32_bf16 v[44:47], v[200:203], v[166:169], v[44:47]
	v_mfma_f32_16x16x32_bf16 v[20:23], v[208:211], v[166:169], v[20:23]
	v_mfma_f32_16x16x32_bf16 v[40:43], v[200:203], v[176:179], v[40:43]
	v_mfma_f32_16x16x32_bf16 v[8:11], v[208:211], v[176:179], v[8:11]
	v_mfma_f32_16x16x32_bf16 v[36:39], v[200:203], v[184:187], v[36:39]
	v_mfma_f32_16x16x32_bf16 v[0:3], v[208:211], v[184:187], v[0:3]
	v_mfma_f32_16x16x32_bf16 v[32:35], v[200:203], v[192:195], v[32:35]
	v_mfma_f32_16x16x32_bf16 v[4:7], v[208:211], v[192:195], v[4:7]
	v_mfma_f32_16x16x32_bf16 v[44:47], v[204:207], v[172:175], v[44:47]
	v_mfma_f32_16x16x32_bf16 v[20:23], v[212:215], v[172:175], v[20:23]
	v_mfma_f32_16x16x32_bf16 v[40:43], v[204:207], v[180:183], v[40:43]
	v_mfma_f32_16x16x32_bf16 v[8:11], v[212:215], v[180:183], v[8:11]
	v_mfma_f32_16x16x32_bf16 v[36:39], v[204:207], v[188:191], v[36:39]
	v_mfma_f32_16x16x32_bf16 v[0:3], v[212:215], v[188:191], v[0:3]
	v_mfma_f32_16x16x32_bf16 v[32:35], v[204:207], v[196:199], v[32:35]
	v_mfma_f32_16x16x32_bf16 v[4:7], v[212:215], v[196:199], v[4:7]
	s_setprio 0
	s_add_i32 s52, 0, 0x18000
	v_add_u32_e32 v161, s52, v156
	s_barrier
	ds_read_b128 v[128:131], v161
	ds_read_b128 v[132:135], v161 offset:1024
	ds_read_b128 v[148:151], v161 offset:2048
	ds_read_b128 v[162:165], v161 offset:3072
	s_add_u32 s12, s72, 0x20000
	s_addc_u32 s13, s73, 0
	s_mov_b32 m0, s81
	v_lshl_add_u64 v[200:201], s[12:13], 0, v[136:137]
	ds_read_b128 v[166:169], v159 offset:32768
	ds_read_b128 v[172:175], v159 offset:33792
	ds_read_b128 v[176:179], v159 offset:34816
	ds_read_b128 v[180:183], v159 offset:35840
	ds_read_b128 v[184:187], v159 offset:36864
	ds_read_b128 v[188:191], v159 offset:37888
	ds_read_b128 v[192:195], v159 offset:38912
	ds_read_b128 v[196:199], v159 offset:39936
	global_load_lds_dwordx4 v[200:201], off
	v_lshl_add_u64 v[200:201], s[12:13], 0, v[140:141]
	s_mov_b32 m0, s82
	s_nop 0
	global_load_lds_dwordx4 v[200:201], off
	s_waitcnt lgkmcnt(8)
	s_barrier
; __device__ __forceinline__ unsigned cvt_pk_bf16(float lo, float hi) { unsigned r; asm volatile("v_cvt_pk_bf16_f32 %0, %1, %2" : "=v"(r) : "v"(lo), "v"(hi)); return r; }
; #define PG8_STAGE(bufoff, gbase, voff) do { _Pragma("unroll") for (int _i = 0; _i < 2; ++_i) \
;         __builtin_amdgcn_global_load_lds((const unsigned*)((const char*)(gbase) + (voff)[_i]), (LAS unsigned*)(lds + (bufoff) + ldsw + _i * 8192), 16, 0, 0); } while (0)
; #define PG8_LDA(dst, b, h) do { _Pragma("unroll") for (int m = 0; m < 4; ++m) _Pragma("unroll") for (int k = 0; k < 2; ++k) dst[m][k] = *(const LAS bf16x8*)(lds + PG8_SA(b, h) + aoff + m * 2048 + k * 1024); } while (0)
; #define PG8_LDB(dst, b, h) do { _Pragma("unroll") for (int n = 0; n < 2; ++n) _Pragma("unroll") for (int k = 0; k < 2; ++k) dst[n][k] = *(const LAS bf16x8*)(lds + PG8_SB(b, h) + boff + n * 2048 + k * 1024); } while (0)
; #define PG8_BAR __builtin_amdgcn_s_barrier()
; template <class Epi, class Sched>
; __device__ __forceinline__ void gemm_phase(LAS unsigned char* lds, const int K, const Sched& S, const Epi& E) {
;     ...
;             PG8_WAIT_L(8); PG8_BAR; PG8_WAIT_L(0); PG8_MMA(0, 0, At, B0); PG8_BAR; PG8_SCHED;
;             PG8_LDB(B1, 1, 1); PG8_STAGE(PG8_SB(1, 0), b3, voffB);
;             PG8_BAR; PG8_WAIT_L(0); PG8_MMA(0, 1, At, B1); PG8_BAR;
;             PG8_LDA(At, 1, 1); PG8_STAGE(PG8_SA(1, 0), a3, voffA);
;             PG8_BAR; PG8_WAIT_L(0); PG8_MMA(1, 0, At, B0); PG8_BAR; PG8_SCHED;
;             PG8_STAGE(PG8_SB(1, 1), b3 + hstep, voffB);
;             PG8_WAIT_V(6); PG8_BAR; PG8_MMA(1, 1, At, B1); PG8_BAR;
;     __device__ __forceinline__ void operator()(f32x4 (&acc)[2][2][4][2], const Unit& u, int wr, int wc, int fr, int fq) const {
;         const int J0 = u.pn * 128 + wc * 32 + fq * 8, sc = u.pm * 2 + wr;
;         const bool f0 = (fr == 0), f15 = (fr == 15);
;         if (f0 || f15) {
; #pragma unroll
;             for (int bj = 0; bj < 2; ++bj)
; #pragma unroll
;                 for (int q = 0; q < 2; ++q) { const f32x4 a0 = f0 ? acc[0][bj][q][0] : acc[1][bj][2 + q][0], a1 = f0 ? acc[0][bj][q][1] : acc[1][bj][2 + q][1];
;                     u32x4 w; w.x = cvt_pk_bf16(a0[0], a0[1]); w.y = cvt_pk_bf16(a0[2], a0[3]); w.z = cvt_pk_bf16(a1[0], a1[1]); w.w = cvt_pk_bf16(a1[2], a1[3]);
;                     *(u32x4*)(side + (size_t)(sc * 4 + (f0 ? q : 2 + q)) * (2 * DFF) + bj * DFF + J0) = w; }
	s_waitcnt lgkmcnt(0)
	s_setprio 1
	v_mfma_f32_16x16x32_bf16 v[84:87], v[128:131], v[166:169], v[84:87]
	v_mfma_f32_16x16x32_bf16 v[76:79], v[148:151], v[166:169], v[76:79]
	v_mfma_f32_16x16x32_bf16 v[124:127], v[128:131], v[176:179], v[124:127]
	v_mfma_f32_16x16x32_bf16 v[72:75], v[148:151], v[176:179], v[72:75]
	v_mfma_f32_16x16x32_bf16 v[120:123], v[128:131], v[184:187], v[120:123]
	v_mfma_f32_16x16x32_bf16 v[96:99], v[148:151], v[184:187], v[96:99]
	v_mfma_f32_16x16x32_bf16 v[116:119], v[128:131], v[192:195], v[116:119]
	v_mfma_f32_16x16x32_bf16 v[92:95], v[148:151], v[192:195], v[92:95]
	v_mfma_f32_16x16x32_bf16 v[84:87], v[132:135], v[172:175], v[84:87]
	v_mfma_f32_16x16x32_bf16 v[76:79], v[162:165], v[172:175], v[76:79]
	v_mfma_f32_16x16x32_bf16 v[124:127], v[132:135], v[180:183], v[124:127]
	v_mfma_f32_16x16x32_bf16 v[72:75], v[162:165], v[180:183], v[72:75]
	v_mfma_f32_16x16x32_bf16 v[120:123], v[132:135], v[188:191], v[120:123]
	v_mfma_f32_16x16x32_bf16 v[96:99], v[162:165], v[188:191], v[96:99]
	v_mfma_f32_16x16x32_bf16 v[116:119], v[132:135], v[196:199], v[116:119]
	v_mfma_f32_16x16x32_bf16 v[92:95], v[162:165], v[196:199], v[92:95]
	s_setprio 0
	s_barrier
	s_add_i32 s53, 0, 0x1c000
	s_add_i32 s12, s52, s78
	v_add_u32_e32 v161, s53, v156
	v_lshl_add_u64 v[216:217], v[216:217], 0, s[38:39]
	s_mov_b32 m0, s12
	ds_read_b128 v[200:203], v161
	ds_read_b128 v[204:207], v161 offset:1024
	ds_read_b128 v[208:211], v161 offset:2048
	ds_read_b128 v[212:215], v161 offset:3072
	global_load_lds_dwordx4 v[216:217], off
	v_lshl_add_u64 v[216:217], v[218:219], 0, s[38:39]
	s_add_i32 m0, s12, 0x2000
	s_nop 0
	global_load_lds_dwordx4 v[216:217], off
	s_barrier
	s_waitcnt lgkmcnt(0)
	s_setprio 1
	v_mfma_f32_16x16x32_bf16 v[60:63], v[200:203], v[166:169], v[60:63]
	v_mfma_f32_16x16x32_bf16 v[16:19], v[208:211], v[166:169], v[16:19]
	v_mfma_f32_16x16x32_bf16 v[56:59], v[200:203], v[176:179], v[56:59]
	v_mfma_f32_16x16x32_bf16 v[12:15], v[208:211], v[176:179], v[12:15]
	v_mfma_f32_16x16x32_bf16 v[52:55], v[200:203], v[184:187], v[52:55]
	v_mfma_f32_16x16x32_bf16 v[28:31], v[208:211], v[184:187], v[28:31]
	v_mfma_f32_16x16x32_bf16 v[48:51], v[200:203], v[192:195], v[48:51]
	v_mfma_f32_16x16x32_bf16 v[24:27], v[208:211], v[192:195], v[24:27]
	v_mfma_f32_16x16x32_bf16 v[60:63], v[204:207], v[172:175], v[60:63]
	v_mfma_f32_16x16x32_bf16 v[16:19], v[212:215], v[172:175], v[16:19]
	v_mfma_f32_16x16x32_bf16 v[56:59], v[204:207], v[180:183], v[56:59]
	v_mfma_f32_16x16x32_bf16 v[12:15], v[212:215], v[180:183], v[12:15]
	v_mfma_f32_16x16x32_bf16 v[52:55], v[204:207], v[188:191], v[52:55]
	v_mfma_f32_16x16x32_bf16 v[28:31], v[212:215], v[188:191], v[28:31]
	v_mfma_f32_16x16x32_bf16 v[48:51], v[204:207], v[196:199], v[48:51]
	v_mfma_f32_16x16x32_bf16 v[24:27], v[212:215], v[196:199], v[24:27]
	s_setprio 0
	s_mov_b32 m0, s84
	v_lshl_add_u64 v[216:217], v[220:221], 0, s[38:39]
	s_barrier
	ds_read_b128 v[166:169], v159 offset:49152
	ds_read_b128 v[172:175], v159 offset:50176
	ds_read_b128 v[176:179], v159 offset:51200
	ds_read_b128 v[180:183], v159 offset:52224
	ds_read_b128 v[184:187], v159 offset:53248
	ds_read_b128 v[188:191], v159 offset:54272
	ds_read_b128 v[192:195], v159 offset:55296
	ds_read_b128 v[196:199], v159 offset:56320
	global_load_lds_dwordx4 v[216:217], off
	v_lshl_add_u64 v[216:217], v[222:223], 0, s[38:39]
	s_mov_b32 m0, s85
	s_nop 0
	global_load_lds_dwordx4 v[216:217], off
	s_barrier
	s_waitcnt lgkmcnt(0)
	s_setprio 1
	v_mfma_f32_16x16x32_bf16 v[112:115], v[128:131], v[166:169], v[112:115]
	v_mfma_f32_16x16x32_bf16 v[88:91], v[148:151], v[166:169], v[88:91]
	v_mfma_f32_16x16x32_bf16 v[104:107], v[128:131], v[176:179], v[104:107]
	v_mfma_f32_16x16x32_bf16 v[80:83], v[148:151], v[176:179], v[80:83]
	v_mfma_f32_16x16x32_bf16 v[100:103], v[128:131], v[184:187], v[100:103]
	v_mfma_f32_16x16x32_bf16 v[64:67], v[148:151], v[184:187], v[64:67]
	v_mfma_f32_16x16x32_bf16 v[108:111], v[128:131], v[192:195], v[108:111]
	v_mfma_f32_16x16x32_bf16 v[68:71], v[148:151], v[192:195], v[68:71]
	v_mfma_f32_16x16x32_bf16 v[112:115], v[132:135], v[172:175], v[112:115]
	v_mfma_f32_16x16x32_bf16 v[88:91], v[162:165], v[172:175], v[88:91]
	v_mfma_f32_16x16x32_bf16 v[104:107], v[132:135], v[180:183], v[104:107]
	v_mfma_f32_16x16x32_bf16 v[80:83], v[162:165], v[180:183], v[80:83]
	v_mfma_f32_16x16x32_bf16 v[100:103], v[132:135], v[188:191], v[100:103]
	v_mfma_f32_16x16x32_bf16 v[64:67], v[162:165], v[188:191], v[64:67]
	v_mfma_f32_16x16x32_bf16 v[108:111], v[132:135], v[196:199], v[108:111]
	v_mfma_f32_16x16x32_bf16 v[68:71], v[162:165], v[196:199], v[68:71]
	s_setprio 0
	s_barrier
	s_add_u32 s12, s70, 0x40080
	s_addc_u32 s13, s71, 0
	s_add_i32 s52, s53, s78
	v_lshl_add_u64 v[128:129], s[12:13], 0, v[138:139]
	s_mov_b32 m0, s52
	s_nop 0
	global_load_lds_dwordx4 v[128:129], off
	v_lshl_add_u64 v[128:129], s[12:13], 0, v[142:143]
	s_add_i32 m0, s52, 0x2000
	s_nop 0
	global_load_lds_dwordx4 v[128:129], off
	s_waitcnt vmcnt(6)
	s_barrier
	s_setprio 1
	v_mfma_f32_16x16x32_bf16 v[44:47], v[200:203], v[166:169], v[44:47]
	v_mfma_f32_16x16x32_bf16 v[20:23], v[208:211], v[166:169], v[20:23]
	v_mfma_f32_16x16x32_bf16 v[40:43], v[200:203], v[176:179], v[40:43]
	v_mfma_f32_16x16x32_bf16 v[8:11], v[208:211], v[176:179], v[8:11]
	v_mfma_f32_16x16x32_bf16 v[36:39], v[200:203], v[184:187], v[36:39]
	v_mfma_f32_16x16x32_bf16 v[0:3], v[208:211], v[184:187], v[0:3]
	v_mfma_f32_16x16x32_bf16 v[32:35], v[200:203], v[192:195], v[32:35]
	v_mfma_f32_16x16x32_bf16 v[4:7], v[208:211], v[192:195], v[4:7]
	v_mfma_f32_16x16x32_bf16 v[44:47], v[204:207], v[172:175], v[44:47]
	v_mfma_f32_16x16x32_bf16 v[20:23], v[212:215], v[172:175], v[20:23]
	v_mfma_f32_16x16x32_bf16 v[40:43], v[204:207], v[180:183], v[40:43]
	v_mfma_f32_16x16x32_bf16 v[8:11], v[212:215], v[180:183], v[8:11]
	v_mfma_f32_16x16x32_bf16 v[36:39], v[204:207], v[188:191], v[36:39]
	v_mfma_f32_16x16x32_bf16 v[0:3], v[212:215], v[188:191], v[0:3]
	v_mfma_f32_16x16x32_bf16 v[32:35], v[204:207], v[196:199], v[32:35]
	v_mfma_f32_16x16x32_bf16 v[4:7], v[212:215], v[196:199], v[4:7]
	s_setprio 0
	s_add_i32 s49, s49, 2
	s_add_u32 s11, s11, 0x100
	s_addc_u32 s33, s33, 0
	s_cmp_gt_u32 s49, 13
	s_mov_b64 s[12:13], s[68:69]
	s_barrier
	s_cbranch_scc0 .LBB0_800
	v_lshl_or_b32 v150, s10, 7, v157
	v_add_u32_e32 v254, 0x2c00, v253
	global_load_dwordx4 v[208:211], v253, s[22:23] offset:16
	global_load_dwordx4 v[212:215], v253, s[24:25] offset:16
	global_load_dwordx4 v[216:219], v253, s[26:27] offset:16
	global_load_dwordx4 v[220:223], v253, s[36:37] offset:16
	v_cmp_gt_i32_e32 vcc, 15, v152
	s_mov_b64 s[70:71], -1
	s_and_saveexec_b64 s[68:69], vcc
	s_cbranch_execz .LBB0_805
	v_cmp_eq_u32_e32 vcc, 0, v152
	v_cmp_ne_u32_e64 s[12:13], 0, v152
	s_and_saveexec_b64 s[70:71], s[12:13]
	v_ashrrev_i32_e32 v151, 31, v150
	v_mov_b64_e32 v[148:149], v[150:151]
	s_or_b64 exec, exec, s[70:71]
	s_orn2_b64 s[70:71], vcc, exec

; #define PG8_STAGE(bufoff, gbase, voff) do { _Pragma("unroll") for (int _i = 0; _i < 2; ++_i) \
;         __builtin_amdgcn_global_load_lds((const unsigned*)((const char*)(gbase) + (voff)[_i]), (LAS unsigned*)(lds + (bufoff) + ldsw + _i * 8192), 16, 0, 0); } while (0)
; #define PG8_LDA(dst, b, h) do { _Pragma("unroll") for (int m = 0; m < 4; ++m) _Pragma("unroll") for (int k = 0; k < 2; ++k) dst[m][k] = *(const LAS bf16x8*)(lds + PG8_SA(b, h) + aoff + m * 2048 + k * 1024); } while (0)
; #define PG8_LDB(dst, b, h) do { _Pragma("unroll") for (int n = 0; n < 2; ++n) _Pragma("unroll") for (int k = 0; k < 2; ++k) dst[n][k] = *(const LAS bf16x8*)(lds + PG8_SB(b, h) + boff + n * 2048 + k * 1024); } while (0)
; #define PG8_MMA(ai, bj, At, Bt) do { __builtin_amdgcn_s_setprio(1); _Pragma("unroll") for (int m = 0; m < 4; ++m) _Pragma("unroll") for (int n = 0; n < 2; ++n) _Pragma("unroll") for (int k = 0; k < 2; ++k) \
;         acc[ai][bj][m][n] = __builtin_amdgcn_mfma_f32_16x16x32_bf16(Bt[n][k], At[m][k], acc[ai][bj][m][n], 0, 0, 0); __builtin_amdgcn_s_setprio(0); } while (0)
; #define PG8_WAIT_L(n) asm volatile("s_waitcnt lgkmcnt(" #n ")" ::: "memory")
; #define PG8_BAR __builtin_amdgcn_s_barrier()
; #define PG8_SCHED __builtin_amdgcn_sched_barrier(0)
; template <class Epi, class Sched>
; __device__ __forceinline__ void gemm_phase(LAS unsigned char* lds, const int K, const Sched& S, const Epi& E) {
;     ...
;             PG8_LDB(B0, 0, 0); PG8_SCHED; PG8_LDA(At, 0, 0); PG8_STAGE(PG8_SA(1, 1), a1 + hstepA, voffA);
;             PG8_WAIT_L(8); PG8_BAR; PG8_WAIT_L(0); PG8_MMA(0, 0, At, B0); PG8_BAR; PG8_SCHED;
;             PG8_LDB(B1, 0, 1); PG8_STAGE(PG8_SB(0, 0), b2, voffB);
;             PG8_BAR; PG8_WAIT_L(0); PG8_MMA(0, 1, At, B1); PG8_BAR;
;             PG8_LDA(At, 0, 1); PG8_STAGE(PG8_SA(0, 0), a2, voffA);
;             PG8_BAR; PG8_WAIT_L(0); PG8_MMA(1, 0, At, B0); PG8_BAR; PG8_SCHED;
.LBB0_1081:
	ds_read_b128 v[96:99], v165
	ds_read_b128 v[100:103], v165 offset:1024
	ds_read_b128 v[104:107], v165 offset:2048
	ds_read_b128 v[112:115], v165 offset:3072
	s_add_u32 s24, s22, 0xfff50080
	s_addc_u32 s25, s23, -1
	s_cmp_eq_u32 s52, 40
	s_cselect_b32 s27, s19, s25
	s_cselect_b32 s26, s18, s24
	s_cselect_b32 s25, s21, s33
	s_cselect_b32 s24, s20, s11
	s_mov_b32 m0, s51
	v_lshl_add_u64 v[200:201], s[22:23], 0, v[148:149]
	ds_read_b128 v[152:155], v166
	ds_read_b128 v[172:175], v166 offset:1024
	ds_read_b128 v[176:179], v166 offset:2048
	ds_read_b128 v[180:183], v166 offset:3072
	ds_read_b128 v[184:187], v166 offset:4096
	ds_read_b128 v[188:191], v166 offset:5120
	ds_read_b128 v[192:195], v166 offset:6144
	ds_read_b128 v[196:199], v166 offset:7168
	global_load_lds_dwordx4 v[200:201], off
	v_lshl_add_u64 v[200:201], s[22:23], 0, v[150:151]
	s_mov_b32 m0, s58
	s_nop 0
	global_load_lds_dwordx4 v[200:201], off
	s_waitcnt lgkmcnt(8)
	s_barrier
	s_waitcnt lgkmcnt(0)
	s_setprio 1
	v_mfma_f32_16x16x32_bf16 v[140:143], v[96:99], v[152:155], v[140:143]
	v_mfma_f32_16x16x32_bf16 v[136:139], v[104:107], v[152:155], v[136:139]
	v_mfma_f32_16x16x32_bf16 v[124:127], v[96:99], v[176:179], v[124:127]
	v_mfma_f32_16x16x32_bf16 v[120:123], v[104:107], v[176:179], v[120:123]
	v_mfma_f32_16x16x32_bf16 v[92:95], v[96:99], v[184:187], v[92:95]
	v_mfma_f32_16x16x32_bf16 v[88:91], v[104:107], v[184:187], v[88:91]
	v_mfma_f32_16x16x32_bf16 v[76:79], v[96:99], v[192:195], v[76:79]
	v_mfma_f32_16x16x32_bf16 v[72:75], v[104:107], v[192:195], v[72:75]
	v_mfma_f32_16x16x32_bf16 v[140:143], v[100:103], v[172:175], v[140:143]
	v_mfma_f32_16x16x32_bf16 v[136:139], v[112:115], v[172:175], v[136:139]
	v_mfma_f32_16x16x32_bf16 v[124:127], v[100:103], v[180:183], v[124:127]
	v_mfma_f32_16x16x32_bf16 v[120:123], v[112:115], v[180:183], v[120:123]
	v_mfma_f32_16x16x32_bf16 v[92:95], v[100:103], v[188:191], v[92:95]
	v_mfma_f32_16x16x32_bf16 v[88:91], v[112:115], v[188:191], v[88:91]
	v_mfma_f32_16x16x32_bf16 v[76:79], v[100:103], v[196:199], v[76:79]
	v_mfma_f32_16x16x32_bf16 v[72:75], v[112:115], v[196:199], v[72:75]
	s_setprio 0
	s_barrier
	s_mov_b32 m0, s59
	v_lshl_add_u64 v[216:217], s[24:25], 0, v[144:145]
	ds_read_b128 v[200:203], v167
	ds_read_b128 v[204:207], v167 offset:1024
	ds_read_b128 v[208:211], v167 offset:2048
	ds_read_b128 v[212:215], v167 offset:3072
	global_load_lds_dwordx4 v[216:217], off
	v_lshl_add_u64 v[218:219], s[24:25], 0, v[146:147]
	s_mov_b32 m0, s60
	s_nop 0
	global_load_lds_dwordx4 v[218:219], off
	s_barrier
	s_waitcnt lgkmcnt(0)
	s_setprio 1
	v_mfma_f32_16x16x32_bf16 v[132:135], v[200:203], v[152:155], v[132:135]
	v_mfma_f32_16x16x32_bf16 v[128:131], v[208:211], v[152:155], v[128:131]
	v_mfma_f32_16x16x32_bf16 v[116:119], v[200:203], v[176:179], v[116:119]
	v_mfma_f32_16x16x32_bf16 v[108:111], v[208:211], v[176:179], v[108:111]
	v_mfma_f32_16x16x32_bf16 v[84:87], v[200:203], v[184:187], v[84:87]
	v_mfma_f32_16x16x32_bf16 v[80:83], v[208:211], v[184:187], v[80:83]
	v_mfma_f32_16x16x32_bf16 v[68:71], v[200:203], v[192:195], v[68:71]
	v_mfma_f32_16x16x32_bf16 v[64:67], v[208:211], v[192:195], v[64:67]
	v_mfma_f32_16x16x32_bf16 v[132:135], v[204:207], v[172:175], v[132:135]
	v_mfma_f32_16x16x32_bf16 v[128:131], v[212:215], v[172:175], v[128:131]
	v_mfma_f32_16x16x32_bf16 v[116:119], v[204:207], v[180:183], v[116:119]
	v_mfma_f32_16x16x32_bf16 v[108:111], v[212:215], v[180:183], v[108:111]
	v_mfma_f32_16x16x32_bf16 v[84:87], v[204:207], v[188:191], v[84:87]
	v_mfma_f32_16x16x32_bf16 v[80:83], v[212:215], v[188:191], v[80:83]
	v_mfma_f32_16x16x32_bf16 v[68:71], v[204:207], v[196:199], v[68:71]
	v_mfma_f32_16x16x32_bf16 v[64:67], v[212:215], v[196:199], v[64:67]
	s_setprio 0
	s_mov_b32 m0, s42
	v_lshl_add_u64 v[220:221], s[26:27], 0, v[144:145]
	s_barrier
	ds_read_b128 v[152:155], v166 offset:16384
	ds_read_b128 v[172:175], v166 offset:17408
	ds_read_b128 v[176:179], v166 offset:18432
	ds_read_b128 v[180:183], v166 offset:19456
	ds_read_b128 v[184:187], v166 offset:20480
	ds_read_b128 v[188:191], v166 offset:21504
	ds_read_b128 v[192:195], v166 offset:22528
	ds_read_b128 v[196:199], v166 offset:23552
	global_load_lds_dwordx4 v[220:221], off
	v_lshl_add_u64 v[222:223], s[26:27], 0, v[146:147]
	s_mov_b32 m0, s43
	s_nop 0
	global_load_lds_dwordx4 v[222:223], off
	s_barrier
	s_waitcnt lgkmcnt(0)
	s_setprio 1
	v_mfma_f32_16x16x32_bf16 v[60:63], v[96:99], v[152:155], v[60:63]
	v_mfma_f32_16x16x32_bf16 v[56:59], v[104:107], v[152:155], v[56:59]
	v_mfma_f32_16x16x32_bf16 v[44:47], v[96:99], v[176:179], v[44:47]
	v_mfma_f32_16x16x32_bf16 v[40:43], v[104:107], v[176:179], v[40:43]
	v_mfma_f32_16x16x32_bf16 v[28:31], v[96:99], v[184:187], v[28:31]
	v_mfma_f32_16x16x32_bf16 v[24:27], v[104:107], v[184:187], v[24:27]
	v_mfma_f32_16x16x32_bf16 v[12:15], v[96:99], v[192:195], v[12:15]
	v_mfma_f32_16x16x32_bf16 v[8:11], v[104:107], v[192:195], v[8:11]
	v_mfma_f32_16x16x32_bf16 v[60:63], v[100:103], v[172:175], v[60:63]
	v_mfma_f32_16x16x32_bf16 v[56:59], v[112:115], v[172:175], v[56:59]
	v_mfma_f32_16x16x32_bf16 v[44:47], v[100:103], v[180:183], v[44:47]
	v_mfma_f32_16x16x32_bf16 v[40:43], v[112:115], v[180:183], v[40:43]
	v_mfma_f32_16x16x32_bf16 v[28:31], v[100:103], v[188:191], v[28:31]
	v_mfma_f32_16x16x32_bf16 v[24:27], v[112:115], v[188:191], v[24:27]
	v_mfma_f32_16x16x32_bf16 v[12:15], v[100:103], v[196:199], v[12:15]
	v_mfma_f32_16x16x32_bf16 v[8:11], v[112:115], v[196:199], v[8:11]
	s_setprio 0
	s_barrier
; #define PG8_STAGE(bufoff, gbase, voff) do { _Pragma("unroll") for (int _i = 0; _i < 2; ++_i) \
;         __builtin_amdgcn_global_load_lds((const unsigned*)((const char*)(gbase) + (voff)[_i]), (LAS unsigned*)(lds + (bufoff) + ldsw + _i * 8192), 16, 0, 0); } while (0)
; #define PG8_LDA(dst, b, h) do { _Pragma("unroll") for (int m = 0; m < 4; ++m) _Pragma("unroll") for (int k = 0; k < 2; ++k) dst[m][k] = *(const LAS bf16x8*)(lds + PG8_SA(b, h) + aoff + m * 2048 + k * 1024); } while (0)
; #define PG8_LDB(dst, b, h) do { _Pragma("unroll") for (int n = 0; n < 2; ++n) _Pragma("unroll") for (int k = 0; k < 2; ++k) dst[n][k] = *(const LAS bf16x8*)(lds + PG8_SB(b, h) + boff + n * 2048 + k * 1024); } while (0)
; #define PG8_MMA(ai, bj, At, Bt) do { __builtin_amdgcn_s_setprio(1); _Pragma("unroll") for (int m = 0; m < 4; ++m) _Pragma("unroll") for (int n = 0; n < 2; ++n) _Pragma("unroll") for (int k = 0; k < 2; ++k) \
;         acc[ai][bj][m][n] = __builtin_amdgcn_mfma_f32_16x16x32_bf16(Bt[n][k], At[m][k], acc[ai][bj][m][n], 0, 0, 0); __builtin_amdgcn_s_setprio(0); } while (0)
; #define PG8_WAIT_V(n) asm volatile("s_waitcnt vmcnt(" #n ")" ::: "memory")
; #define PG8_WAIT_L(n) asm volatile("s_waitcnt lgkmcnt(" #n ")" ::: "memory")
; #define PG8_BAR __builtin_amdgcn_s_barrier()
; #define PG8_SCHED __builtin_amdgcn_sched_barrier(0)
; template <class Epi, class Sched>
; __device__ __forceinline__ void gemm_phase(LAS unsigned char* lds, const int K, const Sched& S, const Epi& E) {
;     ...
;             PG8_STAGE(PG8_SB(0, 1), b2 + hstep, voffB);
;             PG8_WAIT_V(6); PG8_BAR; PG8_MMA(1, 1, At, B1); PG8_BAR;
;             PG8_LDB(B0, 1, 0); PG8_SCHED; PG8_LDA(At, 1, 0); PG8_STAGE(PG8_SA(0, 1), a2 + hstepA, voffA);
;             PG8_WAIT_L(8); PG8_BAR; PG8_WAIT_L(0); PG8_MMA(0, 0, At, B0); PG8_BAR; PG8_SCHED;
;             PG8_LDB(B1, 1, 1); PG8_STAGE(PG8_SB(1, 0), b3, voffB);
;             PG8_BAR; PG8_WAIT_L(0); PG8_MMA(0, 1, At, B1); PG8_BAR;
;             PG8_LDA(At, 1, 1); PG8_STAGE(PG8_SA(1, 0), a3, voffA);
	s_add_u32 s54, s24, 0xb0000
	s_addc_u32 s55, s25, 0
	s_mov_b32 m0, s61
	v_lshl_add_u64 v[96:97], s[54:55], 0, v[144:145]
	global_load_lds_dwordx4 v[96:97], off
	v_lshl_add_u64 v[96:97], s[54:55], 0, v[146:147]
	s_mov_b32 m0, s62
	s_nop 0
	global_load_lds_dwordx4 v[96:97], off
	s_waitcnt vmcnt(6)
	s_barrier
	s_setprio 1
	v_mfma_f32_16x16x32_bf16 v[52:55], v[200:203], v[152:155], v[52:55]
	v_mfma_f32_16x16x32_bf16 v[48:51], v[208:211], v[152:155], v[48:51]
	v_mfma_f32_16x16x32_bf16 v[36:39], v[200:203], v[176:179], v[36:39]
	v_mfma_f32_16x16x32_bf16 v[32:35], v[208:211], v[176:179], v[32:35]
	v_mfma_f32_16x16x32_bf16 v[20:23], v[200:203], v[184:187], v[20:23]
	v_mfma_f32_16x16x32_bf16 v[16:19], v[208:211], v[184:187], v[16:19]
	v_mfma_f32_16x16x32_bf16 v[4:7], v[200:203], v[192:195], v[4:7]
	v_mfma_f32_16x16x32_bf16 v[0:3], v[208:211], v[192:195], v[0:3]
	v_mfma_f32_16x16x32_bf16 v[52:55], v[204:207], v[172:175], v[52:55]
	v_mfma_f32_16x16x32_bf16 v[48:51], v[212:215], v[172:175], v[48:51]
	v_mfma_f32_16x16x32_bf16 v[36:39], v[204:207], v[180:183], v[36:39]
	v_mfma_f32_16x16x32_bf16 v[32:35], v[212:215], v[180:183], v[32:35]
	v_mfma_f32_16x16x32_bf16 v[20:23], v[204:207], v[188:191], v[20:23]
	v_mfma_f32_16x16x32_bf16 v[16:19], v[212:215], v[188:191], v[16:19]
	v_mfma_f32_16x16x32_bf16 v[4:7], v[204:207], v[196:199], v[4:7]
	v_mfma_f32_16x16x32_bf16 v[0:3], v[212:215], v[196:199], v[0:3]
	s_setprio 0
	s_add_i32 s53, 0, 0x18000
	v_add_u32_e32 v112, s53, v163
	s_barrier
	ds_read_b128 v[96:99], v112
	ds_read_b128 v[100:103], v112 offset:1024
	ds_read_b128 v[104:107], v112 offset:2048
	ds_read_b128 v[112:115], v112 offset:3072
	s_add_u32 s26, s26, 0xb0000
	s_addc_u32 s27, s27, 0
	s_mov_b32 m0, s44
	v_lshl_add_u64 v[200:201], s[26:27], 0, v[144:145]
	ds_read_b128 v[152:155], v166 offset:32768
	ds_read_b128 v[172:175], v166 offset:33792
	ds_read_b128 v[176:179], v166 offset:34816
	ds_read_b128 v[180:183], v166 offset:35840
	ds_read_b128 v[184:187], v166 offset:36864
	ds_read_b128 v[188:191], v166 offset:37888
	ds_read_b128 v[192:195], v166 offset:38912
	ds_read_b128 v[196:199], v166 offset:39936
	global_load_lds_dwordx4 v[200:201], off
	v_lshl_add_u64 v[200:201], s[26:27], 0, v[146:147]
	s_mov_b32 m0, s45
	s_nop 0
	global_load_lds_dwordx4 v[200:201], off
	s_waitcnt lgkmcnt(8)
	s_barrier
	s_waitcnt lgkmcnt(0)
	s_setprio 1
	v_mfma_f32_16x16x32_bf16 v[140:143], v[96:99], v[152:155], v[140:143]
	v_mfma_f32_16x16x32_bf16 v[136:139], v[104:107], v[152:155], v[136:139]
	v_mfma_f32_16x16x32_bf16 v[124:127], v[96:99], v[176:179], v[124:127]
	v_mfma_f32_16x16x32_bf16 v[120:123], v[104:107], v[176:179], v[120:123]
	v_mfma_f32_16x16x32_bf16 v[92:95], v[96:99], v[184:187], v[92:95]
	v_mfma_f32_16x16x32_bf16 v[88:91], v[104:107], v[184:187], v[88:91]
	v_mfma_f32_16x16x32_bf16 v[76:79], v[96:99], v[192:195], v[76:79]
	v_mfma_f32_16x16x32_bf16 v[72:75], v[104:107], v[192:195], v[72:75]
	v_mfma_f32_16x16x32_bf16 v[140:143], v[100:103], v[172:175], v[140:143]
	v_mfma_f32_16x16x32_bf16 v[136:139], v[112:115], v[172:175], v[136:139]
	v_mfma_f32_16x16x32_bf16 v[124:127], v[100:103], v[180:183], v[124:127]
	v_mfma_f32_16x16x32_bf16 v[120:123], v[112:115], v[180:183], v[120:123]
	v_mfma_f32_16x16x32_bf16 v[92:95], v[100:103], v[188:191], v[92:95]
	v_mfma_f32_16x16x32_bf16 v[88:91], v[112:115], v[188:191], v[88:91]
	v_mfma_f32_16x16x32_bf16 v[76:79], v[100:103], v[196:199], v[76:79]
	v_mfma_f32_16x16x32_bf16 v[72:75], v[112:115], v[196:199], v[72:75]
	s_setprio 0
	s_barrier
	s_add_i32 s26, 0, 0x1c000
	s_add_i32 s27, s53, s37
	v_add_u32_e32 v169, s26, v163
	v_lshl_add_u64 v[216:217], v[216:217], 0, s[12:13]
	s_mov_b32 m0, s27
	ds_read_b128 v[200:203], v169
	ds_read_b128 v[204:207], v169 offset:1024
	ds_read_b128 v[208:211], v169 offset:2048
	ds_read_b128 v[212:215], v169 offset:3072
	global_load_lds_dwordx4 v[216:217], off
	v_lshl_add_u64 v[216:217], v[218:219], 0, s[12:13]
	s_add_i32 m0, s27, 0x2000
	s_nop 0
	global_load_lds_dwordx4 v[216:217], off
	s_barrier
	s_waitcnt lgkmcnt(0)
	s_setprio 1
	v_mfma_f32_16x16x32_bf16 v[132:135], v[200:203], v[152:155], v[132:135]
	v_mfma_f32_16x16x32_bf16 v[128:131], v[208:211], v[152:155], v[128:131]
	v_mfma_f32_16x16x32_bf16 v[116:119], v[200:203], v[176:179], v[116:119]
	v_mfma_f32_16x16x32_bf16 v[108:111], v[208:211], v[176:179], v[108:111]
	v_mfma_f32_16x16x32_bf16 v[84:87], v[200:203], v[184:187], v[84:87]
	v_mfma_f32_16x16x32_bf16 v[80:83], v[208:211], v[184:187], v[80:83]
	v_mfma_f32_16x16x32_bf16 v[68:71], v[200:203], v[192:195], v[68:71]
	v_mfma_f32_16x16x32_bf16 v[64:67], v[208:211], v[192:195], v[64:67]
	v_mfma_f32_16x16x32_bf16 v[132:135], v[204:207], v[172:175], v[132:135]
	v_mfma_f32_16x16x32_bf16 v[128:131], v[212:215], v[172:175], v[128:131]
	v_mfma_f32_16x16x32_bf16 v[116:119], v[204:207], v[180:183], v[116:119]
	v_mfma_f32_16x16x32_bf16 v[108:111], v[212:215], v[180:183], v[108:111]
	v_mfma_f32_16x16x32_bf16 v[84:87], v[204:207], v[188:191], v[84:87]
	v_mfma_f32_16x16x32_bf16 v[80:83], v[212:215], v[188:191], v[80:83]
	v_mfma_f32_16x16x32_bf16 v[68:71], v[204:207], v[196:199], v[68:71]
	v_mfma_f32_16x16x32_bf16 v[64:67], v[212:215], v[196:199], v[64:67]
	s_setprio 0
	s_mov_b32 m0, s49
	v_lshl_add_u64 v[216:217], v[220:221], 0, s[12:13]
	s_barrier
	ds_read_b128 v[152:155], v166 offset:49152
	ds_read_b128 v[172:175], v166 offset:50176
	ds_read_b128 v[176:179], v166 offset:51200
	ds_read_b128 v[180:183], v166 offset:52224
	ds_read_b128 v[184:187], v166 offset:53248
	ds_read_b128 v[188:191], v166 offset:54272
	ds_read_b128 v[192:195], v166 offset:55296
	ds_read_b128 v[196:199], v166 offset:56320
	global_load_lds_dwordx4 v[216:217], off
	v_lshl_add_u64 v[216:217], v[222:223], 0, s[12:13]
	s_mov_b32 m0, s50
	s_nop 0
	global_load_lds_dwordx4 v[216:217], off
	s_barrier
; #define PG8_STAGE(bufoff, gbase, voff) do { _Pragma("unroll") for (int _i = 0; _i < 2; ++_i) \
;         __builtin_amdgcn_global_load_lds((const unsigned*)((const char*)(gbase) + (voff)[_i]), (LAS unsigned*)(lds + (bufoff) + ldsw + _i * 8192), 16, 0, 0); } while (0)
; #define PG8_MMA(ai, bj, At, Bt) do { __builtin_amdgcn_s_setprio(1); _Pragma("unroll") for (int m = 0; m < 4; ++m) _Pragma("unroll") for (int n = 0; n < 2; ++n) _Pragma("unroll") for (int k = 0; k < 2; ++k) \
;         acc[ai][bj][m][n] = __builtin_amdgcn_mfma_f32_16x16x32_bf16(Bt[n][k], At[m][k], acc[ai][bj][m][n], 0, 0, 0); __builtin_amdgcn_s_setprio(0); } while (0)
; #define PG8_BAR __builtin_amdgcn_s_barrier()
; template <class Epi, class Sched>
; __device__ __forceinline__ void gemm_phase(LAS unsigned char* lds, const int K, const Sched& S, const Epi& E) {
;     ...
;             PG8_BAR; PG8_WAIT_L(0); PG8_MMA(1, 0, At, B0); PG8_BAR; PG8_SCHED;
;             PG8_STAGE(PG8_SB(1, 1), b3 + hstep, voffB);
;             PG8_WAIT_V(6); PG8_BAR; PG8_MMA(1, 1, At, B1); PG8_BAR;
;         }
;         if constexpr (!Epi::AFTER_DRAIN) E(acc, cur, wr, wc, fr, fq);
;         if (!has_next) break;
;     __device__ __forceinline__ void operator()(const f32x4 (&acc)[2][2][4][2], const Unit& u, int wr, int wc, int fr, int fq) const {
;         const int row0 = u.pm * BM + wr * 64 + fr, col0 = u.pn * BM + wc * 32 + 4 * fq, b = u.pm >> 3;
;         f32x4 gv[2][2];
; #pragma unroll
;         for (int bj = 0; bj < 2; ++bj)
; #pragma unroll
;             for (int n = 0; n < 2; ++n) gv[bj][n] = *(const f32x4*)(gate + (size_t)b * NMOD + col0 + bj * HALF + n * 16);
; #pragma unroll
;         for (int ai = 0; ai < 2; ++ai)
; #pragma unroll
;             for (int m = 0; m < 4; ++m) { const int row = row0 + ai * HALF + m * 16; const size_t off = (size_t)row * DM + col0; float s = 0.f;
; #pragma unroll
;                 for (int bj = 0; bj < 2; ++bj)
; #pragma unroll
;                     for (int n = 0; n < 2; ++n) { const f32x4 xv = *(const f32x4*)(base + off + bj * HALF + n * 16); const f32x4 o = xv + gv[bj][n] * acc[ai][bj][m][n];
;                         *(f32x4*)(out + off + bj * HALF + n * 16) = o; s += (o[0] * o[0] + o[1] * o[1]) + (o[2] * o[2] + o[3] * o[3]); }
;                 s += __shfl_xor(s, 16); s += __shfl_xor(s, 32);
;                 if (fq == 0) ssq[(size_t)row * 16 + u.pn * 4 + wc] = s; }
	s_waitcnt lgkmcnt(0)
	s_setprio 1
	v_mfma_f32_16x16x32_bf16 v[60:63], v[96:99], v[152:155], v[60:63]
	v_mfma_f32_16x16x32_bf16 v[56:59], v[104:107], v[152:155], v[56:59]
	v_mfma_f32_16x16x32_bf16 v[44:47], v[96:99], v[176:179], v[44:47]
	v_mfma_f32_16x16x32_bf16 v[40:43], v[104:107], v[176:179], v[40:43]
	v_mfma_f32_16x16x32_bf16 v[28:31], v[96:99], v[184:187], v[28:31]
	v_mfma_f32_16x16x32_bf16 v[24:27], v[104:107], v[184:187], v[24:27]
	v_mfma_f32_16x16x32_bf16 v[12:15], v[96:99], v[192:195], v[12:15]
	v_mfma_f32_16x16x32_bf16 v[8:11], v[104:107], v[192:195], v[8:11]
	v_mfma_f32_16x16x32_bf16 v[60:63], v[100:103], v[172:175], v[60:63]
	v_mfma_f32_16x16x32_bf16 v[56:59], v[112:115], v[172:175], v[56:59]
	v_mfma_f32_16x16x32_bf16 v[44:47], v[100:103], v[180:183], v[44:47]
	v_mfma_f32_16x16x32_bf16 v[40:43], v[112:115], v[180:183], v[40:43]
	v_mfma_f32_16x16x32_bf16 v[28:31], v[100:103], v[188:191], v[28:31]
	v_mfma_f32_16x16x32_bf16 v[24:27], v[112:115], v[188:191], v[24:27]
	v_mfma_f32_16x16x32_bf16 v[12:15], v[100:103], v[196:199], v[12:15]
	v_mfma_f32_16x16x32_bf16 v[8:11], v[112:115], v[196:199], v[8:11]
	s_setprio 0
	s_barrier
	s_add_u32 s24, s24, 0xb0080
	s_addc_u32 s25, s25, 0
	s_add_i32 s26, s26, s37
	v_lshl_add_u64 v[96:97], s[24:25], 0, v[144:145]
	s_mov_b32 m0, s26
	s_nop 0
	global_load_lds_dwordx4 v[96:97], off
	v_lshl_add_u64 v[96:97], s[24:25], 0, v[146:147]
	s_add_i32 m0, s26, 0x2000
	s_nop 0
	global_load_lds_dwordx4 v[96:97], off
	s_waitcnt vmcnt(6)
	s_barrier
	s_setprio 1
	v_mfma_f32_16x16x32_bf16 v[52:55], v[200:203], v[152:155], v[52:55]
	v_mfma_f32_16x16x32_bf16 v[48:51], v[208:211], v[152:155], v[48:51]
	v_mfma_f32_16x16x32_bf16 v[36:39], v[200:203], v[176:179], v[36:39]
	v_mfma_f32_16x16x32_bf16 v[32:35], v[208:211], v[176:179], v[32:35]
	v_mfma_f32_16x16x32_bf16 v[20:23], v[200:203], v[184:187], v[20:23]
	v_mfma_f32_16x16x32_bf16 v[16:19], v[208:211], v[184:187], v[16:19]
	v_mfma_f32_16x16x32_bf16 v[4:7], v[200:203], v[192:195], v[4:7]
	v_mfma_f32_16x16x32_bf16 v[0:3], v[208:211], v[192:195], v[0:3]
	v_mfma_f32_16x16x32_bf16 v[52:55], v[204:207], v[172:175], v[52:55]
	v_mfma_f32_16x16x32_bf16 v[48:51], v[212:215], v[172:175], v[48:51]
	v_mfma_f32_16x16x32_bf16 v[36:39], v[204:207], v[180:183], v[36:39]
	v_mfma_f32_16x16x32_bf16 v[32:35], v[212:215], v[180:183], v[32:35]
	v_mfma_f32_16x16x32_bf16 v[20:23], v[204:207], v[188:191], v[20:23]
	v_mfma_f32_16x16x32_bf16 v[16:19], v[212:215], v[188:191], v[16:19]
	v_mfma_f32_16x16x32_bf16 v[4:7], v[204:207], v[196:199], v[4:7]
	v_mfma_f32_16x16x32_bf16 v[0:3], v[212:215], v[196:199], v[0:3]
	s_setprio 0
	s_add_i32 s52, s52, 2
	s_add_u32 s22, s22, 0x100
	s_addc_u32 s23, s23, 0
	s_add_u32 s11, s11, 0x100
	s_addc_u32 s33, s33, 0
	s_cmp_gt_u32 s52, 41
	s_barrier
	s_cbranch_scc0 .LBB0_1081
	s_ashr_i32 s11, s10, 3
	v_lshl_add_u32 v154, s10, 8, v162
	v_lshl_or_b32 v152, s8, 8, v164
	s_mul_hi_i32 s23, s11, 0x6000
	s_mulk_i32 s11, 0x6000
	v_ashrrev_i32_e32 v155, 31, v154
	s_add_u32 s22, s46, s11
	v_ashrrev_i32_e32 v153, 31, v152
	v_lshlrev_b64 v[98:99], 12, v[154:155]
	s_addc_u32 s23, s47, s23
	v_lshlrev_b64 v[96:97], 2, v[152:153]
	v_lshl_add_u64 v[98:99], s[30:31], 0, v[98:99]
	v_lshl_add_u64 v[104:105], s[22:23], 0, v[96:97]
	v_lshl_add_u64 v[188:189], v[98:99], 0, v[96:97]
	global_load_dwordx4 v[172:175], v[188:189], off
	global_load_dwordx4 v[100:103], v[104:105], off
	global_load_dwordx4 v[96:99], v[104:105], off offset:64
	global_load_dwordx4 v[176:179], v[188:189], off offset:64
	global_load_dwordx4 v[180:183], v[188:189], off offset:512
	global_load_dwordx4 v[112:115], v[104:105], off offset:512
	s_nop 0
	global_load_dwordx4 v[104:107], v[104:105], off offset:576
	s_nop 0
	global_load_dwordx4 v[184:187], v[188:189], off offset:576
	v_and_b32_e32 v190, 64, v168
	v_xor_b32_e32 v169, 16, v168
	v_add_u32_e32 v190, 64, v190
	v_cmp_lt_i32_e32 vcc, v169, v190
	v_xor_b32_e32 v191, 32, v168
	s_lshl_b32 s22, s8, 2
	v_cndmask_b32_e32 v169, v168, v169, vcc
	v_lshlrev_b32_e32 v169, 2, v169
	v_cmp_lt_i32_e32 vcc, v191, v190
	s_ashr_i32 s23, s22, 31
	s_waitcnt vmcnt(0)
	v_pk_fma_f32 v[142:143], v[142:143], v[102:103], v[174:175]
	v_pk_fma_f32 v[140:141], v[140:141], v[100:101], v[172:173]
	v_pk_fma_f32 v[138:139], v[138:139], v[98:99], v[178:179]
	v_pk_fma_f32 v[136:137], v[136:137], v[96:97], v[176:177]
	v_pk_fma_f32 v[134:135], v[134:135], v[114:115], v[182:183]
	v_pk_fma_f32 v[132:133], v[132:133], v[112:113], v[180:181]
	v_pk_fma_f32 v[174:175], v[130:131], v[106:107], v[186:187]
	v_pk_fma_f32 v[172:173], v[128:129], v[104:105], v[184:185]
	v_mul_f32_e32 v128, v141, v141
	v_mul_f32_e32 v129, v143, v143
	v_mul_f32_e32 v130, v137, v137
	v_mul_f32_e32 v131, v139, v139
	v_mul_f32_e32 v176, v133, v133
	v_mul_f32_e32 v177, v135, v135
	v_fmac_f32_e32 v128, v140, v140
	v_fmac_f32_e32 v129, v142, v142
	v_fmac_f32_e32 v130, v136, v136
	v_fmac_f32_e32 v131, v138, v138
	v_mul_f32_e32 v178, v173, v173
	v_mul_f32_e32 v179, v175, v175
	v_fmac_f32_e32 v176, v132, v132
	v_fmac_f32_e32 v177, v134, v134
	v_add_f32_e32 v128, v128, v129
	v_add_f32_e32 v129, v130, v131
	v_fmac_f32_e32 v178, v172, v172
	v_fmac_f32_e32 v179, v174, v174
	v_add_f32_e32 v130, v176, v177
	v_add_f32_e32 v128, v128, v129
	v_add_f32_e32 v131, v178, v179
	v_add_f32_e32 v128, v128, v130
	v_add_f32_e32 v128, v128, v131
	ds_bpermute_b32 v129, v169, v128
	v_cndmask_b32_e32 v130, v168, v191, vcc
	v_lshlrev_b32_e32 v130, 2, v130
	global_store_dwordx4 v[188:189], v[140:143], off
	global_store_dwordx4 v[188:189], v[136:139], off offset:64
	global_store_dwordx4 v[188:189], v[132:135], off offset:512
	global_store_dwordx4 v[188:189], v[172:175], off offset:576
	s_waitcnt lgkmcnt(0)
	v_add_f32_e32 v128, v128, v129
	ds_bpermute_b32 v129, v130, v128
	s_and_saveexec_b64 s[24:25], s[0:1]
	s_cbranch_execz .LBB0_1084
	v_lshlrev_b64 v[132:133], 6, v[154:155]
	v_lshl_add_u64 v[132:133], s[6:7], 0, v[132:133]
	v_lshl_add_u64 v[132:133], s[22:23], 2, v[132:133]
	s_lshl_b32 s8, s48, 2
	v_lshl_add_u64 v[132:133], v[132:133], 0, s[8:9]
	s_waitcnt lgkmcnt(0)
	v_add_f32_e32 v128, v128, v129
	global_store_dword v[132:133], v128, off

; #define PG8_STAGE(bufoff, gbase, voff) do { _Pragma("unroll") for (int _i = 0; _i < 2; ++_i) \
;         __builtin_amdgcn_global_load_lds((const unsigned*)((const char*)(gbase) + (voff)[_i]), (LAS unsigned*)(lds + (bufoff) + ldsw + _i * 8192), 16, 0, 0); } while (0)
; #define PG8_LDA(dst, b, h) do { _Pragma("unroll") for (int m = 0; m < 4; ++m) _Pragma("unroll") for (int k = 0; k < 2; ++k) dst[m][k] = *(const LAS bf16x8*)(lds + PG8_SA(b, h) + aoff + m * 2048 + k * 1024); } while (0)
; #define PG8_LDB(dst, b, h) do { _Pragma("unroll") for (int n = 0; n < 2; ++n) _Pragma("unroll") for (int k = 0; k < 2; ++k) dst[n][k] = *(const LAS bf16x8*)(lds + PG8_SB(b, h) + boff + n * 2048 + k * 1024); } while (0)
; #define PG8_MMA(ai, bj, At, Bt) do { __builtin_amdgcn_s_setprio(1); _Pragma("unroll") for (int m = 0; m < 4; ++m) _Pragma("unroll") for (int n = 0; n < 2; ++n) _Pragma("unroll") for (int k = 0; k < 2; ++k) \
;         acc[ai][bj][m][n] = __builtin_amdgcn_mfma_f32_16x16x32_bf16(Bt[n][k], At[m][k], acc[ai][bj][m][n], 0, 0, 0); __builtin_amdgcn_s_setprio(0); } while (0)
; #define PG8_WAIT_L(n) asm volatile("s_waitcnt lgkmcnt(" #n ")" ::: "memory")
; #define PG8_BAR __builtin_amdgcn_s_barrier()
; #define PG8_SCHED __builtin_amdgcn_sched_barrier(0)
; template <class Epi, class Sched>
; __device__ __forceinline__ void gemm_phase(LAS unsigned char* lds, const int K, const Sched& S, const Epi& E) {
;     ...
;             const bool last = (t == nt - 2);
;             const char* a1 = cA + (size_t)(t + 1) * kstep;
;             const char* a2 = last ? nA : cA + (size_t)(t + 2) * kstep; const char* b2 = last ? nB : cB + (size_t)(t + 2) * kstep;
;             const char* a3 = a2 + kstep; const char* b3 = b2 + kstep;
;             PG8_LDB(B0, 0, 0); PG8_SCHED; PG8_LDA(At, 0, 0); PG8_STAGE(PG8_SA(1, 1), a1 + hstepA, voffA);
;             PG8_WAIT_L(8); PG8_BAR; PG8_WAIT_L(0); PG8_MMA(0, 0, At, B0); PG8_BAR; PG8_SCHED;
;             PG8_LDB(B1, 0, 1); PG8_STAGE(PG8_SB(0, 0), b2, voffB);
;             PG8_BAR; PG8_WAIT_L(0); PG8_MMA(0, 1, At, B1); PG8_BAR;
;             PG8_LDA(At, 0, 1); PG8_STAGE(PG8_SA(0, 0), a2, voffA);
;             PG8_BAR; PG8_WAIT_L(0); PG8_MMA(1, 0, At, B0); PG8_BAR; PG8_SCHED;
.Lpeel_p9:
	v_add_u32_e32 v139, s53, v137
	s_add_u32 s26, s0, s24
	ds_read_b128 v[140:143], v139
	ds_read_b128 v[148:151], v139 offset:1024
	ds_read_b128 v[158:161], v139 offset:2048
	ds_read_b128 v[162:165], v139 offset:3072
	s_addc_u32 s27, s1, s25
	s_add_u32 s26, s26, 0x100
	s_addc_u32 s27, s27, 0
	s_add_u32 s71, s11, s24
	s_addc_u32 s72, s69, s25
	s_cmpk_eq_i32 s24, 0x1500
	s_cselect_b32 s37, s23, s27
	s_cselect_b32 s36, s22, s26
	s_cselect_b32 s27, s17, s72
	s_cselect_b32 s26, s16, s71
	s_mov_b32 m0, s55
	v_lshl_add_u64 v[154:155], v[132:133], 0, s[24:25]
	ds_read_b128 v[166:169], v138
	ds_read_b128 v[172:175], v138 offset:1024
	ds_read_b128 v[176:179], v138 offset:2048
	ds_read_b128 v[180:183], v138 offset:3072
	ds_read_b128 v[184:187], v138 offset:4096
	ds_read_b128 v[188:191], v138 offset:5120
	ds_read_b128 v[192:195], v138 offset:6144
	ds_read_b128 v[196:199], v138 offset:7168
	global_load_lds_dwordx4 v[154:155], off
	v_lshl_add_u64 v[154:155], v[134:135], 0, s[24:25]
	s_mov_b32 m0, s56
	s_nop 0
	global_load_lds_dwordx4 v[154:155], off
	s_waitcnt lgkmcnt(8)
	s_barrier
	s_waitcnt lgkmcnt(0)
	s_setprio 1
	v_mfma_f32_16x16x32_bf16 v[120:123], v[140:143], v[166:169], 0
	v_mfma_f32_16x16x32_bf16 v[124:127], v[158:161], v[166:169], 0
	v_mfma_f32_16x16x32_bf16 v[108:111], v[140:143], v[176:179], 0
	v_mfma_f32_16x16x32_bf16 v[104:107], v[158:161], v[176:179], 0
	v_mfma_f32_16x16x32_bf16 v[92:95], v[140:143], v[184:187], 0
	v_mfma_f32_16x16x32_bf16 v[88:91], v[158:161], v[184:187], 0
	v_mfma_f32_16x16x32_bf16 v[76:79], v[140:143], v[192:195], 0
	v_mfma_f32_16x16x32_bf16 v[72:75], v[158:161], v[192:195], 0
	v_mfma_f32_16x16x32_bf16 v[120:123], v[148:151], v[172:175], v[120:123]
	v_mfma_f32_16x16x32_bf16 v[124:127], v[162:165], v[172:175], v[124:127]
	v_mfma_f32_16x16x32_bf16 v[108:111], v[148:151], v[180:183], v[108:111]
	v_mfma_f32_16x16x32_bf16 v[104:107], v[162:165], v[180:183], v[104:107]
	v_mfma_f32_16x16x32_bf16 v[92:95], v[148:151], v[188:191], v[92:95]
	v_mfma_f32_16x16x32_bf16 v[88:91], v[162:165], v[188:191], v[88:91]
	v_mfma_f32_16x16x32_bf16 v[76:79], v[148:151], v[196:199], v[76:79]
	v_mfma_f32_16x16x32_bf16 v[72:75], v[162:165], v[196:199], v[72:75]
	s_setprio 0
	s_barrier
	s_mov_b32 m0, s57
	v_add_u32_e32 v139, s54, v137
	v_lshl_add_u64 v[154:155], s[26:27], 0, v[144:145]
	ds_read_b128 v[200:203], v139
	ds_read_b128 v[204:207], v139 offset:1024
	ds_read_b128 v[208:211], v139 offset:2048
	ds_read_b128 v[212:215], v139 offset:3072
	global_load_lds_dwordx4 v[154:155], off
	v_lshl_add_u64 v[216:217], s[26:27], 0, v[146:147]
	s_mov_b32 m0, s58
	s_nop 0
	global_load_lds_dwordx4 v[216:217], off
	s_barrier
	s_waitcnt lgkmcnt(0)
	s_setprio 1
	v_mfma_f32_16x16x32_bf16 v[116:119], v[200:203], v[166:169], 0
	v_mfma_f32_16x16x32_bf16 v[112:115], v[208:211], v[166:169], 0
	v_mfma_f32_16x16x32_bf16 v[100:103], v[200:203], v[176:179], 0
	v_mfma_f32_16x16x32_bf16 v[96:99], v[208:211], v[176:179], 0
	v_mfma_f32_16x16x32_bf16 v[84:87], v[200:203], v[184:187], 0
	v_mfma_f32_16x16x32_bf16 v[80:83], v[208:211], v[184:187], 0
	v_mfma_f32_16x16x32_bf16 v[68:71], v[200:203], v[192:195], 0
	v_mfma_f32_16x16x32_bf16 v[64:67], v[208:211], v[192:195], 0
	v_mfma_f32_16x16x32_bf16 v[116:119], v[204:207], v[172:175], v[116:119]
	v_mfma_f32_16x16x32_bf16 v[112:115], v[212:215], v[172:175], v[112:115]
	v_mfma_f32_16x16x32_bf16 v[100:103], v[204:207], v[180:183], v[100:103]
	v_mfma_f32_16x16x32_bf16 v[96:99], v[212:215], v[180:183], v[96:99]
	v_mfma_f32_16x16x32_bf16 v[84:87], v[204:207], v[188:191], v[84:87]
	v_mfma_f32_16x16x32_bf16 v[80:83], v[212:215], v[188:191], v[80:83]
	v_mfma_f32_16x16x32_bf16 v[68:71], v[204:207], v[196:199], v[68:71]
	v_mfma_f32_16x16x32_bf16 v[64:67], v[212:215], v[196:199], v[64:67]
	s_setprio 0
	s_mov_b32 m0, s46
	v_lshl_add_u64 v[218:219], s[36:37], 0, v[144:145]
	s_barrier
	ds_read_b128 v[166:169], v138 offset:16384
	ds_read_b128 v[172:175], v138 offset:17408
	ds_read_b128 v[176:179], v138 offset:18432
	ds_read_b128 v[180:183], v138 offset:19456
	ds_read_b128 v[184:187], v138 offset:20480
	ds_read_b128 v[188:191], v138 offset:21504
	ds_read_b128 v[192:195], v138 offset:22528
	ds_read_b128 v[196:199], v138 offset:23552
	global_load_lds_dwordx4 v[218:219], off
	v_lshl_add_u64 v[220:221], s[36:37], 0, v[146:147]
	s_mov_b32 m0, s47
	s_nop 0
	global_load_lds_dwordx4 v[220:221], off
	s_barrier
	s_waitcnt lgkmcnt(0)
	s_setprio 1
	v_mfma_f32_16x16x32_bf16 v[60:63], v[140:143], v[166:169], 0
	v_mfma_f32_16x16x32_bf16 v[56:59], v[158:161], v[166:169], 0
	v_mfma_f32_16x16x32_bf16 v[44:47], v[140:143], v[176:179], 0
	v_mfma_f32_16x16x32_bf16 v[40:43], v[158:161], v[176:179], 0
	v_mfma_f32_16x16x32_bf16 v[28:31], v[140:143], v[184:187], 0
	v_mfma_f32_16x16x32_bf16 v[24:27], v[158:161], v[184:187], 0
	v_mfma_f32_16x16x32_bf16 v[12:15], v[140:143], v[192:195], 0
	v_mfma_f32_16x16x32_bf16 v[8:11], v[158:161], v[192:195], 0
	v_mfma_f32_16x16x32_bf16 v[60:63], v[148:151], v[172:175], v[60:63]
	v_mfma_f32_16x16x32_bf16 v[56:59], v[162:165], v[172:175], v[56:59]
	v_mfma_f32_16x16x32_bf16 v[44:47], v[148:151], v[180:183], v[44:47]
	v_mfma_f32_16x16x32_bf16 v[40:43], v[162:165], v[180:183], v[40:43]
	v_mfma_f32_16x16x32_bf16 v[28:31], v[148:151], v[188:191], v[28:31]
	v_mfma_f32_16x16x32_bf16 v[24:27], v[162:165], v[188:191], v[24:27]
	v_mfma_f32_16x16x32_bf16 v[12:15], v[148:151], v[196:199], v[12:15]
	v_mfma_f32_16x16x32_bf16 v[8:11], v[162:165], v[196:199], v[8:11]
	s_setprio 0
	s_barrier
; #define PG8_STAGE(bufoff, gbase, voff) do { _Pragma("unroll") for (int _i = 0; _i < 2; ++_i) \
;         __builtin_amdgcn_global_load_lds((const unsigned*)((const char*)(gbase) + (voff)[_i]), (LAS unsigned*)(lds + (bufoff) + ldsw + _i * 8192), 16, 0, 0); } while (0)
; #define PG8_LDA(dst, b, h) do { _Pragma("unroll") for (int m = 0; m < 4; ++m) _Pragma("unroll") for (int k = 0; k < 2; ++k) dst[m][k] = *(const LAS bf16x8*)(lds + PG8_SA(b, h) + aoff + m * 2048 + k * 1024); } while (0)
; #define PG8_LDB(dst, b, h) do { _Pragma("unroll") for (int n = 0; n < 2; ++n) _Pragma("unroll") for (int k = 0; k < 2; ++k) dst[n][k] = *(const LAS bf16x8*)(lds + PG8_SB(b, h) + boff + n * 2048 + k * 1024); } while (0)
; #define PG8_MMA(ai, bj, At, Bt) do { __builtin_amdgcn_s_setprio(1); _Pragma("unroll") for (int m = 0; m < 4; ++m) _Pragma("unroll") for (int n = 0; n < 2; ++n) _Pragma("unroll") for (int k = 0; k < 2; ++k) \
;         acc[ai][bj][m][n] = __builtin_amdgcn_mfma_f32_16x16x32_bf16(Bt[n][k], At[m][k], acc[ai][bj][m][n], 0, 0, 0); __builtin_amdgcn_s_setprio(0); } while (0)
; #define PG8_WAIT_V(n) asm volatile("s_waitcnt vmcnt(" #n ")" ::: "memory")
; #define PG8_WAIT_L(n) asm volatile("s_waitcnt lgkmcnt(" #n ")" ::: "memory")
; #define PG8_BAR __builtin_amdgcn_s_barrier()
; #define PG8_SCHED __builtin_amdgcn_sched_barrier(0)
; template <class Epi, class Sched>
; __device__ __forceinline__ void gemm_phase(LAS unsigned char* lds, const int K, const Sched& S, const Epi& E) {
;     ...
;             PG8_STAGE(PG8_SB(0, 1), b2 + hstep, voffB);
;             PG8_WAIT_V(6); PG8_BAR; PG8_MMA(1, 1, At, B1); PG8_BAR;
;             PG8_LDB(B0, 1, 0); PG8_SCHED; PG8_LDA(At, 1, 0); PG8_STAGE(PG8_SA(0, 1), a2 + hstepA, voffA);
;             PG8_WAIT_L(8); PG8_BAR; PG8_WAIT_L(0); PG8_MMA(0, 0, At, B0); PG8_BAR; PG8_SCHED;
;             PG8_LDB(B1, 1, 1); PG8_STAGE(PG8_SB(1, 0), b3, voffB);
;             PG8_BAR; PG8_WAIT_L(0); PG8_MMA(0, 1, At, B1); PG8_BAR;
;             PG8_LDA(At, 1, 1); PG8_STAGE(PG8_SA(1, 0), a3, voffA);
	s_add_u32 s72, s26, 0xb0000
	s_addc_u32 s73, s27, 0
	s_mov_b32 m0, s59
	v_lshl_add_u64 v[140:141], s[72:73], 0, v[144:145]
	global_load_lds_dwordx4 v[140:141], off
	v_lshl_add_u64 v[140:141], s[72:73], 0, v[146:147]
	s_mov_b32 m0, s60
	s_nop 0
	global_load_lds_dwordx4 v[140:141], off
	s_waitcnt vmcnt(6)
	s_barrier
	s_setprio 1
	v_mfma_f32_16x16x32_bf16 v[52:55], v[200:203], v[166:169], 0
	v_mfma_f32_16x16x32_bf16 v[48:51], v[208:211], v[166:169], 0
	v_mfma_f32_16x16x32_bf16 v[36:39], v[200:203], v[176:179], 0
	v_mfma_f32_16x16x32_bf16 v[32:35], v[208:211], v[176:179], 0
	v_mfma_f32_16x16x32_bf16 v[20:23], v[200:203], v[184:187], 0
	v_mfma_f32_16x16x32_bf16 v[16:19], v[208:211], v[184:187], 0
	v_mfma_f32_16x16x32_bf16 v[4:7], v[200:203], v[192:195], 0
	v_mfma_f32_16x16x32_bf16 v[0:3], v[208:211], v[192:195], 0
	v_mfma_f32_16x16x32_bf16 v[52:55], v[204:207], v[172:175], v[52:55]
	v_mfma_f32_16x16x32_bf16 v[48:51], v[212:215], v[172:175], v[48:51]
	v_mfma_f32_16x16x32_bf16 v[36:39], v[204:207], v[180:183], v[36:39]
	v_mfma_f32_16x16x32_bf16 v[32:35], v[212:215], v[180:183], v[32:35]
	v_mfma_f32_16x16x32_bf16 v[20:23], v[204:207], v[188:191], v[20:23]
	v_mfma_f32_16x16x32_bf16 v[16:19], v[212:215], v[188:191], v[16:19]
	v_mfma_f32_16x16x32_bf16 v[4:7], v[204:207], v[196:199], v[4:7]
	v_mfma_f32_16x16x32_bf16 v[0:3], v[212:215], v[196:199], v[0:3]
	s_setprio 0
	v_add_u32_e32 v139, s61, v137
	s_barrier
	ds_read_b128 v[140:143], v139
	ds_read_b128 v[148:151], v139 offset:1024
	ds_read_b128 v[158:161], v139 offset:2048
	ds_read_b128 v[162:165], v139 offset:3072
	s_add_u32 s36, s36, 0xb0000
	s_addc_u32 s37, s37, 0
	s_mov_b32 m0, s48
	v_lshl_add_u64 v[200:201], s[36:37], 0, v[144:145]
	ds_read_b128 v[166:169], v138 offset:32768
	ds_read_b128 v[172:175], v138 offset:33792
	ds_read_b128 v[176:179], v138 offset:34816
	ds_read_b128 v[180:183], v138 offset:35840
	ds_read_b128 v[184:187], v138 offset:36864
	ds_read_b128 v[188:191], v138 offset:37888
	ds_read_b128 v[192:195], v138 offset:38912
	ds_read_b128 v[196:199], v138 offset:39936
	global_load_lds_dwordx4 v[200:201], off
	v_lshl_add_u64 v[200:201], s[36:37], 0, v[146:147]
	s_mov_b32 m0, s49
	s_nop 0
	global_load_lds_dwordx4 v[200:201], off
	s_waitcnt lgkmcnt(8)
	s_barrier
	s_waitcnt lgkmcnt(0)
	s_setprio 1
	v_mfma_f32_16x16x32_bf16 v[120:123], v[140:143], v[166:169], v[120:123]
	v_mfma_f32_16x16x32_bf16 v[124:127], v[158:161], v[166:169], v[124:127]
	v_mfma_f32_16x16x32_bf16 v[108:111], v[140:143], v[176:179], v[108:111]
	v_mfma_f32_16x16x32_bf16 v[104:107], v[158:161], v[176:179], v[104:107]
	v_mfma_f32_16x16x32_bf16 v[92:95], v[140:143], v[184:187], v[92:95]
	v_mfma_f32_16x16x32_bf16 v[88:91], v[158:161], v[184:187], v[88:91]
	v_mfma_f32_16x16x32_bf16 v[76:79], v[140:143], v[192:195], v[76:79]
	v_mfma_f32_16x16x32_bf16 v[72:75], v[158:161], v[192:195], v[72:75]
	v_mfma_f32_16x16x32_bf16 v[120:123], v[148:151], v[172:175], v[120:123]
	v_mfma_f32_16x16x32_bf16 v[124:127], v[162:165], v[172:175], v[124:127]
	v_mfma_f32_16x16x32_bf16 v[108:111], v[148:151], v[180:183], v[108:111]
	v_mfma_f32_16x16x32_bf16 v[104:107], v[162:165], v[180:183], v[104:107]
	v_mfma_f32_16x16x32_bf16 v[92:95], v[148:151], v[188:191], v[92:95]
	v_mfma_f32_16x16x32_bf16 v[88:91], v[162:165], v[188:191], v[88:91]
	v_mfma_f32_16x16x32_bf16 v[76:79], v[148:151], v[196:199], v[76:79]
	v_mfma_f32_16x16x32_bf16 v[72:75], v[162:165], v[196:199], v[72:75]
	s_setprio 0
	s_barrier
	s_mov_b32 m0, s63
	v_add_u32_e32 v139, s62, v137
	v_lshl_add_u64 v[154:155], v[154:155], 0, s[12:13]
	ds_read_b128 v[200:203], v139
	ds_read_b128 v[204:207], v139 offset:1024
	ds_read_b128 v[208:211], v139 offset:2048
	ds_read_b128 v[212:215], v139 offset:3072
	global_load_lds_dwordx4 v[154:155], off
	v_lshl_add_u64 v[154:155], v[216:217], 0, s[12:13]
	s_mov_b32 m0, s64
	s_nop 0
	global_load_lds_dwordx4 v[154:155], off
	s_barrier
	s_waitcnt lgkmcnt(0)
	s_setprio 1
	v_mfma_f32_16x16x32_bf16 v[116:119], v[200:203], v[166:169], v[116:119]
	v_mfma_f32_16x16x32_bf16 v[112:115], v[208:211], v[166:169], v[112:115]
	v_mfma_f32_16x16x32_bf16 v[100:103], v[200:203], v[176:179], v[100:103]
	v_mfma_f32_16x16x32_bf16 v[96:99], v[208:211], v[176:179], v[96:99]
	v_mfma_f32_16x16x32_bf16 v[84:87], v[200:203], v[184:187], v[84:87]
	v_mfma_f32_16x16x32_bf16 v[80:83], v[208:211], v[184:187], v[80:83]
	v_mfma_f32_16x16x32_bf16 v[68:71], v[200:203], v[192:195], v[68:71]
	v_mfma_f32_16x16x32_bf16 v[64:67], v[208:211], v[192:195], v[64:67]
	v_mfma_f32_16x16x32_bf16 v[116:119], v[204:207], v[172:175], v[116:119]
	v_mfma_f32_16x16x32_bf16 v[112:115], v[212:215], v[172:175], v[112:115]
	v_mfma_f32_16x16x32_bf16 v[100:103], v[204:207], v[180:183], v[100:103]
	v_mfma_f32_16x16x32_bf16 v[96:99], v[212:215], v[180:183], v[96:99]
	v_mfma_f32_16x16x32_bf16 v[84:87], v[204:207], v[188:191], v[84:87]
	v_mfma_f32_16x16x32_bf16 v[80:83], v[212:215], v[188:191], v[80:83]
	v_mfma_f32_16x16x32_bf16 v[68:71], v[204:207], v[196:199], v[68:71]
	v_mfma_f32_16x16x32_bf16 v[64:67], v[212:215], v[196:199], v[64:67]
	s_setprio 0
	s_mov_b32 m0, s33
	v_lshl_add_u64 v[154:155], v[218:219], 0, s[12:13]
	s_barrier
	ds_read_b128 v[166:169], v138 offset:49152
	ds_read_b128 v[172:175], v138 offset:50176
	ds_read_b128 v[176:179], v138 offset:51200
	ds_read_b128 v[180:183], v138 offset:52224
	ds_read_b128 v[184:187], v138 offset:53248
	ds_read_b128 v[188:191], v138 offset:54272
	ds_read_b128 v[192:195], v138 offset:55296
	ds_read_b128 v[196:199], v138 offset:56320
	global_load_lds_dwordx4 v[154:155], off
	v_lshl_add_u64 v[154:155], v[220:221], 0, s[12:13]
	s_mov_b32 m0, s52
	s_nop 0
	global_load_lds_dwordx4 v[154:155], off
	s_barrier
; #define PG8_STAGE(bufoff, gbase, voff) do { _Pragma("unroll") for (int _i = 0; _i < 2; ++_i) \
;         __builtin_amdgcn_global_load_lds((const unsigned*)((const char*)(gbase) + (voff)[_i]), (LAS unsigned*)(lds + (bufoff) + ldsw + _i * 8192), 16, 0, 0); } while (0)
; #define PG8_LDA(dst, b, h) do { _Pragma("unroll") for (int m = 0; m < 4; ++m) _Pragma("unroll") for (int k = 0; k < 2; ++k) dst[m][k] = *(const LAS bf16x8*)(lds + PG8_SA(b, h) + aoff + m * 2048 + k * 1024); } while (0)
; #define PG8_LDB(dst, b, h) do { _Pragma("unroll") for (int n = 0; n < 2; ++n) _Pragma("unroll") for (int k = 0; k < 2; ++k) dst[n][k] = *(const LAS bf16x8*)(lds + PG8_SB(b, h) + boff + n * 2048 + k * 1024); } while (0)
; #define PG8_MMA(ai, bj, At, Bt) do { __builtin_amdgcn_s_setprio(1); _Pragma("unroll") for (int m = 0; m < 4; ++m) _Pragma("unroll") for (int n = 0; n < 2; ++n) _Pragma("unroll") for (int k = 0; k < 2; ++k) \
;         acc[ai][bj][m][n] = __builtin_amdgcn_mfma_f32_16x16x32_bf16(Bt[n][k], At[m][k], acc[ai][bj][m][n], 0, 0, 0); __builtin_amdgcn_s_setprio(0); } while (0)
; #define PG8_WAIT_V(n) asm volatile("s_waitcnt vmcnt(" #n ")" ::: "memory")
; #define PG8_WAIT_L(n) asm volatile("s_waitcnt lgkmcnt(" #n ")" ::: "memory")
; #define PG8_BAR __builtin_amdgcn_s_barrier()
; #define PG8_SCHED __builtin_amdgcn_sched_barrier(0)
; template <class Epi, class Sched>
; __device__ __forceinline__ void gemm_phase(LAS unsigned char* lds, const int K, const Sched& S, const Epi& E) {
;     ...
;         for (int t = 0; t < nt; t += 2) {
;             const bool last = (t == nt - 2);
;             const char* a1 = cA + (size_t)(t + 1) * kstep;
;             const char* a2 = last ? nA : cA + (size_t)(t + 2) * kstep; const char* b2 = last ? nB : cB + (size_t)(t + 2) * kstep;
;             const char* a3 = a2 + kstep; const char* b3 = b2 + kstep;
;             PG8_LDB(B0, 0, 0); PG8_SCHED; PG8_LDA(At, 0, 0); PG8_STAGE(PG8_SA(1, 1), a1 + hstepA, voffA);
;             PG8_WAIT_L(8); PG8_BAR; PG8_WAIT_L(0); PG8_MMA(0, 0, At, B0); PG8_BAR; PG8_SCHED;
;             PG8_LDB(B1, 0, 1); PG8_STAGE(PG8_SB(0, 0), b2, voffB);
;     ...
;             PG8_BAR; PG8_WAIT_L(0); PG8_MMA(1, 0, At, B0); PG8_BAR; PG8_SCHED;
;             PG8_STAGE(PG8_SB(1, 1), b3 + hstep, voffB);
;             PG8_WAIT_V(6); PG8_BAR; PG8_MMA(1, 1, At, B1); PG8_BAR;
	s_waitcnt lgkmcnt(0)
	s_setprio 1
	v_mfma_f32_16x16x32_bf16 v[60:63], v[140:143], v[166:169], v[60:63]
	v_mfma_f32_16x16x32_bf16 v[56:59], v[158:161], v[166:169], v[56:59]
	v_mfma_f32_16x16x32_bf16 v[44:47], v[140:143], v[176:179], v[44:47]
	v_mfma_f32_16x16x32_bf16 v[40:43], v[158:161], v[176:179], v[40:43]
	v_mfma_f32_16x16x32_bf16 v[28:31], v[140:143], v[184:187], v[28:31]
	v_mfma_f32_16x16x32_bf16 v[24:27], v[158:161], v[184:187], v[24:27]
	v_mfma_f32_16x16x32_bf16 v[12:15], v[140:143], v[192:195], v[12:15]
	v_mfma_f32_16x16x32_bf16 v[8:11], v[158:161], v[192:195], v[8:11]
	v_mfma_f32_16x16x32_bf16 v[60:63], v[148:151], v[172:175], v[60:63]
	v_mfma_f32_16x16x32_bf16 v[56:59], v[162:165], v[172:175], v[56:59]
	v_mfma_f32_16x16x32_bf16 v[44:47], v[148:151], v[180:183], v[44:47]
	v_mfma_f32_16x16x32_bf16 v[40:43], v[162:165], v[180:183], v[40:43]
	v_mfma_f32_16x16x32_bf16 v[28:31], v[148:151], v[188:191], v[28:31]
	v_mfma_f32_16x16x32_bf16 v[24:27], v[162:165], v[188:191], v[24:27]
	v_mfma_f32_16x16x32_bf16 v[12:15], v[148:151], v[196:199], v[12:15]
	v_mfma_f32_16x16x32_bf16 v[8:11], v[162:165], v[196:199], v[8:11]
	s_setprio 0
	s_barrier
	s_add_u32 s26, s26, 0xb0080
	s_addc_u32 s27, s27, 0
	s_mov_b32 m0, s65
	v_lshl_add_u64 v[140:141], s[26:27], 0, v[144:145]
	global_load_lds_dwordx4 v[140:141], off
	v_lshl_add_u64 v[140:141], s[26:27], 0, v[146:147]
	s_mov_b32 m0, s66
	s_nop 0
	global_load_lds_dwordx4 v[140:141], off
	s_waitcnt vmcnt(6)
	s_barrier
	s_setprio 1
	v_mfma_f32_16x16x32_bf16 v[52:55], v[200:203], v[166:169], v[52:55]
	v_mfma_f32_16x16x32_bf16 v[48:51], v[208:211], v[166:169], v[48:51]
	v_mfma_f32_16x16x32_bf16 v[36:39], v[200:203], v[176:179], v[36:39]
	v_mfma_f32_16x16x32_bf16 v[32:35], v[208:211], v[176:179], v[32:35]
	v_mfma_f32_16x16x32_bf16 v[20:23], v[200:203], v[184:187], v[20:23]
	v_mfma_f32_16x16x32_bf16 v[16:19], v[208:211], v[184:187], v[16:19]
	v_mfma_f32_16x16x32_bf16 v[4:7], v[200:203], v[192:195], v[4:7]
	v_mfma_f32_16x16x32_bf16 v[0:3], v[208:211], v[192:195], v[0:3]
	v_mfma_f32_16x16x32_bf16 v[52:55], v[204:207], v[172:175], v[52:55]
	v_mfma_f32_16x16x32_bf16 v[48:51], v[212:215], v[172:175], v[48:51]
	v_mfma_f32_16x16x32_bf16 v[36:39], v[204:207], v[180:183], v[36:39]
	v_mfma_f32_16x16x32_bf16 v[32:35], v[212:215], v[180:183], v[32:35]
	v_mfma_f32_16x16x32_bf16 v[20:23], v[204:207], v[188:191], v[20:23]
	v_mfma_f32_16x16x32_bf16 v[16:19], v[212:215], v[188:191], v[16:19]
	v_mfma_f32_16x16x32_bf16 v[4:7], v[204:207], v[196:199], v[4:7]
	v_mfma_f32_16x16x32_bf16 v[0:3], v[212:215], v[196:199], v[0:3]
	s_setprio 0
	s_add_i32 s70, s70, 2
	s_add_u32 s24, s24, 0x100
	s_addc_u32 s25, s25, 0
	s_cmp_gt_u32 s70, 41
	s_barrier
.LBB0_1118:
	v_add_u32_e32 v139, s53, v137
	s_add_u32 s26, s0, s24
	ds_read_b128 v[140:143], v139
	ds_read_b128 v[148:151], v139 offset:1024
	ds_read_b128 v[158:161], v139 offset:2048
	ds_read_b128 v[162:165], v139 offset:3072
	s_addc_u32 s27, s1, s25
	s_add_u32 s26, s26, 0x100
	s_addc_u32 s27, s27, 0
	s_add_u32 s71, s11, s24
	s_addc_u32 s72, s69, s25
	s_cmpk_eq_i32 s24, 0x1500
	s_cselect_b32 s37, s23, s27
	s_cselect_b32 s36, s22, s26
	s_cselect_b32 s27, s17, s72
	s_cselect_b32 s26, s16, s71
	s_mov_b32 m0, s55
	v_lshl_add_u64 v[154:155], v[132:133], 0, s[24:25]
	ds_read_b128 v[166:169], v138
	ds_read_b128 v[172:175], v138 offset:1024
	ds_read_b128 v[176:179], v138 offset:2048
	ds_read_b128 v[180:183], v138 offset:3072
	ds_read_b128 v[184:187], v138 offset:4096
	ds_read_b128 v[188:191], v138 offset:5120
	ds_read_b128 v[192:195], v138 offset:6144
	ds_read_b128 v[196:199], v138 offset:7168
	global_load_lds_dwordx4 v[154:155], off
	v_lshl_add_u64 v[154:155], v[134:135], 0, s[24:25]
	s_mov_b32 m0, s56
	s_nop 0
	global_load_lds_dwordx4 v[154:155], off
	s_waitcnt lgkmcnt(8)
	s_barrier
	s_waitcnt lgkmcnt(0)
	s_setprio 1
	v_mfma_f32_16x16x32_bf16 v[120:123], v[140:143], v[166:169], v[120:123]
	v_mfma_f32_16x16x32_bf16 v[124:127], v[158:161], v[166:169], v[124:127]
	v_mfma_f32_16x16x32_bf16 v[108:111], v[140:143], v[176:179], v[108:111]
	v_mfma_f32_16x16x32_bf16 v[104:107], v[158:161], v[176:179], v[104:107]
	v_mfma_f32_16x16x32_bf16 v[92:95], v[140:143], v[184:187], v[92:95]
	v_mfma_f32_16x16x32_bf16 v[88:91], v[158:161], v[184:187], v[88:91]
	v_mfma_f32_16x16x32_bf16 v[76:79], v[140:143], v[192:195], v[76:79]
	v_mfma_f32_16x16x32_bf16 v[72:75], v[158:161], v[192:195], v[72:75]
	v_mfma_f32_16x16x32_bf16 v[120:123], v[148:151], v[172:175], v[120:123]
	v_mfma_f32_16x16x32_bf16 v[124:127], v[162:165], v[172:175], v[124:127]
	v_mfma_f32_16x16x32_bf16 v[108:111], v[148:151], v[180:183], v[108:111]
	v_mfma_f32_16x16x32_bf16 v[104:107], v[162:165], v[180:183], v[104:107]
	v_mfma_f32_16x16x32_bf16 v[92:95], v[148:151], v[188:191], v[92:95]
	v_mfma_f32_16x16x32_bf16 v[88:91], v[162:165], v[188:191], v[88:91]
	v_mfma_f32_16x16x32_bf16 v[76:79], v[148:151], v[196:199], v[76:79]
	v_mfma_f32_16x16x32_bf16 v[72:75], v[162:165], v[196:199], v[72:75]
	s_setprio 0
	s_barrier
	s_mov_b32 m0, s57
	v_add_u32_e32 v139, s54, v137
	v_lshl_add_u64 v[154:155], s[26:27], 0, v[144:145]
	ds_read_b128 v[200:203], v139
	ds_read_b128 v[204:207], v139 offset:1024
	ds_read_b128 v[208:211], v139 offset:2048
	ds_read_b128 v[212:215], v139 offset:3072
	global_load_lds_dwordx4 v[154:155], off
	v_lshl_add_u64 v[216:217], s[26:27], 0, v[146:147]
	s_mov_b32 m0, s58
	s_nop 0
	global_load_lds_dwordx4 v[216:217], off
	s_barrier
; #define PG8_STAGE(bufoff, gbase, voff) do { _Pragma("unroll") for (int _i = 0; _i < 2; ++_i) \
;         __builtin_amdgcn_global_load_lds((const unsigned*)((const char*)(gbase) + (voff)[_i]), (LAS unsigned*)(lds + (bufoff) + ldsw + _i * 8192), 16, 0, 0); } while (0)
; #define PG8_LDA(dst, b, h) do { _Pragma("unroll") for (int m = 0; m < 4; ++m) _Pragma("unroll") for (int k = 0; k < 2; ++k) dst[m][k] = *(const LAS bf16x8*)(lds + PG8_SA(b, h) + aoff + m * 2048 + k * 1024); } while (0)
; #define PG8_LDB(dst, b, h) do { _Pragma("unroll") for (int n = 0; n < 2; ++n) _Pragma("unroll") for (int k = 0; k < 2; ++k) dst[n][k] = *(const LAS bf16x8*)(lds + PG8_SB(b, h) + boff + n * 2048 + k * 1024); } while (0)
; #define PG8_MMA(ai, bj, At, Bt) do { __builtin_amdgcn_s_setprio(1); _Pragma("unroll") for (int m = 0; m < 4; ++m) _Pragma("unroll") for (int n = 0; n < 2; ++n) _Pragma("unroll") for (int k = 0; k < 2; ++k) \
;         acc[ai][bj][m][n] = __builtin_amdgcn_mfma_f32_16x16x32_bf16(Bt[n][k], At[m][k], acc[ai][bj][m][n], 0, 0, 0); __builtin_amdgcn_s_setprio(0); } while (0)
; #define PG8_WAIT_V(n) asm volatile("s_waitcnt vmcnt(" #n ")" ::: "memory")
; #define PG8_WAIT_L(n) asm volatile("s_waitcnt lgkmcnt(" #n ")" ::: "memory")
; #define PG8_BAR __builtin_amdgcn_s_barrier()
; #define PG8_SCHED __builtin_amdgcn_sched_barrier(0)
; template <class Epi, class Sched>
; __device__ __forceinline__ void gemm_phase(LAS unsigned char* lds, const int K, const Sched& S, const Epi& E) {
;     ...
;             PG8_BAR; PG8_WAIT_L(0); PG8_MMA(0, 1, At, B1); PG8_BAR;
;             PG8_LDA(At, 0, 1); PG8_STAGE(PG8_SA(0, 0), a2, voffA);
;             PG8_BAR; PG8_WAIT_L(0); PG8_MMA(1, 0, At, B0); PG8_BAR; PG8_SCHED;
;             PG8_STAGE(PG8_SB(0, 1), b2 + hstep, voffB);
;             PG8_WAIT_V(6); PG8_BAR; PG8_MMA(1, 1, At, B1); PG8_BAR;
;             PG8_LDB(B0, 1, 0); PG8_SCHED; PG8_LDA(At, 1, 0); PG8_STAGE(PG8_SA(0, 1), a2 + hstepA, voffA);
;             PG8_WAIT_L(8); PG8_BAR; PG8_WAIT_L(0); PG8_MMA(0, 0, At, B0); PG8_BAR; PG8_SCHED;
	s_waitcnt lgkmcnt(0)
	s_setprio 1
	v_mfma_f32_16x16x32_bf16 v[116:119], v[200:203], v[166:169], v[116:119]
	v_mfma_f32_16x16x32_bf16 v[112:115], v[208:211], v[166:169], v[112:115]
	v_mfma_f32_16x16x32_bf16 v[100:103], v[200:203], v[176:179], v[100:103]
	v_mfma_f32_16x16x32_bf16 v[96:99], v[208:211], v[176:179], v[96:99]
	v_mfma_f32_16x16x32_bf16 v[84:87], v[200:203], v[184:187], v[84:87]
	v_mfma_f32_16x16x32_bf16 v[80:83], v[208:211], v[184:187], v[80:83]
	v_mfma_f32_16x16x32_bf16 v[68:71], v[200:203], v[192:195], v[68:71]
	v_mfma_f32_16x16x32_bf16 v[64:67], v[208:211], v[192:195], v[64:67]
	v_mfma_f32_16x16x32_bf16 v[116:119], v[204:207], v[172:175], v[116:119]
	v_mfma_f32_16x16x32_bf16 v[112:115], v[212:215], v[172:175], v[112:115]
	v_mfma_f32_16x16x32_bf16 v[100:103], v[204:207], v[180:183], v[100:103]
	v_mfma_f32_16x16x32_bf16 v[96:99], v[212:215], v[180:183], v[96:99]
	v_mfma_f32_16x16x32_bf16 v[84:87], v[204:207], v[188:191], v[84:87]
	v_mfma_f32_16x16x32_bf16 v[80:83], v[212:215], v[188:191], v[80:83]
	v_mfma_f32_16x16x32_bf16 v[68:71], v[204:207], v[196:199], v[68:71]
	v_mfma_f32_16x16x32_bf16 v[64:67], v[212:215], v[196:199], v[64:67]
	s_setprio 0
	s_mov_b32 m0, s46
	v_lshl_add_u64 v[218:219], s[36:37], 0, v[144:145]
	s_barrier
	ds_read_b128 v[166:169], v138 offset:16384
	ds_read_b128 v[172:175], v138 offset:17408
	ds_read_b128 v[176:179], v138 offset:18432
	ds_read_b128 v[180:183], v138 offset:19456
	ds_read_b128 v[184:187], v138 offset:20480
	ds_read_b128 v[188:191], v138 offset:21504
	ds_read_b128 v[192:195], v138 offset:22528
	ds_read_b128 v[196:199], v138 offset:23552
	global_load_lds_dwordx4 v[218:219], off
	v_lshl_add_u64 v[220:221], s[36:37], 0, v[146:147]
	s_mov_b32 m0, s47
	s_nop 0
	global_load_lds_dwordx4 v[220:221], off
	s_barrier
	s_waitcnt lgkmcnt(0)
	s_setprio 1
	v_mfma_f32_16x16x32_bf16 v[60:63], v[140:143], v[166:169], v[60:63]
	v_mfma_f32_16x16x32_bf16 v[56:59], v[158:161], v[166:169], v[56:59]
	v_mfma_f32_16x16x32_bf16 v[44:47], v[140:143], v[176:179], v[44:47]
	v_mfma_f32_16x16x32_bf16 v[40:43], v[158:161], v[176:179], v[40:43]
	v_mfma_f32_16x16x32_bf16 v[28:31], v[140:143], v[184:187], v[28:31]
	v_mfma_f32_16x16x32_bf16 v[24:27], v[158:161], v[184:187], v[24:27]
	v_mfma_f32_16x16x32_bf16 v[12:15], v[140:143], v[192:195], v[12:15]
	v_mfma_f32_16x16x32_bf16 v[8:11], v[158:161], v[192:195], v[8:11]
	v_mfma_f32_16x16x32_bf16 v[60:63], v[148:151], v[172:175], v[60:63]
	v_mfma_f32_16x16x32_bf16 v[56:59], v[162:165], v[172:175], v[56:59]
	v_mfma_f32_16x16x32_bf16 v[44:47], v[148:151], v[180:183], v[44:47]
	v_mfma_f32_16x16x32_bf16 v[40:43], v[162:165], v[180:183], v[40:43]
	v_mfma_f32_16x16x32_bf16 v[28:31], v[148:151], v[188:191], v[28:31]
	v_mfma_f32_16x16x32_bf16 v[24:27], v[162:165], v[188:191], v[24:27]
	v_mfma_f32_16x16x32_bf16 v[12:15], v[148:151], v[196:199], v[12:15]
	v_mfma_f32_16x16x32_bf16 v[8:11], v[162:165], v[196:199], v[8:11]
	s_setprio 0
	s_barrier
	s_add_u32 s72, s26, 0xb0000
	s_addc_u32 s73, s27, 0
	s_mov_b32 m0, s59
	v_lshl_add_u64 v[140:141], s[72:73], 0, v[144:145]
	global_load_lds_dwordx4 v[140:141], off
	v_lshl_add_u64 v[140:141], s[72:73], 0, v[146:147]
	s_mov_b32 m0, s60
	s_nop 0
	global_load_lds_dwordx4 v[140:141], off
	s_waitcnt vmcnt(6)
	s_barrier
	s_setprio 1
	v_mfma_f32_16x16x32_bf16 v[52:55], v[200:203], v[166:169], v[52:55]
	v_mfma_f32_16x16x32_bf16 v[48:51], v[208:211], v[166:169], v[48:51]
	v_mfma_f32_16x16x32_bf16 v[36:39], v[200:203], v[176:179], v[36:39]
	v_mfma_f32_16x16x32_bf16 v[32:35], v[208:211], v[176:179], v[32:35]
	v_mfma_f32_16x16x32_bf16 v[20:23], v[200:203], v[184:187], v[20:23]
	v_mfma_f32_16x16x32_bf16 v[16:19], v[208:211], v[184:187], v[16:19]
	v_mfma_f32_16x16x32_bf16 v[4:7], v[200:203], v[192:195], v[4:7]
	v_mfma_f32_16x16x32_bf16 v[0:3], v[208:211], v[192:195], v[0:3]
	v_mfma_f32_16x16x32_bf16 v[52:55], v[204:207], v[172:175], v[52:55]
	v_mfma_f32_16x16x32_bf16 v[48:51], v[212:215], v[172:175], v[48:51]
	v_mfma_f32_16x16x32_bf16 v[36:39], v[204:207], v[180:183], v[36:39]
	v_mfma_f32_16x16x32_bf16 v[32:35], v[212:215], v[180:183], v[32:35]
	v_mfma_f32_16x16x32_bf16 v[20:23], v[204:207], v[188:191], v[20:23]
	v_mfma_f32_16x16x32_bf16 v[16:19], v[212:215], v[188:191], v[16:19]
	v_mfma_f32_16x16x32_bf16 v[4:7], v[204:207], v[196:199], v[4:7]
	v_mfma_f32_16x16x32_bf16 v[0:3], v[212:215], v[196:199], v[0:3]
	s_setprio 0
	v_add_u32_e32 v139, s61, v137
	s_barrier
	ds_read_b128 v[140:143], v139
	ds_read_b128 v[148:151], v139 offset:1024
	ds_read_b128 v[158:161], v139 offset:2048
	ds_read_b128 v[162:165], v139 offset:3072
	s_add_u32 s36, s36, 0xb0000
	s_addc_u32 s37, s37, 0
	s_mov_b32 m0, s48
	v_lshl_add_u64 v[200:201], s[36:37], 0, v[144:145]
	ds_read_b128 v[166:169], v138 offset:32768
	ds_read_b128 v[172:175], v138 offset:33792
	ds_read_b128 v[176:179], v138 offset:34816
	ds_read_b128 v[180:183], v138 offset:35840
	ds_read_b128 v[184:187], v138 offset:36864
	ds_read_b128 v[188:191], v138 offset:37888
	ds_read_b128 v[192:195], v138 offset:38912
	ds_read_b128 v[196:199], v138 offset:39936
	global_load_lds_dwordx4 v[200:201], off
	v_lshl_add_u64 v[200:201], s[36:37], 0, v[146:147]
	s_mov_b32 m0, s49
	s_nop 0
	global_load_lds_dwordx4 v[200:201], off
	s_waitcnt lgkmcnt(8)
	s_barrier
; #define PG8_STAGE(bufoff, gbase, voff) do { _Pragma("unroll") for (int _i = 0; _i < 2; ++_i) \
;         __builtin_amdgcn_global_load_lds((const unsigned*)((const char*)(gbase) + (voff)[_i]), (LAS unsigned*)(lds + (bufoff) + ldsw + _i * 8192), 16, 0, 0); } while (0)
; #define PG8_LDA(dst, b, h) do { _Pragma("unroll") for (int m = 0; m < 4; ++m) _Pragma("unroll") for (int k = 0; k < 2; ++k) dst[m][k] = *(const LAS bf16x8*)(lds + PG8_SA(b, h) + aoff + m * 2048 + k * 1024); } while (0)
; #define PG8_LDB(dst, b, h) do { _Pragma("unroll") for (int n = 0; n < 2; ++n) _Pragma("unroll") for (int k = 0; k < 2; ++k) dst[n][k] = *(const LAS bf16x8*)(lds + PG8_SB(b, h) + boff + n * 2048 + k * 1024); } while (0)
; #define PG8_MMA(ai, bj, At, Bt) do { __builtin_amdgcn_s_setprio(1); _Pragma("unroll") for (int m = 0; m < 4; ++m) _Pragma("unroll") for (int n = 0; n < 2; ++n) _Pragma("unroll") for (int k = 0; k < 2; ++k) \
;         acc[ai][bj][m][n] = __builtin_amdgcn_mfma_f32_16x16x32_bf16(Bt[n][k], At[m][k], acc[ai][bj][m][n], 0, 0, 0); __builtin_amdgcn_s_setprio(0); } while (0)
; #define PG8_WAIT_L(n) asm volatile("s_waitcnt lgkmcnt(" #n ")" ::: "memory")
; #define PG8_BAR __builtin_amdgcn_s_barrier()
; #define PG8_SCHED __builtin_amdgcn_sched_barrier(0)
; template <class Epi, class Sched>
; __device__ __forceinline__ void gemm_phase(LAS unsigned char* lds, const int K, const Sched& S, const Epi& E) {
;     ...
;             PG8_WAIT_L(8); PG8_BAR; PG8_WAIT_L(0); PG8_MMA(0, 0, At, B0); PG8_BAR; PG8_SCHED;
;             PG8_LDB(B1, 1, 1); PG8_STAGE(PG8_SB(1, 0), b3, voffB);
;             PG8_BAR; PG8_WAIT_L(0); PG8_MMA(0, 1, At, B1); PG8_BAR;
;             PG8_LDA(At, 1, 1); PG8_STAGE(PG8_SA(1, 0), a3, voffA);
;             PG8_BAR; PG8_WAIT_L(0); PG8_MMA(1, 0, At, B0); PG8_BAR; PG8_SCHED;
	s_waitcnt lgkmcnt(0)
	s_setprio 1
	v_mfma_f32_16x16x32_bf16 v[120:123], v[140:143], v[166:169], v[120:123]
	v_mfma_f32_16x16x32_bf16 v[124:127], v[158:161], v[166:169], v[124:127]
	v_mfma_f32_16x16x32_bf16 v[108:111], v[140:143], v[176:179], v[108:111]
	v_mfma_f32_16x16x32_bf16 v[104:107], v[158:161], v[176:179], v[104:107]
	v_mfma_f32_16x16x32_bf16 v[92:95], v[140:143], v[184:187], v[92:95]
	v_mfma_f32_16x16x32_bf16 v[88:91], v[158:161], v[184:187], v[88:91]
	v_mfma_f32_16x16x32_bf16 v[76:79], v[140:143], v[192:195], v[76:79]
	v_mfma_f32_16x16x32_bf16 v[72:75], v[158:161], v[192:195], v[72:75]
	v_mfma_f32_16x16x32_bf16 v[120:123], v[148:151], v[172:175], v[120:123]
	v_mfma_f32_16x16x32_bf16 v[124:127], v[162:165], v[172:175], v[124:127]
	v_mfma_f32_16x16x32_bf16 v[108:111], v[148:151], v[180:183], v[108:111]
	v_mfma_f32_16x16x32_bf16 v[104:107], v[162:165], v[180:183], v[104:107]
	v_mfma_f32_16x16x32_bf16 v[92:95], v[148:151], v[188:191], v[92:95]
	v_mfma_f32_16x16x32_bf16 v[88:91], v[162:165], v[188:191], v[88:91]
	v_mfma_f32_16x16x32_bf16 v[76:79], v[148:151], v[196:199], v[76:79]
	v_mfma_f32_16x16x32_bf16 v[72:75], v[162:165], v[196:199], v[72:75]
	s_setprio 0
	s_barrier
	s_mov_b32 m0, s63
	v_add_u32_e32 v139, s62, v137
	v_lshl_add_u64 v[154:155], v[154:155], 0, s[12:13]
	ds_read_b128 v[200:203], v139
	ds_read_b128 v[204:207], v139 offset:1024
	ds_read_b128 v[208:211], v139 offset:2048
	ds_read_b128 v[212:215], v139 offset:3072
	global_load_lds_dwordx4 v[154:155], off
	v_lshl_add_u64 v[154:155], v[216:217], 0, s[12:13]
	s_mov_b32 m0, s64
	s_nop 0
	global_load_lds_dwordx4 v[154:155], off
	s_barrier
	s_waitcnt lgkmcnt(0)
	s_setprio 1
	v_mfma_f32_16x16x32_bf16 v[116:119], v[200:203], v[166:169], v[116:119]
	v_mfma_f32_16x16x32_bf16 v[112:115], v[208:211], v[166:169], v[112:115]
	v_mfma_f32_16x16x32_bf16 v[100:103], v[200:203], v[176:179], v[100:103]
	v_mfma_f32_16x16x32_bf16 v[96:99], v[208:211], v[176:179], v[96:99]
	v_mfma_f32_16x16x32_bf16 v[84:87], v[200:203], v[184:187], v[84:87]
	v_mfma_f32_16x16x32_bf16 v[80:83], v[208:211], v[184:187], v[80:83]
	v_mfma_f32_16x16x32_bf16 v[68:71], v[200:203], v[192:195], v[68:71]
	v_mfma_f32_16x16x32_bf16 v[64:67], v[208:211], v[192:195], v[64:67]
	v_mfma_f32_16x16x32_bf16 v[116:119], v[204:207], v[172:175], v[116:119]
	v_mfma_f32_16x16x32_bf16 v[112:115], v[212:215], v[172:175], v[112:115]
	v_mfma_f32_16x16x32_bf16 v[100:103], v[204:207], v[180:183], v[100:103]
	v_mfma_f32_16x16x32_bf16 v[96:99], v[212:215], v[180:183], v[96:99]
	v_mfma_f32_16x16x32_bf16 v[84:87], v[204:207], v[188:191], v[84:87]
	v_mfma_f32_16x16x32_bf16 v[80:83], v[212:215], v[188:191], v[80:83]
	v_mfma_f32_16x16x32_bf16 v[68:71], v[204:207], v[196:199], v[68:71]
	v_mfma_f32_16x16x32_bf16 v[64:67], v[212:215], v[196:199], v[64:67]
	s_setprio 0
	s_mov_b32 m0, s33
	v_lshl_add_u64 v[154:155], v[218:219], 0, s[12:13]
	s_barrier
	ds_read_b128 v[166:169], v138 offset:49152
	ds_read_b128 v[172:175], v138 offset:50176
	ds_read_b128 v[176:179], v138 offset:51200
	ds_read_b128 v[180:183], v138 offset:52224
	ds_read_b128 v[184:187], v138 offset:53248
	ds_read_b128 v[188:191], v138 offset:54272
	ds_read_b128 v[192:195], v138 offset:55296
	ds_read_b128 v[196:199], v138 offset:56320
	global_load_lds_dwordx4 v[154:155], off
	v_lshl_add_u64 v[154:155], v[220:221], 0, s[12:13]
	s_mov_b32 m0, s52
	s_nop 0
	global_load_lds_dwordx4 v[154:155], off
	s_barrier
	s_waitcnt lgkmcnt(0)
	s_setprio 1
	v_mfma_f32_16x16x32_bf16 v[60:63], v[140:143], v[166:169], v[60:63]
	v_mfma_f32_16x16x32_bf16 v[56:59], v[158:161], v[166:169], v[56:59]
	v_mfma_f32_16x16x32_bf16 v[44:47], v[140:143], v[176:179], v[44:47]
	v_mfma_f32_16x16x32_bf16 v[40:43], v[158:161], v[176:179], v[40:43]
	v_mfma_f32_16x16x32_bf16 v[28:31], v[140:143], v[184:187], v[28:31]
	v_mfma_f32_16x16x32_bf16 v[24:27], v[158:161], v[184:187], v[24:27]
	v_mfma_f32_16x16x32_bf16 v[12:15], v[140:143], v[192:195], v[12:15]
	v_mfma_f32_16x16x32_bf16 v[8:11], v[158:161], v[192:195], v[8:11]
	v_mfma_f32_16x16x32_bf16 v[60:63], v[148:151], v[172:175], v[60:63]
	v_mfma_f32_16x16x32_bf16 v[56:59], v[162:165], v[172:175], v[56:59]
	v_mfma_f32_16x16x32_bf16 v[44:47], v[148:151], v[180:183], v[44:47]
	v_mfma_f32_16x16x32_bf16 v[40:43], v[162:165], v[180:183], v[40:43]
	v_mfma_f32_16x16x32_bf16 v[28:31], v[148:151], v[188:191], v[28:31]
	v_mfma_f32_16x16x32_bf16 v[24:27], v[162:165], v[188:191], v[24:27]
	v_mfma_f32_16x16x32_bf16 v[12:15], v[148:151], v[196:199], v[12:15]
	v_mfma_f32_16x16x32_bf16 v[8:11], v[162:165], v[196:199], v[8:11]
	s_setprio 0
	s_barrier
; #define PG8_STAGE(bufoff, gbase, voff) do { _Pragma("unroll") for (int _i = 0; _i < 2; ++_i) \
;         __builtin_amdgcn_global_load_lds((const unsigned*)((const char*)(gbase) + (voff)[_i]), (LAS unsigned*)(lds + (bufoff) + ldsw + _i * 8192), 16, 0, 0); } while (0)
; #define PG8_MMA(ai, bj, At, Bt) do { __builtin_amdgcn_s_setprio(1); _Pragma("unroll") for (int m = 0; m < 4; ++m) _Pragma("unroll") for (int n = 0; n < 2; ++n) _Pragma("unroll") for (int k = 0; k < 2; ++k) \
;         acc[ai][bj][m][n] = __builtin_amdgcn_mfma_f32_16x16x32_bf16(Bt[n][k], At[m][k], acc[ai][bj][m][n], 0, 0, 0); __builtin_amdgcn_s_setprio(0); } while (0)
; #define PG8_WAIT_V(n) asm volatile("s_waitcnt vmcnt(" #n ")" ::: "memory")
; #define PG8_BAR __builtin_amdgcn_s_barrier()
; template <class Epi, class Sched>
; __device__ __forceinline__ void gemm_phase(LAS unsigned char* lds, const int K, const Sched& S, const Epi& E) {
;     ...
;             PG8_STAGE(PG8_SB(1, 1), b3 + hstep, voffB);
;             PG8_WAIT_V(6); PG8_BAR; PG8_MMA(1, 1, At, B1); PG8_BAR;
;         }
;         if constexpr (!Epi::AFTER_DRAIN) E(acc, cur, wr, wc, fr, fq);
;         if (!has_next) break;
; #pragma unroll
;         for (int a = 0; a < 2; ++a)
; #pragma unroll
;             for (int b = 0; b < 2; ++b)
; #pragma unroll
;                 for (int m = 0; m < 4; ++m)
; #pragma unroll
;                     for (int n = 0; n < 2; ++n) acc[a][b][m][n] = (f32x4){0.f, 0.f, 0.f, 0.f};
	s_add_u32 s26, s26, 0xb0080
	s_addc_u32 s27, s27, 0
	s_mov_b32 m0, s65
	v_lshl_add_u64 v[140:141], s[26:27], 0, v[144:145]
	global_load_lds_dwordx4 v[140:141], off
	v_lshl_add_u64 v[140:141], s[26:27], 0, v[146:147]
	s_mov_b32 m0, s66
	s_nop 0
	global_load_lds_dwordx4 v[140:141], off
	s_waitcnt vmcnt(6)
	s_barrier
	s_setprio 1
	v_mfma_f32_16x16x32_bf16 v[52:55], v[200:203], v[166:169], v[52:55]
	v_mfma_f32_16x16x32_bf16 v[48:51], v[208:211], v[166:169], v[48:51]
	v_mfma_f32_16x16x32_bf16 v[36:39], v[200:203], v[176:179], v[36:39]
	v_mfma_f32_16x16x32_bf16 v[32:35], v[208:211], v[176:179], v[32:35]
	v_mfma_f32_16x16x32_bf16 v[20:23], v[200:203], v[184:187], v[20:23]
	v_mfma_f32_16x16x32_bf16 v[16:19], v[208:211], v[184:187], v[16:19]
	v_mfma_f32_16x16x32_bf16 v[4:7], v[200:203], v[192:195], v[4:7]
	v_mfma_f32_16x16x32_bf16 v[0:3], v[208:211], v[192:195], v[0:3]
	v_mfma_f32_16x16x32_bf16 v[52:55], v[204:207], v[172:175], v[52:55]
	v_mfma_f32_16x16x32_bf16 v[48:51], v[212:215], v[172:175], v[48:51]
	v_mfma_f32_16x16x32_bf16 v[36:39], v[204:207], v[180:183], v[36:39]
	v_mfma_f32_16x16x32_bf16 v[32:35], v[212:215], v[180:183], v[32:35]
	v_mfma_f32_16x16x32_bf16 v[20:23], v[204:207], v[188:191], v[20:23]
	v_mfma_f32_16x16x32_bf16 v[16:19], v[212:215], v[188:191], v[16:19]
	v_mfma_f32_16x16x32_bf16 v[4:7], v[204:207], v[196:199], v[4:7]
	v_mfma_f32_16x16x32_bf16 v[0:3], v[212:215], v[196:199], v[0:3]
	s_setprio 0
	s_add_i32 s70, s70, 2
	s_add_u32 s24, s24, 0x100
	s_addc_u32 s25, s25, 0
	s_cmp_gt_u32 s70, 41
	s_barrier
	s_cbranch_scc0 .LBB0_1118
	s_add_u32 s24, s11, 0xffffff00
	s_addc_u32 s25, s69, -1
	s_andn2_b64 vcc, exec, s[20:21]
	s_cbranch_vccnz .LBB0_1121
	v_mov_b32_e32 v0, 0
	s_mov_b32 s43, s67
	s_mov_b32 s8, s68
	s_mov_b64 s[0:1], s[22:23]
	s_mov_b32 s51, s10
	v_mov_b32_e32 v1, v0
	v_mov_b32_e32 v2, v0
	v_mov_b32_e32 v3, v0
	v_mov_b32_e32 v4, v0
	v_mov_b32_e32 v5, v0
	v_mov_b32_e32 v6, v0
	v_mov_b32_e32 v7, v0
	v_mov_b32_e32 v16, v0
	v_mov_b32_e32 v17, v0
	v_mov_b32_e32 v18, v0
	v_mov_b32_e32 v19, v0
	v_mov_b32_e32 v20, v0
	v_mov_b32_e32 v21, v0
	v_mov_b32_e32 v22, v0
	v_mov_b32_e32 v23, v0
	v_mov_b32_e32 v32, v0
	v_mov_b32_e32 v33, v0
	v_mov_b32_e32 v34, v0
	v_mov_b32_e32 v35, v0
	v_mov_b32_e32 v36, v0
	v_mov_b32_e32 v37, v0
	v_mov_b32_e32 v38, v0
	v_mov_b32_e32 v39, v0
	v_mov_b32_e32 v48, v0
	v_mov_b32_e32 v49, v0
	v_mov_b32_e32 v50, v0
	v_mov_b32_e32 v51, v0
	v_mov_b32_e32 v52, v0
	v_mov_b32_e32 v53, v0
	v_mov_b32_e32 v54, v0
	v_mov_b32_e32 v55, v0
	v_mov_b32_e32 v8, v0
	v_mov_b32_e32 v9, v0
	v_mov_b32_e32 v10, v0
	v_mov_b32_e32 v11, v0
	v_mov_b32_e32 v12, v0
	v_mov_b32_e32 v13, v0
	v_mov_b32_e32 v14, v0
	v_mov_b32_e32 v15, v0
	v_mov_b32_e32 v24, v0
	v_mov_b32_e32 v25, v0
	v_mov_b32_e32 v26, v0
	v_mov_b32_e32 v27, v0
	v_mov_b32_e32 v28, v0
	v_mov_b32_e32 v29, v0
	v_mov_b32_e32 v30, v0
	v_mov_b32_e32 v31, v0
	v_mov_b32_e32 v40, v0
	v_mov_b32_e32 v41, v0
	v_mov_b32_e32 v42, v0
	v_mov_b32_e32 v43, v0
	v_mov_b32_e32 v44, v0
	v_mov_b32_e32 v45, v0
	v_mov_b32_e32 v46, v0
	v_mov_b32_e32 v47, v0
	v_mov_b32_e32 v56, v0
	v_mov_b32_e32 v57, v0
	v_mov_b32_e32 v58, v0
	v_mov_b32_e32 v59, v0
	v_mov_b32_e32 v60, v0
	v_mov_b32_e32 v61, v0
	v_mov_b32_e32 v62, v0
	v_mov_b32_e32 v63, v0
	v_mov_b32_e32 v64, v0
	v_mov_b32_e32 v65, v0
	v_mov_b32_e32 v66, v0
	v_mov_b32_e32 v67, v0
	v_mov_b32_e32 v68, v0
	v_mov_b32_e32 v69, v0
	v_mov_b32_e32 v70, v0
	v_mov_b32_e32 v71, v0
	v_mov_b32_e32 v80, v0
	v_mov_b32_e32 v81, v0
	v_mov_b32_e32 v82, v0
	v_mov_b32_e32 v83, v0
	v_mov_b32_e32 v84, v0
	v_mov_b32_e32 v85, v0
	v_mov_b32_e32 v86, v0
	v_mov_b32_e32 v87, v0
	v_mov_b32_e32 v96, v0
	v_mov_b32_e32 v97, v0
	v_mov_b32_e32 v98, v0
	v_mov_b32_e32 v99, v0
	v_mov_b32_e32 v100, v0
	v_mov_b32_e32 v101, v0
	v_mov_b32_e32 v102, v0
	v_mov_b32_e32 v103, v0
	v_mov_b32_e32 v112, v0
	v_mov_b32_e32 v113, v0
	v_mov_b32_e32 v114, v0
	v_mov_b32_e32 v115, v0
	v_mov_b32_e32 v116, v0
	v_mov_b32_e32 v117, v0
	v_mov_b32_e32 v118, v0
	v_mov_b32_e32 v119, v0
	v_mov_b32_e32 v72, v0
	v_mov_b32_e32 v73, v0
	v_mov_b32_e32 v74, v0
	v_mov_b32_e32 v75, v0
	v_mov_b32_e32 v76, v0
	v_mov_b32_e32 v77, v0
	v_mov_b32_e32 v78, v0
	v_mov_b32_e32 v79, v0
	v_mov_b32_e32 v88, v0
	v_mov_b32_e32 v89, v0
	v_mov_b32_e32 v90, v0
	v_mov_b32_e32 v91, v0
	v_mov_b32_e32 v92, v0
	v_mov_b32_e32 v93, v0
	v_mov_b32_e32 v94, v0
	v_mov_b32_e32 v95, v0
	v_mov_b32_e32 v104, v0
	v_mov_b32_e32 v105, v0
	v_mov_b32_e32 v106, v0
	v_mov_b32_e32 v107, v0
	v_mov_b32_e32 v108, v0
	v_mov_b32_e32 v109, v0
	v_mov_b32_e32 v110, v0
	v_mov_b32_e32 v111, v0
	v_mov_b32_e32 v124, v0
	v_mov_b32_e32 v125, v0
	v_mov_b32_e32 v126, v0
	v_mov_b32_e32 v127, v0
	v_mov_b32_e32 v120, v0
	v_mov_b32_e32 v121, v0
	v_mov_b32_e32 v122, v0
	v_mov_b32_e32 v123, v0
	s_andn2_b64 vcc, exec, s[18:19]
	s_cbranch_vccnz .LBB0_1122
	s_branch .LBB0_1123
